# GEMM k-loops unrolled over the two LDS stages: fragment read addresses are loop invariants (stage 1 via read offset +0x8000), four v_add3 per k-step removed
# baseline (speedup 1.0000x reference)
.LBB0_230:
	s_ashr_i32 s24, s26, 3
	s_add_i32 s27, s27, s24
	s_mul_hi_i32 s24, s27, 0x4bda12f7
	s_lshr_b32 s25, s24, 31
	s_ashr_i32 s24, s24, 6
	s_add_i32 s24, s24, s25
	s_lshl_b32 s49, s24, 3
	s_mul_i32 s47, s24, 0xd8
	s_sub_i32 s24, 0x84, s49
	s_min_u32 s48, s24, 8
	s_sub_i32 s46, s27, s47
	v_cvt_f32_ubyte0_e32 v1, s48
	v_cvt_f32_i32_e32 v0, s46
	v_rcp_iflag_f32_e32 v2, v1
	s_ashr_i32 s24, s46, 30
	s_or_b32 s26, s24, 1
	v_mul_f32_e32 v2, v0, v2
	v_trunc_f32_e32 v2, v2
	v_fma_f32 v0, -v2, v1, v0
	v_cvt_i32_f32_e32 v2, v2
	v_cmp_ge_f32_e64 s[24:25], |v0|, v1
	s_and_b64 s[24:25], s[24:25], exec
	s_cselect_b32 s24, s26, 0
	v_readfirstlane_b32 s45, v2
	s_add_i32 s45, s45, s24
	s_mul_i32 s50, s45, s48
	s_sub_i32 s24, s46, s50
	s_sext_i32_i16 s24, s24
	s_sext_i32_i16 s26, s45
	s_add_i32 s46, s49, s24
	v_mad_i64_i32 v[0:1], s[24:25], s46, v91, v[66:67]
	v_mad_i64_i32 v[2:3], s[24:25], s26, v91, v[68:69]
	v_readfirstlane_b32 s24, v92
	s_mov_b32 m0, s24
	v_readfirstlane_b32 s24, v93
	s_barrier
	global_load_lds_dwordx4 v[0:1], off
	s_mov_b32 m0, s24
	v_readfirstlane_b32 s24, v94
	global_load_lds_dwordx4 v[2:3], off
	v_lshl_add_u64 v[4:5], v[0:1], 0, s[4:5]
	s_mov_b32 m0, s24
	v_readfirstlane_b32 s24, v95
	global_load_lds_dwordx4 v[4:5], off
	v_lshl_add_u64 v[4:5], v[2:3], 0, s[4:5]
	s_mov_b32 m0, s24
	v_readfirstlane_b32 s24, v96
	global_load_lds_dwordx4 v[4:5], off
	v_lshl_add_u64 v[4:5], v[0:1], 0, s[6:7]
	s_mov_b32 m0, s24
	v_readfirstlane_b32 s24, v97
	global_load_lds_dwordx4 v[4:5], off
	v_lshl_add_u64 v[4:5], v[2:3], 0, s[6:7]
	s_mov_b32 m0, s24
	v_readfirstlane_b32 s24, v98
	global_load_lds_dwordx4 v[4:5], off
	v_lshl_add_u64 v[0:1], v[0:1], 0, s[8:9]
	s_mov_b32 m0, s24
	v_readfirstlane_b32 s24, v99
	global_load_lds_dwordx4 v[0:1], off
	v_lshl_add_u64 v[0:1], v[2:3], 0, s[8:9]
	s_mov_b32 m0, s24
	s_sub_i32 s24, s27, s50
	global_load_lds_dwordx4 v[0:1], off
	s_sub_i32 s24, s24, s47
	s_sext_i32_i16 s24, s24
	s_add_i32 s49, s49, s24
	v_mov_b32_e32 v28, 0
	s_mov_b32 s48, 0
	s_mov_b64 s[24:25], 0
	v_mov_b32_e32 v29, v28
	v_mov_b32_e32 v30, v28
	v_mov_b32_e32 v31, v28
	v_mov_b32_e32 v0, v28
	v_mov_b32_e32 v1, v28
	v_mov_b32_e32 v2, v28
	v_mov_b32_e32 v3, v28
	v_mov_b32_e32 v4, v28
	v_mov_b32_e32 v5, v28
	v_mov_b32_e32 v6, v28
	v_mov_b32_e32 v7, v28
	v_mov_b32_e32 v8, v28
	v_mov_b32_e32 v9, v28
	v_mov_b32_e32 v10, v28
	v_mov_b32_e32 v11, v28
	v_mov_b32_e32 v12, v28
	v_mov_b32_e32 v13, v28
	v_mov_b32_e32 v14, v28
	v_mov_b32_e32 v15, v28
	v_mov_b32_e32 v16, v28
	v_mov_b32_e32 v17, v28
	v_mov_b32_e32 v18, v28
	v_mov_b32_e32 v19, v28
	v_mov_b32_e32 v20, v28
	v_mov_b32_e32 v21, v28
	v_mov_b32_e32 v22, v28
	v_mov_b32_e32 v23, v28
	v_mov_b32_e32 v24, v28
	v_mov_b32_e32 v25, v28
	v_mov_b32_e32 v26, v28
	v_mov_b32_e32 v27, v28
	v_mov_b32_e32 v32, v28
	v_mov_b32_e32 v33, v28
	v_mov_b32_e32 v34, v28
	v_mov_b32_e32 v35, v28
	v_mov_b32_e32 v36, v28
	v_mov_b32_e32 v37, v28
	v_mov_b32_e32 v38, v28
	v_mov_b32_e32 v39, v28
	v_mov_b32_e32 v40, v28
	v_mov_b32_e32 v41, v28
	v_mov_b32_e32 v42, v28
	v_mov_b32_e32 v43, v28
	v_mov_b32_e32 v44, v28
	v_mov_b32_e32 v45, v28
	v_mov_b32_e32 v46, v28
	v_mov_b32_e32 v47, v28
	v_mov_b32_e32 v48, v28
	v_mov_b32_e32 v49, v28
	v_mov_b32_e32 v50, v28
	v_mov_b32_e32 v51, v28
	v_mov_b32_e32 v52, v28
	v_mov_b32_e32 v53, v28
	v_mov_b32_e32 v54, v28
	v_mov_b32_e32 v55, v28
	v_mov_b32_e32 v56, v28
	v_mov_b32_e32 v57, v28
	v_mov_b32_e32 v58, v28
	v_mov_b32_e32 v59, v28
	v_mov_b32_e32 v60, v28
	v_mov_b32_e32 v61, v28
	v_mov_b32_e32 v62, v28
	v_mov_b32_e32 v63, v28
	v_mad_i64_i32 v[80:81], s[50:51], s49, v91, v[76:77]
	v_mad_i64_i32 v[82:83], s[50:51], s26, v91, v[78:79]
	v_readfirstlane_b32 s96, v80
	v_readfirstlane_b32 s97, v81
	v_readfirstlane_b32 s72, v82
	v_readfirstlane_b32 s73, v83
	v_readfirstlane_b32 s71, v84
	s_nop 1
	v_subrev_u32_e32 v244, s96, v80
	v_subrev_u32_e32 v245, s72, v82
	v_add_u32_e32 v246, 0x11000, v244
	v_add_u32_e32 v247, 0x11000, v245
	v_add_u32_e32 v248, 0x22000, v244
	v_add_u32_e32 v249, 0x22000, v245
	v_add_u32_e32 v250, 0x33000, v244
	v_add_u32_e32 v251, 0x33000, v245
	s_add_u32 s96, s96, 0x2200080
	s_addc_u32 s97, s97, 0
	s_add_u32 s72, s72, 0x700080
	s_addc_u32 s73, s73, 0
	v_add_u32_e32 v145, v86, v87
	v_add_u32_e32 v208, v87, v88
	v_add_u32_e32 v209, v86, v89
	v_add_u32_e32 v210, v88, v89
.LBB0_231:
	s_add_i32 s47, s48, 0x8000
	s_and_b32 s27, s48, 0x8000
	s_and_b32 s50, s47, 0x8000
	s_add_i32 s48, s27, 0
	s_add_i32 s27, s50, 0
	s_add_u32 s70, s27, s71
	s_mov_b32 m0, s70
	s_waitcnt vmcnt(0) lgkmcnt(0)
	s_barrier
	global_load_lds_dwordx4 v244, s[96:97]
	s_add_u32 m0, s70, 0x4000
	s_nop 0
	global_load_lds_dwordx4 v245, s[72:73]
	s_add_u32 m0, s70, 0x1000
	s_nop 0
	global_load_lds_dwordx4 v246, s[96:97]
	s_add_u32 m0, s70, 0x5000
	s_nop 0
	global_load_lds_dwordx4 v247, s[72:73]
	s_add_u32 m0, s70, 0x2000
	s_nop 0
	global_load_lds_dwordx4 v248, s[96:97]
	s_add_u32 m0, s70, 0x6000
	s_nop 0
	global_load_lds_dwordx4 v249, s[72:73]
	s_add_u32 m0, s70, 0x3000
	s_nop 0
	global_load_lds_dwordx4 v250, s[96:97]
	s_add_u32 m0, s70, 0x7000
	s_nop 0
	global_load_lds_dwordx4 v251, s[72:73]
	s_add_u32 s96, s96, 0x80
	s_addc_u32 s97, s97, 0
	s_add_u32 s72, s72, 0x80
	s_addc_u32 s73, s73, 0
	ds_read_b128 v[104:107], v208
	ds_read_b128 v[100:103], v145 offset:16384
	ds_read_b128 v[108:111], v145 offset:18432
	ds_read_b128 v[164:167], v208 offset:2048
	ds_read_b128 v[112:115], v145 offset:20480
	ds_read_b128 v[116:119], v145 offset:22528
	ds_read_b128 v[120:123], v145 offset:24576
	ds_read_b128 v[124:127], v145 offset:26624
	ds_read_b128 v[128:131], v145 offset:28672
	ds_read_b128 v[132:135], v145 offset:30720
	ds_read_b128 v[200:203], v210
	ds_read_b128 v[168:171], v209 offset:16384
	ds_read_b128 v[172:175], v209 offset:18432
	ds_read_b128 v[204:207], v210 offset:2048
	ds_read_b128 v[176:179], v209 offset:20480
	ds_read_b128 v[180:183], v209 offset:22528
	ds_read_b128 v[184:187], v209 offset:24576
	ds_read_b128 v[188:191], v209 offset:26624
	ds_read_b128 v[192:195], v209 offset:28672
	ds_read_b128 v[196:199], v209 offset:30720
	s_add_u32 s24, s24, 0x80
	s_addc_u32 s25, s25, 0
	s_cmpk_eq_i32 s24, 0x780
	s_mov_b32 s48, s47
	s_waitcnt lgkmcnt(15)
	v_mfma_f32_16x16x32_bf16 v[60:63], v[100:103], v[104:107], v[60:63]
	v_mfma_f32_16x16x32_bf16 v[56:59], v[108:111], v[104:107], v[56:59]
	v_mfma_f32_16x16x32_bf16 v[24:27], v[100:103], v[164:167], v[24:27]
	v_mfma_f32_16x16x32_bf16 v[20:23], v[108:111], v[164:167], v[20:23]
	v_mfma_f32_16x16x32_bf16 v[52:55], v[112:115], v[104:107], v[52:55]
	v_mfma_f32_16x16x32_bf16 v[16:19], v[112:115], v[164:167], v[16:19]
	s_waitcnt lgkmcnt(14)
	v_mfma_f32_16x16x32_bf16 v[48:51], v[116:119], v[104:107], v[48:51]
	v_mfma_f32_16x16x32_bf16 v[12:15], v[116:119], v[164:167], v[12:15]
	s_waitcnt lgkmcnt(13)
	v_mfma_f32_16x16x32_bf16 v[44:47], v[120:123], v[104:107], v[44:47]
	v_mfma_f32_16x16x32_bf16 v[8:11], v[120:123], v[164:167], v[8:11]
	s_waitcnt lgkmcnt(12)
	v_mfma_f32_16x16x32_bf16 v[40:43], v[124:127], v[104:107], v[40:43]
	v_mfma_f32_16x16x32_bf16 v[4:7], v[124:127], v[164:167], v[4:7]
	s_waitcnt lgkmcnt(11)
	v_mfma_f32_16x16x32_bf16 v[36:39], v[128:131], v[104:107], v[36:39]
	v_mfma_f32_16x16x32_bf16 v[0:3], v[128:131], v[164:167], v[0:3]
	s_waitcnt lgkmcnt(10)
	v_mfma_f32_16x16x32_bf16 v[32:35], v[132:135], v[104:107], v[32:35]
	v_mfma_f32_16x16x32_bf16 v[28:31], v[132:135], v[164:167], v[28:31]
	s_waitcnt lgkmcnt(8)
	v_mfma_f32_16x16x32_bf16 v[60:63], v[168:171], v[200:203], v[60:63]
	s_waitcnt lgkmcnt(7)
	v_mfma_f32_16x16x32_bf16 v[56:59], v[172:175], v[200:203], v[56:59]
	s_waitcnt lgkmcnt(6)
	v_mfma_f32_16x16x32_bf16 v[24:27], v[168:171], v[204:207], v[24:27]
	v_mfma_f32_16x16x32_bf16 v[20:23], v[172:175], v[204:207], v[20:23]
	s_waitcnt lgkmcnt(5)
	v_mfma_f32_16x16x32_bf16 v[52:55], v[176:179], v[200:203], v[52:55]
	v_mfma_f32_16x16x32_bf16 v[16:19], v[176:179], v[204:207], v[16:19]
	s_waitcnt lgkmcnt(4)
	v_mfma_f32_16x16x32_bf16 v[48:51], v[180:183], v[200:203], v[48:51]
	v_mfma_f32_16x16x32_bf16 v[12:15], v[180:183], v[204:207], v[12:15]
	s_waitcnt lgkmcnt(3)
	v_mfma_f32_16x16x32_bf16 v[44:47], v[184:187], v[200:203], v[44:47]
	v_mfma_f32_16x16x32_bf16 v[8:11], v[184:187], v[204:207], v[8:11]
	s_waitcnt lgkmcnt(2)
	v_mfma_f32_16x16x32_bf16 v[40:43], v[188:191], v[200:203], v[40:43]
	v_mfma_f32_16x16x32_bf16 v[4:7], v[188:191], v[204:207], v[4:7]
	s_waitcnt lgkmcnt(1)
	v_mfma_f32_16x16x32_bf16 v[36:39], v[192:195], v[200:203], v[36:39]
	v_mfma_f32_16x16x32_bf16 v[0:3], v[192:195], v[204:207], v[0:3]
	s_waitcnt lgkmcnt(0)
	v_mfma_f32_16x16x32_bf16 v[32:35], v[196:199], v[200:203], v[32:35]
	v_mfma_f32_16x16x32_bf16 v[28:31], v[196:199], v[204:207], v[28:31]
	s_cbranch_scc1 .Lu2x_231
	s_add_i32 s47, s48, 0x8000
	s_and_b32 s27, s48, 0x8000
	s_and_b32 s50, s47, 0x8000
	s_add_i32 s48, s27, 0
	s_add_i32 s27, s50, 0
	s_add_u32 s70, s27, s71
	s_mov_b32 m0, s70
	s_waitcnt vmcnt(0) lgkmcnt(0)
	s_barrier
	global_load_lds_dwordx4 v244, s[96:97]
	s_add_u32 m0, s70, 0x4000
	s_nop 0
	global_load_lds_dwordx4 v245, s[72:73]
	s_add_u32 m0, s70, 0x1000
	s_nop 0
	global_load_lds_dwordx4 v246, s[96:97]
	s_add_u32 m0, s70, 0x5000
	s_nop 0
	global_load_lds_dwordx4 v247, s[72:73]
	s_add_u32 m0, s70, 0x2000
	s_nop 0
	global_load_lds_dwordx4 v248, s[96:97]
	s_add_u32 m0, s70, 0x6000
	s_nop 0
	global_load_lds_dwordx4 v249, s[72:73]
	s_add_u32 m0, s70, 0x3000
	s_nop 0
	global_load_lds_dwordx4 v250, s[96:97]
	s_add_u32 m0, s70, 0x7000
	s_nop 0
	global_load_lds_dwordx4 v251, s[72:73]
	s_add_u32 s96, s96, 0x80
	s_addc_u32 s97, s97, 0
	s_add_u32 s72, s72, 0x80
	s_addc_u32 s73, s73, 0
	ds_read_b128 v[104:107], v208 offset:32768
	ds_read_b128 v[100:103], v145 offset:49152
	ds_read_b128 v[108:111], v145 offset:51200
	ds_read_b128 v[164:167], v208 offset:34816
	ds_read_b128 v[112:115], v145 offset:53248
	ds_read_b128 v[116:119], v145 offset:55296
	ds_read_b128 v[120:123], v145 offset:57344
	ds_read_b128 v[124:127], v145 offset:59392
	ds_read_b128 v[128:131], v145 offset:61440
	ds_read_b128 v[132:135], v145 offset:63488
	ds_read_b128 v[200:203], v210 offset:32768
	ds_read_b128 v[168:171], v209 offset:49152
	ds_read_b128 v[172:175], v209 offset:51200
	ds_read_b128 v[204:207], v210 offset:34816
	ds_read_b128 v[176:179], v209 offset:53248
	ds_read_b128 v[180:183], v209 offset:55296
	ds_read_b128 v[184:187], v209 offset:57344
	ds_read_b128 v[188:191], v209 offset:59392
	ds_read_b128 v[192:195], v209 offset:61440
	ds_read_b128 v[196:199], v209 offset:63488
	s_add_u32 s24, s24, 0x80
	s_addc_u32 s25, s25, 0
	s_cmpk_eq_i32 s24, 0x780
	s_mov_b32 s48, s47
	s_waitcnt lgkmcnt(15)
	v_mfma_f32_16x16x32_bf16 v[60:63], v[100:103], v[104:107], v[60:63]
	v_mfma_f32_16x16x32_bf16 v[56:59], v[108:111], v[104:107], v[56:59]
	v_mfma_f32_16x16x32_bf16 v[24:27], v[100:103], v[164:167], v[24:27]
	v_mfma_f32_16x16x32_bf16 v[20:23], v[108:111], v[164:167], v[20:23]
	v_mfma_f32_16x16x32_bf16 v[52:55], v[112:115], v[104:107], v[52:55]
	v_mfma_f32_16x16x32_bf16 v[16:19], v[112:115], v[164:167], v[16:19]
	s_waitcnt lgkmcnt(14)
	v_mfma_f32_16x16x32_bf16 v[48:51], v[116:119], v[104:107], v[48:51]
	v_mfma_f32_16x16x32_bf16 v[12:15], v[116:119], v[164:167], v[12:15]
	s_waitcnt lgkmcnt(13)
	v_mfma_f32_16x16x32_bf16 v[44:47], v[120:123], v[104:107], v[44:47]
	v_mfma_f32_16x16x32_bf16 v[8:11], v[120:123], v[164:167], v[8:11]
	s_waitcnt lgkmcnt(12)
	v_mfma_f32_16x16x32_bf16 v[40:43], v[124:127], v[104:107], v[40:43]
	v_mfma_f32_16x16x32_bf16 v[4:7], v[124:127], v[164:167], v[4:7]
	s_waitcnt lgkmcnt(11)
	v_mfma_f32_16x16x32_bf16 v[36:39], v[128:131], v[104:107], v[36:39]
	v_mfma_f32_16x16x32_bf16 v[0:3], v[128:131], v[164:167], v[0:3]
	s_waitcnt lgkmcnt(10)
	v_mfma_f32_16x16x32_bf16 v[32:35], v[132:135], v[104:107], v[32:35]
	v_mfma_f32_16x16x32_bf16 v[28:31], v[132:135], v[164:167], v[28:31]
	s_waitcnt lgkmcnt(8)
	v_mfma_f32_16x16x32_bf16 v[60:63], v[168:171], v[200:203], v[60:63]
	s_waitcnt lgkmcnt(7)
	v_mfma_f32_16x16x32_bf16 v[56:59], v[172:175], v[200:203], v[56:59]
	s_waitcnt lgkmcnt(6)
	v_mfma_f32_16x16x32_bf16 v[24:27], v[168:171], v[204:207], v[24:27]
	v_mfma_f32_16x16x32_bf16 v[20:23], v[172:175], v[204:207], v[20:23]
	s_waitcnt lgkmcnt(5)
	v_mfma_f32_16x16x32_bf16 v[52:55], v[176:179], v[200:203], v[52:55]
	v_mfma_f32_16x16x32_bf16 v[16:19], v[176:179], v[204:207], v[16:19]
	s_waitcnt lgkmcnt(4)
	v_mfma_f32_16x16x32_bf16 v[48:51], v[180:183], v[200:203], v[48:51]
	v_mfma_f32_16x16x32_bf16 v[12:15], v[180:183], v[204:207], v[12:15]
	s_waitcnt lgkmcnt(3)
	v_mfma_f32_16x16x32_bf16 v[44:47], v[184:187], v[200:203], v[44:47]
	v_mfma_f32_16x16x32_bf16 v[8:11], v[184:187], v[204:207], v[8:11]
	s_waitcnt lgkmcnt(2)
	v_mfma_f32_16x16x32_bf16 v[40:43], v[188:191], v[200:203], v[40:43]
	v_mfma_f32_16x16x32_bf16 v[4:7], v[188:191], v[204:207], v[4:7]
	s_waitcnt lgkmcnt(1)
	v_mfma_f32_16x16x32_bf16 v[36:39], v[192:195], v[200:203], v[36:39]
	v_mfma_f32_16x16x32_bf16 v[0:3], v[192:195], v[204:207], v[0:3]
	s_waitcnt lgkmcnt(0)
	v_mfma_f32_16x16x32_bf16 v[32:35], v[196:199], v[200:203], v[32:35]
	v_mfma_f32_16x16x32_bf16 v[28:31], v[196:199], v[204:207], v[28:31]
	s_cbranch_scc0 .LBB0_231
.Lu2x_231:
	v_add_u32_e32 v64, s27, v86
	v_add_u32_e32 v136, v64, v87
	v_add3_u32 v108, s27, v87, v88
	s_waitcnt vmcnt(0)
	s_barrier
	ds_read_b128 v[80:83], v136 offset:16384
	ds_read_b128 v[100:103], v136 offset:18432
	ds_read_b128 v[104:107], v108
	ds_read_b128 v[108:111], v108 offset:2048
	ds_read_b128 v[112:115], v136 offset:20480
	ds_read_b128 v[116:119], v136 offset:22528
	ds_read_b128 v[128:131], v136 offset:28672
	s_waitcnt lgkmcnt(2)
	v_mfma_f32_16x16x32_bf16 v[120:123], v[112:115], v[104:107], v[52:55]
	s_nop 2
	ds_read_b128 v[52:55], v136 offset:24576
	ds_read_b128 v[124:127], v136 offset:26624
	s_cmp_gt_i32 s26, 11
	s_waitcnt lgkmcnt(0)
	v_mfma_f32_16x16x32_bf16 v[132:135], v[124:127], v[104:107], v[40:43]
	s_nop 2
	ds_read_b128 v[40:43], v136 offset:30720
	s_cselect_b64 s[24:25], -1, 0
	s_cmp_lt_i32 s26, 12
	v_mfma_f32_16x16x32_bf16 v[60:63], v[80:83], v[104:107], v[60:63]
	s_cselect_b64 s[48:49], -1, 0
	v_mfma_f32_16x16x32_bf16 v[56:59], v[100:103], v[104:107], v[56:59]
	v_mfma_f32_16x16x32_bf16 v[48:51], v[116:119], v[104:107], v[48:51]
	v_mfma_f32_16x16x32_bf16 v[44:47], v[52:55], v[104:107], v[44:47]
	v_mfma_f32_16x16x32_bf16 v[136:139], v[128:131], v[104:107], v[36:39]
	s_waitcnt lgkmcnt(0)
	v_mfma_f32_16x16x32_bf16 v[32:35], v[40:43], v[104:107], v[32:35]
	v_mfma_f32_16x16x32_bf16 v[104:107], v[52:55], v[108:111], v[8:11]
	s_nop 2
	v_add_u32_e32 v8, v64, v89
	v_mfma_f32_16x16x32_bf16 v[24:27], v[80:83], v[108:111], v[24:27]
	v_add3_u32 v9, s27, v89, v88
	v_lshl_or_b32 v64, s26, 7, v90
	s_sub_i32 s26, s26, 18
	v_mfma_f32_16x16x32_bf16 v[80:83], v[112:115], v[108:111], v[16:19]
	s_cmp_lt_u32 s26, 8
	s_cselect_b64 s[26:27], -1, 0
	s_or_b64 s[48:49], s[48:49], s[26:27]
	v_mfma_f32_16x16x32_bf16 v[112:115], v[124:127], v[108:111], v[4:7]
	s_mov_b64 s[26:27], -1
	s_andn2_b64 vcc, exec, s[48:49]
	s_nop 0
	ds_read_b128 v[4:7], v8 offset:16384
	v_mfma_f32_16x16x32_bf16 v[20:23], v[100:103], v[108:111], v[20:23]
	v_mfma_f32_16x16x32_bf16 v[100:103], v[116:119], v[108:111], v[12:15]
	v_mfma_f32_16x16x32_bf16 v[116:119], v[128:131], v[108:111], v[0:3]
	ds_read_b128 v[124:127], v8 offset:18432
	s_nop 1
	ds_read_b128 v[0:3], v9
	ds_read_b128 v[128:131], v9 offset:2048
	ds_read_b128 v[140:143], v8 offset:22528
	ds_read_b128 v[146:149], v8 offset:28672
	s_waitcnt lgkmcnt(3)
	v_mfma_f32_16x16x32_bf16 v[52:55], v[4:7], v[0:3], v[60:63]
	s_nop 2
	ds_read_b128 v[60:63], v8 offset:20480
	v_mfma_f32_16x16x32_bf16 v[108:111], v[40:43], v[108:111], v[28:31]
	s_waitcnt lgkmcnt(0)
	v_mfma_f32_16x16x32_bf16 v[36:39], v[60:63], v[0:3], v[120:123]
	s_nop 2
	ds_read_b128 v[120:123], v8 offset:24576
	v_mfma_f32_16x16x32_bf16 v[40:43], v[140:143], v[0:3], v[48:51]
	s_nop 2
	ds_read_b128 v[48:51], v8 offset:26624
	s_waitcnt lgkmcnt(0)
	v_mfma_f32_16x16x32_bf16 v[16:19], v[48:51], v[0:3], v[132:135]
	s_nop 2
	ds_read_b128 v[132:135], v8 offset:30720
	v_mfma_f32_16x16x32_bf16 v[56:59], v[124:127], v[0:3], v[56:59]
	v_mfma_f32_16x16x32_bf16 v[12:15], v[120:123], v[0:3], v[44:47]
	v_mfma_f32_16x16x32_bf16 v[8:11], v[146:149], v[0:3], v[136:139]
	s_waitcnt lgkmcnt(0)
	v_mfma_f32_16x16x32_bf16 v[0:3], v[132:135], v[0:3], v[32:35]
	v_mfma_f32_16x16x32_bf16 v[28:31], v[4:7], v[128:131], v[24:27]
	v_mfma_f32_16x16x32_bf16 v[20:23], v[124:127], v[128:131], v[20:23]
	v_mfma_f32_16x16x32_bf16 v[4:7], v[60:63], v[128:131], v[80:83]
	v_mfma_f32_16x16x32_bf16 v[24:27], v[140:143], v[128:131], v[100:103]
	s_nop 1
	v_lshl_add_u32 v80, s46, 7, v85
	v_mfma_f32_16x16x32_bf16 v[32:35], v[120:123], v[128:131], v[104:107]
	v_mfma_f32_16x16x32_bf16 v[44:47], v[48:51], v[128:131], v[112:115]
	v_mfma_f32_16x16x32_bf16 v[48:51], v[146:149], v[128:131], v[116:119]
	v_mfma_f32_16x16x32_bf16 v[60:63], v[132:135], v[128:131], v[108:111]
	s_cbranch_vccz .LBB0_240
	s_and_b32 s47, 0xffff, s45
	s_cmp_gt_u32 s47, 17
	s_cbranch_scc0 .LBB0_237
	s_cmp_eq_u32 s47, 26
	s_cselect_b64 s[26:27], -1, 0
	s_and_b64 s[48:49], s[10:11], s[26:27]
	s_and_saveexec_b64 s[26:27], s[48:49]
	s_cbranch_execz .LBB0_236
	global_load_dwordx4 v[100:103], v[72:73], off
	v_mad_i64_i32 v[82:83], s[48:49], v80, s28, v[70:71]
	v_or_b32_e32 v81, 16, v80
	s_waitcnt vmcnt(0)
	v_pk_add_f32 v[102:103], v[54:55], v[102:103]
	v_pk_add_f32 v[100:101], v[52:53], v[100:101]
	global_store_dwordx4 v[82:83], v[100:103], off
	global_load_dwordx4 v[100:103], v[72:73], off offset:16
	v_mad_i64_i32 v[82:83], s[48:49], v80, s28, v[74:75]
	s_waitcnt vmcnt(0)
	v_pk_add_f32 v[102:103], v[58:59], v[102:103]
	v_pk_add_f32 v[100:101], v[56:57], v[100:101]
	global_store_dwordx4 v[82:83], v[100:103], off
	global_load_dwordx4 v[100:103], v[72:73], off
	v_mad_i64_i32 v[82:83], s[48:49], v81, s28, v[70:71]
	s_waitcnt vmcnt(0)
	v_pk_add_f32 v[102:103], v[30:31], v[102:103]
	v_pk_add_f32 v[100:101], v[28:29], v[100:101]
	global_store_dwordx4 v[82:83], v[100:103], off
	global_load_dwordx4 v[100:103], v[72:73], off offset:16
	v_mad_i64_i32 v[82:83], s[48:49], v81, s28, v[74:75]
	s_waitcnt vmcnt(0)
	v_pk_add_f32 v[102:103], v[22:23], v[102:103]
	v_pk_add_f32 v[100:101], v[20:21], v[100:101]
	global_store_dwordx4 v[82:83], v[100:103], off

.LBB0_854:
	s_ashr_i32 s34, s41, 3
	s_add_i32 s34, s43, s34
	s_ashr_i32 s35, s34, 31
	s_lshr_b32 s35, s35, 26
	s_add_i32 s35, s34, s35
	s_ashr_i32 s42, s35, 6
	s_and_b32 s35, s35, 0xffc0
	s_sub_i32 s34, s34, s35
	s_bfe_i32 s35, s34, 0x80000
	s_bfe_u32 s35, s35, 0x3000c
	s_add_i32 s35, s34, s35
	s_bfe_i32 s41, s35, 0x80000
	s_and_b32 s35, s35, 0xf8
	s_sub_i32 s34, s34, s35
	s_lshl_b32 s42, s42, 3
	s_sext_i32_i8 s34, s34
	s_add_i32 s34, s42, s34
	s_ashr_i32 s35, s34, 31
	s_lshr_b32 s35, s35, 26
	s_add_i32 s35, s34, s35
	s_sext_i32_i16 s41, s41
	s_ashr_i32 s42, s35, 6
	s_andn2_b32 s35, s35, 63
	s_ashr_i32 s41, s41, 3
	s_mulk_i32 s42, 0x42
	s_sub_i32 s34, s34, s35
	s_add_i32 s42, s34, s42
	s_mul_i32 s34, s41, 0x22000
	s_add_i32 s42, s42, 2
	s_ashr_i32 s35, s34, 31
	v_readfirstlane_b32 s43, v94
	v_mad_i64_i32 v[0:1], s[44:45], s42, v93, v[64:65]
	s_lshl_b64 s[34:35], s[34:35], 1
	s_mov_b32 m0, s43
	v_readfirstlane_b32 s43, v95
	v_lshl_add_u64 v[2:3], v[66:67], 0, s[34:35]
	s_waitcnt vmcnt(63) expcnt(7) lgkmcnt(15)
	s_barrier
	global_load_lds_dwordx4 v[0:1], off
	s_mov_b32 m0, s43
	v_readfirstlane_b32 s43, v96
	global_load_lds_dwordx4 v[2:3], off
	v_lshl_add_u64 v[4:5], v[0:1], 0, s[8:9]
	s_mov_b32 m0, s43
	v_readfirstlane_b32 s43, v97
	global_load_lds_dwordx4 v[4:5], off
	v_lshl_add_u64 v[4:5], v[2:3], 0, s[8:9]
	s_mov_b32 m0, s43
	v_readfirstlane_b32 s43, v98
	global_load_lds_dwordx4 v[4:5], off
	v_lshl_add_u64 v[4:5], v[0:1], 0, s[10:11]
	s_mov_b32 m0, s43
	v_readfirstlane_b32 s43, v99
	global_load_lds_dwordx4 v[4:5], off
	v_lshl_add_u64 v[4:5], v[2:3], 0, s[10:11]
	s_mov_b32 m0, s43
	v_readfirstlane_b32 s43, v100
	global_load_lds_dwordx4 v[4:5], off
	v_lshl_add_u64 v[0:1], v[0:1], 0, s[12:13]
	s_mov_b32 m0, s43
	v_readfirstlane_b32 s43, v101
	global_load_lds_dwordx4 v[0:1], off
	v_lshl_add_u64 v[0:1], v[2:3], 0, s[12:13]
	s_mov_b32 m0, s43
	v_mov_b32_e32 v36, 0
	global_load_lds_dwordx4 v[0:1], off
	v_mad_i64_i32 v[72:73], s[44:45], s42, v93, v[68:69]
	v_lshl_add_u64 v[74:75], v[70:71], 0, s[34:35]
	s_mov_b64 s[34:35], 0
	s_mov_b32 s43, 0
	v_mov_b32_e32 v37, v36
	v_mov_b32_e32 v38, v36
	v_mov_b32_e32 v39, v36
	v_mov_b32_e32 v0, v36
	v_mov_b32_e32 v1, v36
	v_mov_b32_e32 v2, v36
	v_mov_b32_e32 v3, v36
	v_mov_b32_e32 v4, v36
	v_mov_b32_e32 v5, v36
	v_mov_b32_e32 v6, v36
	v_mov_b32_e32 v7, v36
	v_mov_b32_e32 v8, v36
	v_mov_b32_e32 v9, v36
	v_mov_b32_e32 v10, v36
	v_mov_b32_e32 v11, v36
	v_mov_b32_e32 v12, v36
	v_mov_b32_e32 v13, v36
	v_mov_b32_e32 v14, v36
	v_mov_b32_e32 v15, v36
	v_mov_b32_e32 v16, v36
	v_mov_b32_e32 v17, v36
	v_mov_b32_e32 v18, v36
	v_mov_b32_e32 v19, v36
	v_mov_b32_e32 v20, v36
	v_mov_b32_e32 v21, v36
	v_mov_b32_e32 v22, v36
	v_mov_b32_e32 v23, v36
	v_mov_b32_e32 v24, v36
	v_mov_b32_e32 v25, v36
	v_mov_b32_e32 v26, v36
	v_mov_b32_e32 v27, v36
	v_mov_b32_e32 v28, v36
	v_mov_b32_e32 v29, v36
	v_mov_b32_e32 v30, v36
	v_mov_b32_e32 v31, v36
	v_mov_b32_e32 v32, v36
	v_mov_b32_e32 v33, v36
	v_mov_b32_e32 v34, v36
	v_mov_b32_e32 v35, v36
	v_mov_b32_e32 v40, v36
	v_mov_b32_e32 v41, v36
	v_mov_b32_e32 v42, v36
	v_mov_b32_e32 v43, v36
	v_mov_b32_e32 v44, v36
	v_mov_b32_e32 v45, v36
	v_mov_b32_e32 v46, v36
	v_mov_b32_e32 v47, v36
	v_mov_b32_e32 v48, v36
	v_mov_b32_e32 v49, v36
	v_mov_b32_e32 v50, v36
	v_mov_b32_e32 v51, v36
	v_mov_b32_e32 v52, v36
	v_mov_b32_e32 v53, v36
	v_mov_b32_e32 v54, v36
	v_mov_b32_e32 v55, v36
	v_mov_b32_e32 v56, v36
	v_mov_b32_e32 v57, v36
	v_mov_b32_e32 v58, v36
	v_mov_b32_e32 v59, v36
	v_mov_b32_e32 v60, v36
	v_mov_b32_e32 v61, v36
	v_mov_b32_e32 v62, v36
	v_mov_b32_e32 v63, v36
	v_readfirstlane_b32 s96, v72
	v_readfirstlane_b32 s97, v73
	v_readfirstlane_b32 s88, v74
	v_readfirstlane_b32 s89, v75
	v_readfirstlane_b32 s87, v87
	s_nop 1
	v_subrev_u32_e32 v244, s96, v72
	v_subrev_u32_e32 v245, s88, v74
	v_add_u32_e32 v246, 0x11000, v244
	v_add_u32_e32 v247, 0x11000, v245
	v_add_u32_e32 v248, 0x22000, v244
	v_add_u32_e32 v249, 0x22000, v245
	v_add_u32_e32 v250, 0x33000, v244
	v_add_u32_e32 v251, 0x33000, v245
	s_add_u32 s96, s96, 0x2200080
	s_addc_u32 s97, s97, 0
	s_add_u32 s88, s88, 0xe70080
	s_addc_u32 s89, s89, 0
	v_add_u32_e32 v212, v88, v89
	v_add_u32_e32 v213, v89, v90
	v_add_u32_e32 v214, v88, v91
	v_add_u32_e32 v215, v90, v91
.LBB0_855:
	s_add_i32 s45, s43, 0x8000
	s_and_b32 s44, s45, 0x8000
	s_add_i32 s44, s44, 0
	s_add_u32 s86, s44, s87
	s_mov_b32 m0, s86
	s_waitcnt vmcnt(0) lgkmcnt(0)
	s_barrier
	global_load_lds_dwordx4 v244, s[96:97]
	s_add_u32 m0, s86, 0x4000
	s_nop 0
	global_load_lds_dwordx4 v245, s[88:89]
	s_add_u32 m0, s86, 0x1000
	s_nop 0
	global_load_lds_dwordx4 v246, s[96:97]
	s_add_u32 m0, s86, 0x5000
	s_nop 0
	global_load_lds_dwordx4 v247, s[88:89]
	s_add_u32 m0, s86, 0x2000
	s_nop 0
	global_load_lds_dwordx4 v248, s[96:97]
	s_add_u32 m0, s86, 0x6000
	s_nop 0
	global_load_lds_dwordx4 v249, s[88:89]
	s_add_u32 m0, s86, 0x3000
	s_nop 0
	global_load_lds_dwordx4 v250, s[96:97]
	s_add_u32 m0, s86, 0x7000
	s_nop 0
	global_load_lds_dwordx4 v251, s[88:89]
	s_add_u32 s96, s96, 0x80
	s_addc_u32 s97, s97, 0
	s_add_u32 s88, s88, 0x80
	s_addc_u32 s89, s89, 0
	s_and_b32 s43, s43, 0x8000
	s_add_i32 s43, s43, 0
	ds_read_b128 v[106:109], v213
	ds_read_b128 v[76:79], v212 offset:16384
	ds_read_b128 v[102:105], v212 offset:18432
	ds_read_b128 v[110:113], v213 offset:2048
	ds_read_b128 v[114:117], v212 offset:20480
	ds_read_b128 v[118:121], v212 offset:22528
	ds_read_b128 v[122:125], v212 offset:24576
	ds_read_b128 v[126:129], v212 offset:26624
	ds_read_b128 v[130:133], v212 offset:28672
	ds_read_b128 v[134:137], v212 offset:30720
	ds_read_b128 v[180:183], v215
	ds_read_b128 v[172:175], v214 offset:16384
	ds_read_b128 v[176:179], v214 offset:18432
	ds_read_b128 v[184:187], v215 offset:2048
	ds_read_b128 v[188:191], v214 offset:20480
	ds_read_b128 v[192:195], v214 offset:22528
	ds_read_b128 v[196:199], v214 offset:24576
	ds_read_b128 v[200:203], v214 offset:26624
	ds_read_b128 v[204:207], v214 offset:28672
	ds_read_b128 v[208:211], v214 offset:30720
	s_add_u32 s34, s34, 0x80
	s_addc_u32 s35, s35, 0
	s_cmpk_eq_i32 s34, 0x780
	s_mov_b32 s43, s45
	s_waitcnt lgkmcnt(15)
	v_mfma_f32_16x16x32_bf16 v[60:63], v[76:79], v[106:109], v[60:63]
	v_mfma_f32_16x16x32_bf16 v[56:59], v[102:105], v[106:109], v[56:59]
	v_mfma_f32_16x16x32_bf16 v[24:27], v[76:79], v[110:113], v[24:27]
	v_mfma_f32_16x16x32_bf16 v[20:23], v[102:105], v[110:113], v[20:23]
	v_mfma_f32_16x16x32_bf16 v[52:55], v[114:117], v[106:109], v[52:55]
	v_mfma_f32_16x16x32_bf16 v[16:19], v[114:117], v[110:113], v[16:19]
	s_waitcnt lgkmcnt(14)
	v_mfma_f32_16x16x32_bf16 v[48:51], v[118:121], v[106:109], v[48:51]
	v_mfma_f32_16x16x32_bf16 v[12:15], v[118:121], v[110:113], v[12:15]
	s_waitcnt lgkmcnt(13)
	v_mfma_f32_16x16x32_bf16 v[44:47], v[122:125], v[106:109], v[44:47]
	v_mfma_f32_16x16x32_bf16 v[8:11], v[122:125], v[110:113], v[8:11]
	s_waitcnt lgkmcnt(12)
	v_mfma_f32_16x16x32_bf16 v[40:43], v[126:129], v[106:109], v[40:43]
	v_mfma_f32_16x16x32_bf16 v[4:7], v[126:129], v[110:113], v[4:7]
	s_waitcnt lgkmcnt(11)
	v_mfma_f32_16x16x32_bf16 v[32:35], v[130:133], v[106:109], v[32:35]
	v_mfma_f32_16x16x32_bf16 v[0:3], v[130:133], v[110:113], v[0:3]
	s_waitcnt lgkmcnt(10)
	v_mfma_f32_16x16x32_bf16 v[28:31], v[134:137], v[106:109], v[28:31]
	v_mfma_f32_16x16x32_bf16 v[36:39], v[134:137], v[110:113], v[36:39]
	s_waitcnt lgkmcnt(8)
	v_mfma_f32_16x16x32_bf16 v[60:63], v[172:175], v[180:183], v[60:63]
	s_waitcnt lgkmcnt(7)
	v_mfma_f32_16x16x32_bf16 v[56:59], v[176:179], v[180:183], v[56:59]
	s_waitcnt lgkmcnt(6)
	v_mfma_f32_16x16x32_bf16 v[24:27], v[172:175], v[184:187], v[24:27]
	v_mfma_f32_16x16x32_bf16 v[20:23], v[176:179], v[184:187], v[20:23]
	s_waitcnt lgkmcnt(5)
	v_mfma_f32_16x16x32_bf16 v[52:55], v[188:191], v[180:183], v[52:55]
	v_mfma_f32_16x16x32_bf16 v[16:19], v[188:191], v[184:187], v[16:19]
	s_waitcnt lgkmcnt(4)
	v_mfma_f32_16x16x32_bf16 v[48:51], v[192:195], v[180:183], v[48:51]
	v_mfma_f32_16x16x32_bf16 v[12:15], v[192:195], v[184:187], v[12:15]
	s_waitcnt lgkmcnt(3)
	v_mfma_f32_16x16x32_bf16 v[44:47], v[196:199], v[180:183], v[44:47]
	v_mfma_f32_16x16x32_bf16 v[8:11], v[196:199], v[184:187], v[8:11]
	s_waitcnt lgkmcnt(2)
	v_mfma_f32_16x16x32_bf16 v[40:43], v[200:203], v[180:183], v[40:43]
	v_mfma_f32_16x16x32_bf16 v[4:7], v[200:203], v[184:187], v[4:7]
	s_waitcnt lgkmcnt(1)
	v_mfma_f32_16x16x32_bf16 v[32:35], v[204:207], v[180:183], v[32:35]
	v_mfma_f32_16x16x32_bf16 v[0:3], v[204:207], v[184:187], v[0:3]
	s_waitcnt lgkmcnt(0)
	v_mfma_f32_16x16x32_bf16 v[28:31], v[208:211], v[180:183], v[28:31]
	v_mfma_f32_16x16x32_bf16 v[36:39], v[208:211], v[184:187], v[36:39]
	s_cbranch_scc1 .Lu2x_855
	s_add_i32 s45, s43, 0x8000
	s_and_b32 s44, s45, 0x8000
	s_add_i32 s44, s44, 0
	s_add_u32 s86, s44, s87
	s_mov_b32 m0, s86
	s_waitcnt vmcnt(0) lgkmcnt(0)
	s_barrier
	global_load_lds_dwordx4 v244, s[96:97]
	s_add_u32 m0, s86, 0x4000
	s_nop 0
	global_load_lds_dwordx4 v245, s[88:89]
	s_add_u32 m0, s86, 0x1000
	s_nop 0
	global_load_lds_dwordx4 v246, s[96:97]
	s_add_u32 m0, s86, 0x5000
	s_nop 0
	global_load_lds_dwordx4 v247, s[88:89]
	s_add_u32 m0, s86, 0x2000
	s_nop 0
	global_load_lds_dwordx4 v248, s[96:97]
	s_add_u32 m0, s86, 0x6000
	s_nop 0
	global_load_lds_dwordx4 v249, s[88:89]
	s_add_u32 m0, s86, 0x3000
	s_nop 0
	global_load_lds_dwordx4 v250, s[96:97]
	s_add_u32 m0, s86, 0x7000
	s_nop 0
	global_load_lds_dwordx4 v251, s[88:89]
	s_add_u32 s96, s96, 0x80
	s_addc_u32 s97, s97, 0
	s_add_u32 s88, s88, 0x80
	s_addc_u32 s89, s89, 0
	s_and_b32 s43, s43, 0x8000
	s_add_i32 s43, s43, 0
	ds_read_b128 v[106:109], v213 offset:32768
	ds_read_b128 v[76:79], v212 offset:49152
	ds_read_b128 v[102:105], v212 offset:51200
	ds_read_b128 v[110:113], v213 offset:34816
	ds_read_b128 v[114:117], v212 offset:53248
	ds_read_b128 v[118:121], v212 offset:55296
	ds_read_b128 v[122:125], v212 offset:57344
	ds_read_b128 v[126:129], v212 offset:59392
	ds_read_b128 v[130:133], v212 offset:61440
	ds_read_b128 v[134:137], v212 offset:63488
	ds_read_b128 v[180:183], v215 offset:32768
	ds_read_b128 v[172:175], v214 offset:49152
	ds_read_b128 v[176:179], v214 offset:51200
	ds_read_b128 v[184:187], v215 offset:34816
	ds_read_b128 v[188:191], v214 offset:53248
	ds_read_b128 v[192:195], v214 offset:55296
	ds_read_b128 v[196:199], v214 offset:57344
	ds_read_b128 v[200:203], v214 offset:59392
	ds_read_b128 v[204:207], v214 offset:61440
	ds_read_b128 v[208:211], v214 offset:63488
	s_add_u32 s34, s34, 0x80
	s_addc_u32 s35, s35, 0
	s_cmpk_eq_i32 s34, 0x780
	s_mov_b32 s43, s45
	s_waitcnt lgkmcnt(15)
	v_mfma_f32_16x16x32_bf16 v[60:63], v[76:79], v[106:109], v[60:63]
	v_mfma_f32_16x16x32_bf16 v[56:59], v[102:105], v[106:109], v[56:59]
	v_mfma_f32_16x16x32_bf16 v[24:27], v[76:79], v[110:113], v[24:27]
	v_mfma_f32_16x16x32_bf16 v[20:23], v[102:105], v[110:113], v[20:23]
	v_mfma_f32_16x16x32_bf16 v[52:55], v[114:117], v[106:109], v[52:55]
	v_mfma_f32_16x16x32_bf16 v[16:19], v[114:117], v[110:113], v[16:19]
	s_waitcnt lgkmcnt(14)
	v_mfma_f32_16x16x32_bf16 v[48:51], v[118:121], v[106:109], v[48:51]
	v_mfma_f32_16x16x32_bf16 v[12:15], v[118:121], v[110:113], v[12:15]
	s_waitcnt lgkmcnt(13)
	v_mfma_f32_16x16x32_bf16 v[44:47], v[122:125], v[106:109], v[44:47]
	v_mfma_f32_16x16x32_bf16 v[8:11], v[122:125], v[110:113], v[8:11]
	s_waitcnt lgkmcnt(12)
	v_mfma_f32_16x16x32_bf16 v[40:43], v[126:129], v[106:109], v[40:43]
	v_mfma_f32_16x16x32_bf16 v[4:7], v[126:129], v[110:113], v[4:7]
	s_waitcnt lgkmcnt(11)
	v_mfma_f32_16x16x32_bf16 v[32:35], v[130:133], v[106:109], v[32:35]
	v_mfma_f32_16x16x32_bf16 v[0:3], v[130:133], v[110:113], v[0:3]
	s_waitcnt lgkmcnt(10)
	v_mfma_f32_16x16x32_bf16 v[28:31], v[134:137], v[106:109], v[28:31]
	v_mfma_f32_16x16x32_bf16 v[36:39], v[134:137], v[110:113], v[36:39]
	s_waitcnt lgkmcnt(8)
	v_mfma_f32_16x16x32_bf16 v[60:63], v[172:175], v[180:183], v[60:63]
	s_waitcnt lgkmcnt(7)
	v_mfma_f32_16x16x32_bf16 v[56:59], v[176:179], v[180:183], v[56:59]
	s_waitcnt lgkmcnt(6)
	v_mfma_f32_16x16x32_bf16 v[24:27], v[172:175], v[184:187], v[24:27]
	v_mfma_f32_16x16x32_bf16 v[20:23], v[176:179], v[184:187], v[20:23]
	s_waitcnt lgkmcnt(5)
	v_mfma_f32_16x16x32_bf16 v[52:55], v[188:191], v[180:183], v[52:55]
	v_mfma_f32_16x16x32_bf16 v[16:19], v[188:191], v[184:187], v[16:19]
	s_waitcnt lgkmcnt(4)
	v_mfma_f32_16x16x32_bf16 v[48:51], v[192:195], v[180:183], v[48:51]
	v_mfma_f32_16x16x32_bf16 v[12:15], v[192:195], v[184:187], v[12:15]
	s_waitcnt lgkmcnt(3)
	v_mfma_f32_16x16x32_bf16 v[44:47], v[196:199], v[180:183], v[44:47]
	v_mfma_f32_16x16x32_bf16 v[8:11], v[196:199], v[184:187], v[8:11]
	s_waitcnt lgkmcnt(2)
	v_mfma_f32_16x16x32_bf16 v[40:43], v[200:203], v[180:183], v[40:43]
	v_mfma_f32_16x16x32_bf16 v[4:7], v[200:203], v[184:187], v[4:7]
	s_waitcnt lgkmcnt(1)
	v_mfma_f32_16x16x32_bf16 v[32:35], v[204:207], v[180:183], v[32:35]
	v_mfma_f32_16x16x32_bf16 v[0:3], v[204:207], v[184:187], v[0:3]
	s_waitcnt lgkmcnt(0)
	v_mfma_f32_16x16x32_bf16 v[28:31], v[208:211], v[180:183], v[28:31]
	v_mfma_f32_16x16x32_bf16 v[36:39], v[208:211], v[184:187], v[36:39]
	s_cbranch_scc0 .LBB0_855
.Lu2x_855:
	v_add_u32_e32 v80, s44, v88
	v_add_u32_e32 v81, v80, v89
	v_add3_u32 v106, s44, v89, v90
	s_waitcnt vmcnt(0)
	s_barrier
	ds_read_b128 v[72:75], v81 offset:16384
	ds_read_b128 v[76:79], v81 offset:18432
	ds_read_b128 v[102:105], v106
	ds_read_b128 v[106:109], v106 offset:2048
	ds_read_b128 v[110:113], v81 offset:20480
	ds_read_b128 v[114:117], v81 offset:22528
	ds_read_b128 v[118:121], v81 offset:24576
	ds_read_b128 v[122:125], v81 offset:26624
	ds_read_b128 v[126:129], v81 offset:28672
	ds_read_b128 v[130:133], v81 offset:30720
	v_add_u32_e32 v80, v80, v91
	s_waitcnt lgkmcnt(7)
	v_mfma_f32_16x16x32_bf16 v[60:63], v[72:75], v[102:105], v[60:63]
	s_lshl_b32 s42, s42, 7
	v_mfma_f32_16x16x32_bf16 v[56:59], v[76:79], v[102:105], v[56:59]
	s_waitcnt lgkmcnt(4)
	v_mfma_f32_16x16x32_bf16 v[48:51], v[114:117], v[102:105], v[48:51]
	s_waitcnt lgkmcnt(3)
	v_mfma_f32_16x16x32_bf16 v[44:47], v[118:121], v[102:105], v[44:47]
	s_waitcnt lgkmcnt(2)
	v_mfma_f32_16x16x32_bf16 v[40:43], v[122:125], v[102:105], v[40:43]
	s_waitcnt lgkmcnt(1)
	v_mfma_f32_16x16x32_bf16 v[32:35], v[126:129], v[102:105], v[32:35]
	s_waitcnt lgkmcnt(0)
	v_mfma_f32_16x16x32_bf16 v[28:31], v[130:133], v[102:105], v[28:31]
	v_mfma_f32_16x16x32_bf16 v[24:27], v[72:75], v[106:109], v[24:27]
	ds_read_b128 v[72:75], v80 offset:16384
	v_mfma_f32_16x16x32_bf16 v[52:55], v[110:113], v[102:105], v[52:55]
	v_mfma_f32_16x16x32_bf16 v[20:23], v[76:79], v[106:109], v[20:23]
	v_mfma_f32_16x16x32_bf16 v[16:19], v[110:113], v[106:109], v[16:19]
	v_mfma_f32_16x16x32_bf16 v[12:15], v[114:117], v[106:109], v[12:15]
	v_mfma_f32_16x16x32_bf16 v[8:11], v[118:121], v[106:109], v[8:11]
	v_mfma_f32_16x16x32_bf16 v[4:7], v[122:125], v[106:109], v[4:7]
	v_mfma_f32_16x16x32_bf16 v[0:3], v[126:129], v[106:109], v[0:3]
	v_mfma_f32_16x16x32_bf16 v[102:105], v[130:133], v[106:109], v[36:39]
	s_nop 2
	v_add3_u32 v36, s44, v91, v90
	ds_read_b128 v[76:79], v80 offset:18432
	ds_read_b128 v[106:109], v36
	ds_read_b128 v[110:113], v36 offset:2048
	ds_read_b128 v[130:133], v80 offset:28672
	ds_read_b128 v[134:137], v80 offset:30720
	ds_read_b128 v[114:117], v80 offset:20480
	ds_read_b128 v[118:121], v80 offset:22528
	ds_read_b128 v[122:125], v80 offset:24576
	ds_read_b128 v[126:129], v80 offset:26624
	s_waitcnt lgkmcnt(7)
	v_mfma_f32_16x16x32_bf16 v[60:63], v[72:75], v[106:109], v[60:63]
	v_readlane_b32 s44, v252, 5
	v_readlane_b32 s48, v252, 9
	v_readlane_b32 s49, v252, 10
	s_waitcnt lgkmcnt(5)
	v_mfma_f32_16x16x32_bf16 v[36:39], v[130:133], v[106:109], v[32:35]
	v_readlane_b32 s45, v252, 6
	v_readlane_b32 s46, v252, 7
	v_readlane_b32 s47, v252, 8
	s_waitcnt lgkmcnt(4)
	v_mfma_f32_16x16x32_bf16 v[32:35], v[134:137], v[106:109], v[28:31]
	v_readlane_b32 s50, v252, 11
	v_readlane_b32 s51, v252, 12
	v_readlane_b32 s52, v252, 13
	v_mfma_f32_16x16x32_bf16 v[28:31], v[72:75], v[110:113], v[24:27]
	v_add_u32_e32 v72, s42, v82
	v_mul_hi_i32 v73, v72, s36
	v_lshrrev_b32_e32 v74, 31, v73
	v_mfma_f32_16x16x32_bf16 v[24:27], v[76:79], v[110:113], v[20:23]
	v_readlane_b32 s53, v252, 14
	v_readlane_b32 s54, v252, 15
	v_readlane_b32 s55, v252, 16
	s_waitcnt lgkmcnt(3)
	v_mfma_f32_16x16x32_bf16 v[20:23], v[114:117], v[110:113], v[16:19]
	v_readlane_b32 s56, v252, 17
	v_readlane_b32 s57, v252, 18
	v_readlane_b32 s58, v252, 19
	s_waitcnt lgkmcnt(2)
	v_mfma_f32_16x16x32_bf16 v[16:19], v[118:121], v[110:113], v[12:15]
	v_readlane_b32 s59, v252, 20
	s_waitcnt lgkmcnt(1)
	v_mfma_f32_16x16x32_bf16 v[12:15], v[122:125], v[110:113], v[8:11]
	s_waitcnt lgkmcnt(0)
	v_mfma_f32_16x16x32_bf16 v[8:11], v[126:129], v[110:113], v[4:7]
	s_nop 2
	v_ashrrev_i32_e32 v4, 11, v73
	v_mfma_f32_16x16x32_bf16 v[56:59], v[76:79], v[106:109], v[56:59]
	v_add_u32_e32 v73, v4, v74
	v_mad_i32_i24 v75, v73, s37, v72
	v_lshlrev_b32_e32 v78, 13, v73
	v_mfma_f32_16x16x32_bf16 v[52:55], v[114:117], v[106:109], v[52:55]
	v_cmp_lt_i32_e32 vcc, s38, v75
	v_mov_b64_e32 v[76:77], s[48:49]
	v_add3_u32 v74, v78, v75, s39
	v_mfma_f32_16x16x32_bf16 v[48:51], v[118:121], v[106:109], v[48:51]
	v_mfma_f32_16x16x32_bf16 v[44:47], v[122:125], v[106:109], v[44:47]
	v_mfma_f32_16x16x32_bf16 v[40:43], v[126:129], v[106:109], v[40:43]
	v_mfma_f32_16x16x32_bf16 v[0:3], v[130:133], v[110:113], v[0:3]
	v_mfma_f32_16x16x32_bf16 v[4:7], v[134:137], v[110:113], v[102:105]
	s_and_saveexec_b64 s[34:35], vcc
	s_xor_b64 s[34:35], exec, s[34:35]
	s_cbranch_execz .LBB0_858
	v_readlane_b32 s44, v252, 5
	v_readlane_b32 s45, v252, 6
	v_add3_u32 v72, v78, v75, s39
	v_readlane_b32 s46, v252, 7
	v_readlane_b32 s47, v252, 8
	v_readlane_b32 s48, v252, 9
	v_readlane_b32 s49, v252, 10
	v_readlane_b32 s50, v252, 11
	v_readlane_b32 s51, v252, 12
	v_readlane_b32 s52, v252, 13
	v_readlane_b32 s53, v252, 14
	v_readlane_b32 s54, v252, 15
	v_readlane_b32 s55, v252, 16
	v_readlane_b32 s56, v252, 17
	v_readlane_b32 s57, v252, 18
	v_readlane_b32 s58, v252, 19
	v_readlane_b32 s59, v252, 20
	v_mov_b64_e32 v[76:77], s[44:45]
	s_or_saveexec_b64 s[34:35], s[34:35]
	v_lshl_add_u32 v102, v73, 8, v75
	s_xor_b64 exec, exec, s[34:35]
	s_branch .LBB0_859

.LBB0_1005:
	s_ashr_i32 s26, s31, 31
	s_lshr_b32 s26, s26, 29
	s_add_i32 s26, s31, s26
	s_ashr_i32 s27, s26, 3
	s_and_b32 s26, s26, -8
	s_sub_i32 s26, s31, s26
	s_cmp_lt_i32 s26, 0
	s_cselect_b32 s33, s29, 0x210
	s_mul_i32 s26, s33, s26
	s_add_i32 s35, s26, s27
	s_ashr_i32 s26, s35, 31
	s_lshr_b32 s26, s26, 24
	s_add_i32 s26, s35, s26
	s_ashr_i32 s27, s26, 8
	s_lshl_b32 s37, s27, 3
	s_and_b32 s36, s26, 0xffffff00
	s_sub_i32 s26, 0x84, s37
	s_min_u32 s38, s26, 8
	s_sub_i32 s34, s35, s36
	v_cvt_f32_ubyte0_e32 v1, s38
	v_cvt_f32_i32_e32 v0, s34
	v_rcp_iflag_f32_e32 v2, v1
	s_ashr_i32 s26, s34, 30
	s_or_b32 s33, s26, 1
	s_waitcnt lgkmcnt(0)
	v_mul_f32_e32 v2, v0, v2
	v_trunc_f32_e32 v2, v2
	v_fma_f32 v0, -v2, v1, v0
	v_cvt_i32_f32_e32 v2, v2
	v_cmp_ge_f32_e64 s[26:27], |v0|, v1
	s_and_b64 s[26:27], s[26:27], exec
	s_cselect_b32 s26, s33, 0
	v_readfirstlane_b32 s27, v2
	s_add_i32 s26, s27, s26
	s_mul_i32 s38, s26, s38
	s_sext_i32_i16 s33, s26
	s_sub_i32 s26, s34, s38
	s_sext_i32_i16 s26, s26
	s_add_i32 s34, s37, s26
	v_mad_i64_i32 v[0:1], s[26:27], s34, v85, v[66:67]
	v_mad_i64_i32 v[2:3], s[26:27], s33, v85, v[68:69]
	v_readfirstlane_b32 s26, v86
	s_mov_b32 m0, s26
	v_readfirstlane_b32 s26, v87
	s_barrier
	global_load_lds_dwordx4 v[0:1], off
	s_mov_b32 m0, s26
	v_readfirstlane_b32 s26, v88
	global_load_lds_dwordx4 v[2:3], off
	v_lshl_add_u64 v[4:5], v[0:1], 0, s[4:5]
	s_mov_b32 m0, s26
	v_readfirstlane_b32 s26, v89
	global_load_lds_dwordx4 v[4:5], off
	v_lshl_add_u64 v[4:5], v[2:3], 0, s[4:5]
	s_mov_b32 m0, s26
	v_readfirstlane_b32 s26, v90
	global_load_lds_dwordx4 v[4:5], off
	v_lshl_add_u64 v[4:5], v[0:1], 0, s[6:7]
	s_mov_b32 m0, s26
	v_readfirstlane_b32 s26, v91
	global_load_lds_dwordx4 v[4:5], off
	v_lshl_add_u64 v[4:5], v[2:3], 0, s[6:7]
	s_mov_b32 m0, s26
	v_readfirstlane_b32 s26, v92
	global_load_lds_dwordx4 v[4:5], off
	v_lshl_add_u64 v[0:1], v[0:1], 0, s[8:9]
	s_mov_b32 m0, s26
	v_readfirstlane_b32 s26, v93
	global_load_lds_dwordx4 v[0:1], off
	v_lshl_add_u64 v[0:1], v[2:3], 0, s[8:9]
	s_mov_b32 m0, s26
	s_sub_i32 s26, s35, s38
	global_load_lds_dwordx4 v[0:1], off
	s_sub_i32 s26, s26, s36
	s_sext_i32_i16 s26, s26
	s_add_i32 s37, s37, s26
	v_mad_i64_i32 v[74:75], s[26:27], s37, v85, v[70:71]
	v_mad_i64_i32 v[76:77], s[26:27], s33, v85, v[72:73]
	s_mov_b64 s[26:27], 0
	s_mov_b32 s35, 0
	v_mov_b32_e32 v20, 0
	v_mov_b32_e32 v21, v65
	v_mov_b32_e32 v22, v65
	v_mov_b32_e32 v23, v65
	v_mov_b32_e32 v0, 0
	v_mov_b32_e32 v1, v65
	v_mov_b32_e32 v2, v65
	v_mov_b32_e32 v3, v65
	v_mov_b32_e32 v4, 0
	v_mov_b32_e32 v5, v65
	v_mov_b32_e32 v6, v65
	v_mov_b32_e32 v7, v65
	v_mov_b32_e32 v8, 0
	v_mov_b32_e32 v9, v65
	v_mov_b32_e32 v10, v65
	v_mov_b32_e32 v11, v65
	v_mov_b32_e32 v12, 0
	v_mov_b32_e32 v13, v65
	v_mov_b32_e32 v14, v65
	v_mov_b32_e32 v15, v65
	v_mov_b32_e32 v16, 0
	v_mov_b32_e32 v17, v65
	v_mov_b32_e32 v18, v65
	v_mov_b32_e32 v19, v65
	v_mov_b32_e32 v24, 0
	v_mov_b32_e32 v25, v65
	v_mov_b32_e32 v26, v65
	v_mov_b32_e32 v27, v65
	v_mov_b32_e32 v28, 0
	v_mov_b32_e32 v29, v65
	v_mov_b32_e32 v30, v65
	v_mov_b32_e32 v31, v65
	v_mov_b32_e32 v32, 0
	v_mov_b32_e32 v33, v65
	v_mov_b32_e32 v34, v65
	v_mov_b32_e32 v35, v65
	v_mov_b32_e32 v36, 0
	v_mov_b32_e32 v37, v65
	v_mov_b32_e32 v38, v65
	v_mov_b32_e32 v39, v65
	v_mov_b32_e32 v40, 0
	v_mov_b32_e32 v41, v65
	v_mov_b32_e32 v42, v65
	v_mov_b32_e32 v43, v65
	v_mov_b32_e32 v44, 0
	v_mov_b32_e32 v45, v65
	v_mov_b32_e32 v46, v65
	v_mov_b32_e32 v47, v65
	v_mov_b32_e32 v48, 0
	v_mov_b32_e32 v49, v65
	v_mov_b32_e32 v50, v65
	v_mov_b32_e32 v51, v65
	v_mov_b32_e32 v52, 0
	v_mov_b32_e32 v53, v65
	v_mov_b32_e32 v54, v65
	v_mov_b32_e32 v55, v65
	v_mov_b32_e32 v56, 0
	v_mov_b32_e32 v57, v65
	v_mov_b32_e32 v58, v65
	v_mov_b32_e32 v59, v65
	v_mov_b32_e32 v60, 0
	v_mov_b32_e32 v61, v65
	v_mov_b32_e32 v62, v65
	v_mov_b32_e32 v63, v65
	v_readfirstlane_b32 s96, v74
	v_readfirstlane_b32 s97, v75
	v_readfirstlane_b32 s88, v76
	v_readfirstlane_b32 s89, v77
	v_readfirstlane_b32 s87, v78
	s_nop 1
	v_subrev_u32_e32 v244, s96, v74
	v_subrev_u32_e32 v245, s88, v76
	v_add_u32_e32 v246, 0x11000, v244
	v_add_u32_e32 v247, 0x11000, v245
	v_add_u32_e32 v248, 0x22000, v244
	v_add_u32_e32 v249, 0x22000, v245
	v_add_u32_e32 v250, 0x33000, v244
	v_add_u32_e32 v251, 0x33000, v245
	s_add_u32 s96, s96, 0x2200080
	s_addc_u32 s97, s97, 0
	s_add_u32 s88, s88, 0x1090080
	s_addc_u32 s89, s89, 0
	v_add_u32_e32 v143, v80, v81
	v_add_u32_e32 v145, v81, v82
	v_add_u32_e32 v206, v80, v83
	v_add_u32_e32 v207, v82, v83
.LBB0_1006:
	s_add_i32 s37, s35, 0x8000
	s_and_b32 s36, s37, 0x8000
	s_add_i32 s36, s36, 0
	s_add_u32 s86, s36, s87
	s_mov_b32 m0, s86
	s_waitcnt vmcnt(0) lgkmcnt(0)
	s_barrier
	global_load_lds_dwordx4 v244, s[96:97]
	s_add_u32 m0, s86, 0x4000
	s_nop 0
	global_load_lds_dwordx4 v245, s[88:89]
	s_add_u32 m0, s86, 0x1000
	s_nop 0
	global_load_lds_dwordx4 v246, s[96:97]
	s_add_u32 m0, s86, 0x5000
	s_nop 0
	global_load_lds_dwordx4 v247, s[88:89]
	s_add_u32 m0, s86, 0x2000
	s_nop 0
	global_load_lds_dwordx4 v248, s[96:97]
	s_add_u32 m0, s86, 0x6000
	s_nop 0
	global_load_lds_dwordx4 v249, s[88:89]
	s_add_u32 m0, s86, 0x3000
	s_nop 0
	global_load_lds_dwordx4 v250, s[96:97]
	s_add_u32 m0, s86, 0x7000
	s_nop 0
	global_load_lds_dwordx4 v251, s[88:89]
	s_add_u32 s96, s96, 0x80
	s_addc_u32 s97, s97, 0
	s_add_u32 s88, s88, 0x80
	s_addc_u32 s89, s89, 0
	s_and_b32 s35, s35, 0x8000
	s_add_i32 s35, s35, 0
	ds_read_b128 v[102:105], v145
	ds_read_b128 v[94:97], v143 offset:16384
	ds_read_b128 v[98:101], v143 offset:18432
	ds_read_b128 v[106:109], v145 offset:2048
	ds_read_b128 v[110:113], v143 offset:20480
	ds_read_b128 v[114:117], v143 offset:22528
	ds_read_b128 v[118:121], v143 offset:24576
	ds_read_b128 v[122:125], v143 offset:26624
	ds_read_b128 v[126:129], v143 offset:28672
	ds_read_b128 v[130:133], v143 offset:30720
	ds_read_b128 v[174:177], v207
	ds_read_b128 v[166:169], v206 offset:16384
	ds_read_b128 v[170:173], v206 offset:18432
	ds_read_b128 v[178:181], v207 offset:2048
	ds_read_b128 v[182:185], v206 offset:20480
	ds_read_b128 v[186:189], v206 offset:22528
	ds_read_b128 v[190:193], v206 offset:24576
	ds_read_b128 v[194:197], v206 offset:26624
	ds_read_b128 v[198:201], v206 offset:28672
	ds_read_b128 v[202:205], v206 offset:30720
	s_add_u32 s26, s26, 0x80
	s_addc_u32 s27, s27, 0
	s_cmpk_eq_i32 s26, 0x780
	s_mov_b32 s35, s37
	s_waitcnt lgkmcnt(15)
	v_mfma_f32_16x16x32_bf16 v[60:63], v[94:97], v[102:105], v[60:63]
	v_mfma_f32_16x16x32_bf16 v[56:59], v[98:101], v[102:105], v[56:59]
	v_mfma_f32_16x16x32_bf16 v[28:31], v[94:97], v[106:109], v[28:31]
	v_mfma_f32_16x16x32_bf16 v[24:27], v[98:101], v[106:109], v[24:27]
	v_mfma_f32_16x16x32_bf16 v[52:55], v[110:113], v[102:105], v[52:55]
	v_mfma_f32_16x16x32_bf16 v[16:19], v[110:113], v[106:109], v[16:19]
	s_waitcnt lgkmcnt(14)
	v_mfma_f32_16x16x32_bf16 v[48:51], v[114:117], v[102:105], v[48:51]
	v_mfma_f32_16x16x32_bf16 v[12:15], v[114:117], v[106:109], v[12:15]
	s_waitcnt lgkmcnt(13)
	v_mfma_f32_16x16x32_bf16 v[44:47], v[118:121], v[102:105], v[44:47]
	v_mfma_f32_16x16x32_bf16 v[8:11], v[118:121], v[106:109], v[8:11]
	s_waitcnt lgkmcnt(12)
	v_mfma_f32_16x16x32_bf16 v[40:43], v[122:125], v[102:105], v[40:43]
	v_mfma_f32_16x16x32_bf16 v[4:7], v[122:125], v[106:109], v[4:7]
	s_waitcnt lgkmcnt(11)
	v_mfma_f32_16x16x32_bf16 v[36:39], v[126:129], v[102:105], v[36:39]
	v_mfma_f32_16x16x32_bf16 v[0:3], v[126:129], v[106:109], v[0:3]
	s_waitcnt lgkmcnt(10)
	v_mfma_f32_16x16x32_bf16 v[32:35], v[130:133], v[102:105], v[32:35]
	v_mfma_f32_16x16x32_bf16 v[20:23], v[130:133], v[106:109], v[20:23]
	s_waitcnt lgkmcnt(8)
	v_mfma_f32_16x16x32_bf16 v[60:63], v[166:169], v[174:177], v[60:63]
	s_waitcnt lgkmcnt(7)
	v_mfma_f32_16x16x32_bf16 v[56:59], v[170:173], v[174:177], v[56:59]
	s_waitcnt lgkmcnt(6)
	v_mfma_f32_16x16x32_bf16 v[28:31], v[166:169], v[178:181], v[28:31]
	v_mfma_f32_16x16x32_bf16 v[24:27], v[170:173], v[178:181], v[24:27]
	s_waitcnt lgkmcnt(5)
	v_mfma_f32_16x16x32_bf16 v[52:55], v[182:185], v[174:177], v[52:55]
	v_mfma_f32_16x16x32_bf16 v[16:19], v[182:185], v[178:181], v[16:19]
	s_waitcnt lgkmcnt(4)
	v_mfma_f32_16x16x32_bf16 v[48:51], v[186:189], v[174:177], v[48:51]
	v_mfma_f32_16x16x32_bf16 v[12:15], v[186:189], v[178:181], v[12:15]
	s_waitcnt lgkmcnt(3)
	v_mfma_f32_16x16x32_bf16 v[44:47], v[190:193], v[174:177], v[44:47]
	v_mfma_f32_16x16x32_bf16 v[8:11], v[190:193], v[178:181], v[8:11]
	s_waitcnt lgkmcnt(2)
	v_mfma_f32_16x16x32_bf16 v[40:43], v[194:197], v[174:177], v[40:43]
	v_mfma_f32_16x16x32_bf16 v[4:7], v[194:197], v[178:181], v[4:7]
	s_waitcnt lgkmcnt(1)
	v_mfma_f32_16x16x32_bf16 v[36:39], v[198:201], v[174:177], v[36:39]
	v_mfma_f32_16x16x32_bf16 v[0:3], v[198:201], v[178:181], v[0:3]
	s_waitcnt lgkmcnt(0)
	v_mfma_f32_16x16x32_bf16 v[32:35], v[202:205], v[174:177], v[32:35]
	v_mfma_f32_16x16x32_bf16 v[20:23], v[202:205], v[178:181], v[20:23]
	s_cbranch_scc1 .Lu2x_1006
	s_add_i32 s37, s35, 0x8000
	s_and_b32 s36, s37, 0x8000
	s_add_i32 s36, s36, 0
	s_add_u32 s86, s36, s87
	s_mov_b32 m0, s86
	s_waitcnt vmcnt(0) lgkmcnt(0)
	s_barrier
	global_load_lds_dwordx4 v244, s[96:97]
	s_add_u32 m0, s86, 0x4000
	s_nop 0
	global_load_lds_dwordx4 v245, s[88:89]
	s_add_u32 m0, s86, 0x1000
	s_nop 0
	global_load_lds_dwordx4 v246, s[96:97]
	s_add_u32 m0, s86, 0x5000
	s_nop 0
	global_load_lds_dwordx4 v247, s[88:89]
	s_add_u32 m0, s86, 0x2000
	s_nop 0
	global_load_lds_dwordx4 v248, s[96:97]
	s_add_u32 m0, s86, 0x6000
	s_nop 0
	global_load_lds_dwordx4 v249, s[88:89]
	s_add_u32 m0, s86, 0x3000
	s_nop 0
	global_load_lds_dwordx4 v250, s[96:97]
	s_add_u32 m0, s86, 0x7000
	s_nop 0
	global_load_lds_dwordx4 v251, s[88:89]
	s_add_u32 s96, s96, 0x80
	s_addc_u32 s97, s97, 0
	s_add_u32 s88, s88, 0x80
	s_addc_u32 s89, s89, 0
	s_and_b32 s35, s35, 0x8000
	s_add_i32 s35, s35, 0
	ds_read_b128 v[102:105], v145 offset:32768
	ds_read_b128 v[94:97], v143 offset:49152
	ds_read_b128 v[98:101], v143 offset:51200
	ds_read_b128 v[106:109], v145 offset:34816
	ds_read_b128 v[110:113], v143 offset:53248
	ds_read_b128 v[114:117], v143 offset:55296
	ds_read_b128 v[118:121], v143 offset:57344
	ds_read_b128 v[122:125], v143 offset:59392
	ds_read_b128 v[126:129], v143 offset:61440
	ds_read_b128 v[130:133], v143 offset:63488
	ds_read_b128 v[174:177], v207 offset:32768
	ds_read_b128 v[166:169], v206 offset:49152
	ds_read_b128 v[170:173], v206 offset:51200
	ds_read_b128 v[178:181], v207 offset:34816
	ds_read_b128 v[182:185], v206 offset:53248
	ds_read_b128 v[186:189], v206 offset:55296
	ds_read_b128 v[190:193], v206 offset:57344
	ds_read_b128 v[194:197], v206 offset:59392
	ds_read_b128 v[198:201], v206 offset:61440
	ds_read_b128 v[202:205], v206 offset:63488
	s_add_u32 s26, s26, 0x80
	s_addc_u32 s27, s27, 0
	s_cmpk_eq_i32 s26, 0x780
	s_mov_b32 s35, s37
	s_waitcnt lgkmcnt(15)
	v_mfma_f32_16x16x32_bf16 v[60:63], v[94:97], v[102:105], v[60:63]
	v_mfma_f32_16x16x32_bf16 v[56:59], v[98:101], v[102:105], v[56:59]
	v_mfma_f32_16x16x32_bf16 v[28:31], v[94:97], v[106:109], v[28:31]
	v_mfma_f32_16x16x32_bf16 v[24:27], v[98:101], v[106:109], v[24:27]
	v_mfma_f32_16x16x32_bf16 v[52:55], v[110:113], v[102:105], v[52:55]
	v_mfma_f32_16x16x32_bf16 v[16:19], v[110:113], v[106:109], v[16:19]
	s_waitcnt lgkmcnt(14)
	v_mfma_f32_16x16x32_bf16 v[48:51], v[114:117], v[102:105], v[48:51]
	v_mfma_f32_16x16x32_bf16 v[12:15], v[114:117], v[106:109], v[12:15]
	s_waitcnt lgkmcnt(13)
	v_mfma_f32_16x16x32_bf16 v[44:47], v[118:121], v[102:105], v[44:47]
	v_mfma_f32_16x16x32_bf16 v[8:11], v[118:121], v[106:109], v[8:11]
	s_waitcnt lgkmcnt(12)
	v_mfma_f32_16x16x32_bf16 v[40:43], v[122:125], v[102:105], v[40:43]
	v_mfma_f32_16x16x32_bf16 v[4:7], v[122:125], v[106:109], v[4:7]
	s_waitcnt lgkmcnt(11)
	v_mfma_f32_16x16x32_bf16 v[36:39], v[126:129], v[102:105], v[36:39]
	v_mfma_f32_16x16x32_bf16 v[0:3], v[126:129], v[106:109], v[0:3]
	s_waitcnt lgkmcnt(10)
	v_mfma_f32_16x16x32_bf16 v[32:35], v[130:133], v[102:105], v[32:35]
	v_mfma_f32_16x16x32_bf16 v[20:23], v[130:133], v[106:109], v[20:23]
	s_waitcnt lgkmcnt(8)
	v_mfma_f32_16x16x32_bf16 v[60:63], v[166:169], v[174:177], v[60:63]
	s_waitcnt lgkmcnt(7)
	v_mfma_f32_16x16x32_bf16 v[56:59], v[170:173], v[174:177], v[56:59]
	s_waitcnt lgkmcnt(6)
	v_mfma_f32_16x16x32_bf16 v[28:31], v[166:169], v[178:181], v[28:31]
	v_mfma_f32_16x16x32_bf16 v[24:27], v[170:173], v[178:181], v[24:27]
	s_waitcnt lgkmcnt(5)
	v_mfma_f32_16x16x32_bf16 v[52:55], v[182:185], v[174:177], v[52:55]
	v_mfma_f32_16x16x32_bf16 v[16:19], v[182:185], v[178:181], v[16:19]
	s_waitcnt lgkmcnt(4)
	v_mfma_f32_16x16x32_bf16 v[48:51], v[186:189], v[174:177], v[48:51]
	v_mfma_f32_16x16x32_bf16 v[12:15], v[186:189], v[178:181], v[12:15]
	s_waitcnt lgkmcnt(3)
	v_mfma_f32_16x16x32_bf16 v[44:47], v[190:193], v[174:177], v[44:47]
	v_mfma_f32_16x16x32_bf16 v[8:11], v[190:193], v[178:181], v[8:11]
	s_waitcnt lgkmcnt(2)
	v_mfma_f32_16x16x32_bf16 v[40:43], v[194:197], v[174:177], v[40:43]
	v_mfma_f32_16x16x32_bf16 v[4:7], v[194:197], v[178:181], v[4:7]
	s_waitcnt lgkmcnt(1)
	v_mfma_f32_16x16x32_bf16 v[36:39], v[198:201], v[174:177], v[36:39]
	v_mfma_f32_16x16x32_bf16 v[0:3], v[198:201], v[178:181], v[0:3]
	s_waitcnt lgkmcnt(0)
	v_mfma_f32_16x16x32_bf16 v[32:35], v[202:205], v[174:177], v[32:35]
	v_mfma_f32_16x16x32_bf16 v[20:23], v[202:205], v[178:181], v[20:23]
	s_cbranch_scc0 .LBB0_1006
.Lu2x_1006:
	v_add_u32_e32 v138, s36, v80
	v_add_u32_e32 v126, v138, v81
	s_waitcnt vmcnt(0)
	s_barrier
	ds_read_b128 v[74:77], v126 offset:16384
	v_add3_u32 v102, s36, v81, v82
	ds_read_b128 v[94:97], v102
	ds_read_b128 v[98:101], v126 offset:18432
	ds_read_b128 v[102:105], v102 offset:2048
	ds_read_b128 v[106:109], v126 offset:20480
	ds_read_b128 v[110:113], v126 offset:22528
	ds_read_b128 v[114:117], v126 offset:24576
	ds_read_b128 v[118:121], v126 offset:26624
	v_add3_u32 v134, s36, v83, v82
	v_add_u32_e32 v142, v138, v83
	ds_read_b128 v[122:125], v126 offset:28672
	ds_read_b128 v[126:129], v126 offset:30720
	ds_read_b128 v[130:133], v134
	ds_read_b128 v[134:137], v134 offset:2048
	ds_read_b128 v[138:141], v142 offset:16384
	ds_read_b128 v[146:149], v142 offset:18432
	s_waitcnt lgkmcnt(11)
	v_mfma_f32_16x16x32_bf16 v[56:59], v[98:101], v[94:97], v[56:59]
	s_lshl_b32 s36, s34, 7
	s_lshl_b32 s26, s33, 7
	s_ashr_i32 s27, s26, 31
	v_mfma_f32_16x16x32_bf16 v[60:63], v[74:77], v[94:97], v[60:63]
	s_lshl_b64 s[26:27], s[26:27], 1
	s_add_i32 s31, s31, s28
	s_cmpk_gt_i32 s31, 0x107f
	s_waitcnt lgkmcnt(0)
	v_mfma_f32_16x16x32_bf16 v[56:59], v[146:149], v[130:133], v[56:59]
	v_mfma_f32_16x16x32_bf16 v[48:51], v[110:113], v[94:97], v[48:51]
	v_mfma_f32_16x16x32_bf16 v[52:55], v[106:109], v[94:97], v[52:55]
	s_nop 5
	v_max_f32_e32 v56, v56, v56
	v_max_f32_e32 v57, v57, v57
	v_max_f32_e32 v56, 0, v56
	v_mfma_f32_16x16x32_bf16 v[44:47], v[114:117], v[94:97], v[44:47]
	v_max_f32_e32 v57, 0, v57
	v_max_f32_e32 v59, v59, v59
	v_max_f32_e32 v59, 0, v59
	v_mfma_f32_16x16x32_bf16 v[40:43], v[118:121], v[94:97], v[40:43]
	v_mfma_f32_16x16x32_bf16 v[36:39], v[122:125], v[94:97], v[36:39]
	v_mfma_f32_16x16x32_bf16 v[32:35], v[126:129], v[94:97], v[32:35]
	ds_read_b128 v[94:97], v142 offset:20480
	ds_read_b128 v[150:153], v142 offset:22528
	ds_read_b128 v[154:157], v142 offset:24576
	ds_read_b128 v[158:161], v142 offset:26624
	v_mfma_f32_16x16x32_bf16 v[60:63], v[138:141], v[130:133], v[60:63]
	s_waitcnt lgkmcnt(2)
	v_mfma_f32_16x16x32_bf16 v[48:51], v[150:153], v[130:133], v[48:51]
	v_mfma_f32_16x16x32_bf16 v[16:19], v[106:109], v[102:105], v[16:19]
	v_mul_f32_e64 v106, v56, v56
	v_mul_f32_e64 v107, v57, v57
	v_max_f32_e32 v57, v58, v58
	s_nop 1
	v_max_f32_e32 v60, v60, v60
	v_mfma_f32_16x16x32_bf16 v[24:27], v[98:101], v[102:105], v[24:27]
	v_add_u32_e32 v100, s36, v79
	v_mov_b64_e32 v[98:99], s[0:1]
	v_max_f32_e32 v61, v61, v61
	v_max_f32_e32 v56, v62, v62
	v_max_f32_e32 v58, 0, v57
	v_max_f32_e32 v57, v63, v63
	v_mad_i64_i32 v[100:101], s[34:35], v100, s30, v[98:99]
	v_max_f32_e32 v60, 0, v60
	v_max_f32_e32 v61, 0, v61
	v_max_f32_e32 v56, 0, v56
	v_max_f32_e32 v57, 0, v57
	v_mfma_f32_16x16x32_bf16 v[52:55], v[94:97], v[130:133], v[52:55]
	v_lshl_add_u64 v[100:101], v[100:101], 0, s[26:27]
	v_pk_mul_f32 v[60:61], v[60:61], v[60:61]
	v_pk_mul_f32 v[62:63], v[56:57], v[56:57]
	v_mfma_f32_16x16x32_bf16 v[28:31], v[74:77], v[102:105], v[28:31]
	v_max_f32_e32 v48, v48, v48
	v_max_f32_e32 v49, v49, v49
	ds_read_b128 v[74:77], v142 offset:28672
	ds_read_b128 v[162:165], v142 offset:30720
	v_mfma_f32_16x16x32_bf16 v[12:15], v[110:113], v[102:105], v[12:15]
	v_lshl_add_u64 v[100:101], v[100:101], 0, v[64:65]
	v_cvt_pk_bf16_f32 v56, v60, v61
	v_cvt_pk_bf16_f32 v57, v62, v63
	v_mfma_f32_16x16x32_bf16 v[8:11], v[114:117], v[102:105], v[8:11]
	v_max_f32_e32 v48, 0, v48
	v_max_f32_e32 v49, 0, v49
	v_max_f32_e32 v52, v52, v52
	v_mfma_f32_16x16x32_bf16 v[4:7], v[118:121], v[102:105], v[4:7]
	v_max_f32_e32 v53, v53, v53
	v_max_f32_e32 v51, v51, v51
	v_max_f32_e32 v52, 0, v52
	v_mfma_f32_16x16x32_bf16 v[0:3], v[122:125], v[102:105], v[0:3]
	v_max_f32_e32 v53, 0, v53
	v_max_f32_e32 v51, 0, v51
	v_pk_mul_f32 v[52:53], v[52:53], v[52:53]
	v_mfma_f32_16x16x32_bf16 v[20:23], v[126:129], v[102:105], v[20:23]
	v_mul_f32_e64 v102, v58, v58
	v_mul_f32_e64 v103, v59, v59
	v_cvt_pk_bf16_f32 v58, v106, v107
	v_cvt_pk_bf16_f32 v59, v102, v103
	s_waitcnt lgkmcnt(2)
	v_mfma_f32_16x16x32_bf16 v[40:43], v[158:161], v[130:133], v[40:43]
	global_store_dwordx4 v[100:101], v[56:59], off
	s_nop 1
	v_pk_mul_f32 v[56:57], v[48:49], v[48:49]
	v_max_f32_e32 v49, v50, v50
	v_max_f32_e32 v48, v54, v54
	v_max_f32_e32 v50, 0, v49
	v_max_f32_e32 v49, v55, v55
	v_mfma_f32_16x16x32_bf16 v[44:47], v[154:157], v[130:133], v[44:47]
	v_max_f32_e32 v48, 0, v48
	v_max_f32_e32 v49, 0, v49
	v_pk_mul_f32 v[54:55], v[48:49], v[48:49]
	v_pk_mul_f32 v[58:59], v[50:51], v[50:51]
	v_max_f32_e32 v40, v40, v40
	v_max_f32_e32 v41, v41, v41
	s_waitcnt lgkmcnt(0)
	v_mfma_f32_16x16x32_bf16 v[32:35], v[162:165], v[130:133], v[32:35]
	v_cvt_pk_bf16_f32 v48, v52, v53
	v_cvt_pk_bf16_f32 v49, v54, v55
	v_cvt_pk_bf16_f32 v50, v56, v57
	v_cvt_pk_bf16_f32 v51, v58, v59
	v_max_f32_e32 v40, 0, v40
	v_max_f32_e32 v41, 0, v41
	global_store_dwordx4 v[100:101], v[48:51], off offset:64
	v_max_f32_e32 v44, v44, v44
	v_max_f32_e32 v45, v45, v45
	v_pk_mul_f32 v[48:49], v[40:41], v[40:41]
	v_max_f32_e32 v41, v42, v42
	v_max_f32_e32 v40, v46, v46
	v_max_f32_e32 v42, 0, v41
	v_max_f32_e32 v41, v47, v47
	v_max_f32_e32 v43, v43, v43
	v_mfma_f32_16x16x32_bf16 v[36:39], v[74:77], v[130:133], v[36:39]
	v_max_f32_e32 v44, 0, v44
	v_max_f32_e32 v45, 0, v45
	v_max_f32_e32 v40, 0, v40
	v_max_f32_e32 v41, 0, v41
	v_max_f32_e32 v43, 0, v43
	v_pk_mul_f32 v[44:45], v[44:45], v[44:45]
	v_pk_mul_f32 v[46:47], v[40:41], v[40:41]
	v_pk_mul_f32 v[50:51], v[42:43], v[42:43]
	v_max_f32_e32 v32, v32, v32
	v_max_f32_e32 v33, v33, v33
	v_mfma_f32_16x16x32_bf16 v[24:27], v[146:149], v[134:137], v[24:27]
	v_cvt_pk_bf16_f32 v40, v44, v45
	v_cvt_pk_bf16_f32 v41, v46, v47
	v_cvt_pk_bf16_f32 v42, v48, v49
	v_cvt_pk_bf16_f32 v43, v50, v51
	v_max_f32_e32 v32, 0, v32
	v_max_f32_e32 v33, 0, v33
	global_store_dwordx4 v[100:101], v[40:43], off offset:128
	v_max_f32_e32 v36, v36, v36
	v_max_f32_e32 v37, v37, v37
	v_pk_mul_f32 v[40:41], v[32:33], v[32:33]
	v_max_f32_e32 v33, v34, v34
	v_max_f32_e32 v32, v38, v38
	v_max_f32_e32 v34, 0, v33
	v_max_f32_e32 v33, v39, v39
	v_max_f32_e32 v35, v35, v35
	v_mfma_f32_16x16x32_bf16 v[28:31], v[138:141], v[134:137], v[28:31]
	v_max_f32_e32 v36, 0, v36
	v_max_f32_e32 v37, 0, v37
	v_max_f32_e32 v32, 0, v32
	v_max_f32_e32 v33, 0, v33
	v_max_f32_e32 v35, 0, v35
	v_pk_mul_f32 v[36:37], v[36:37], v[36:37]
	v_pk_mul_f32 v[38:39], v[32:33], v[32:33]
	v_pk_mul_f32 v[42:43], v[34:35], v[34:35]
	v_max_f32_e32 v24, v24, v24
	v_max_f32_e32 v25, v25, v25
	v_mfma_f32_16x16x32_bf16 v[12:15], v[150:153], v[134:137], v[12:15]
	v_cvt_pk_bf16_f32 v32, v36, v37
	v_cvt_pk_bf16_f32 v33, v38, v39
	v_cvt_pk_bf16_f32 v34, v40, v41
	v_cvt_pk_bf16_f32 v35, v42, v43
	v_max_f32_e32 v24, 0, v24
	v_max_f32_e32 v25, 0, v25
	global_store_dwordx4 v[100:101], v[32:35], off offset:192
	v_max_f32_e32 v28, v28, v28
	v_max_f32_e32 v29, v29, v29
	v_pk_mul_f32 v[34:35], v[24:25], v[24:25]
	v_max_f32_e32 v25, v26, v26
	v_add_u32_e32 v32, s36, v84
	v_max_f32_e32 v24, v30, v30
	v_max_f32_e32 v26, 0, v25
	v_max_f32_e32 v25, v31, v31
	v_max_f32_e32 v27, v27, v27
	v_mfma_f32_16x16x32_bf16 v[16:19], v[94:97], v[134:137], v[16:19]
	v_mad_i64_i32 v[32:33], s[34:35], v32, s30, v[98:99]
	v_max_f32_e32 v28, 0, v28
	v_max_f32_e32 v29, 0, v29
	v_max_f32_e32 v24, 0, v24
	v_max_f32_e32 v25, 0, v25
	v_max_f32_e32 v27, 0, v27
	v_lshl_add_u64 v[32:33], v[32:33], 0, s[26:27]
	v_pk_mul_f32 v[28:29], v[28:29], v[28:29]
	v_pk_mul_f32 v[30:31], v[24:25], v[24:25]
	v_pk_mul_f32 v[36:37], v[26:27], v[26:27]
	v_max_f32_e32 v12, v12, v12
	v_max_f32_e32 v13, v13, v13
	v_mfma_f32_16x16x32_bf16 v[4:7], v[158:161], v[134:137], v[4:7]
	v_lshl_add_u64 v[32:33], v[32:33], 0, v[64:65]
	v_cvt_pk_bf16_f32 v24, v28, v29
	v_cvt_pk_bf16_f32 v25, v30, v31
	v_cvt_pk_bf16_f32 v26, v34, v35
	v_cvt_pk_bf16_f32 v27, v36, v37
	v_max_f32_e32 v12, 0, v12
	v_max_f32_e32 v13, 0, v13
	global_store_dwordx4 v[32:33], v[24:27], off
	v_max_f32_e32 v16, v16, v16
	v_max_f32_e32 v17, v17, v17
	v_pk_mul_f32 v[24:25], v[12:13], v[12:13]
	v_max_f32_e32 v13, v14, v14
	v_max_f32_e32 v12, v18, v18
	v_max_f32_e32 v14, 0, v13
	v_max_f32_e32 v13, v19, v19
	v_max_f32_e32 v15, v15, v15
	v_mfma_f32_16x16x32_bf16 v[8:11], v[154:157], v[134:137], v[8:11]
	v_max_f32_e32 v16, 0, v16
	v_max_f32_e32 v17, 0, v17
	v_max_f32_e32 v12, 0, v12
	v_max_f32_e32 v13, 0, v13
	v_max_f32_e32 v15, 0, v15
	v_pk_mul_f32 v[16:17], v[16:17], v[16:17]
	v_pk_mul_f32 v[18:19], v[12:13], v[12:13]
	v_pk_mul_f32 v[26:27], v[14:15], v[14:15]
	v_max_f32_e32 v4, v4, v4
	v_max_f32_e32 v5, v5, v5
	v_cvt_pk_bf16_f32 v12, v16, v17
	v_cvt_pk_bf16_f32 v13, v18, v19
	v_cvt_pk_bf16_f32 v14, v24, v25
	v_cvt_pk_bf16_f32 v15, v26, v27
	v_max_f32_e32 v4, 0, v4
	v_max_f32_e32 v5, 0, v5
	global_store_dwordx4 v[32:33], v[12:15], off offset:64
	v_mfma_f32_16x16x32_bf16 v[0:3], v[74:77], v[134:137], v[0:3]
	v_max_f32_e32 v8, v8, v8
	v_pk_mul_f32 v[12:13], v[4:5], v[4:5]
	v_max_f32_e32 v5, v6, v6
	v_mfma_f32_16x16x32_bf16 v[20:23], v[162:165], v[134:137], v[20:23]
	v_max_f32_e32 v9, v9, v9
	v_max_f32_e32 v4, v10, v10
	v_max_f32_e32 v6, 0, v5
	v_max_f32_e32 v5, v11, v11
	v_max_f32_e32 v7, v7, v7
	v_max_f32_e32 v8, 0, v8
	v_max_f32_e32 v9, 0, v9
	v_max_f32_e32 v4, 0, v4
	v_max_f32_e32 v5, 0, v5
	v_max_f32_e32 v7, 0, v7
	v_pk_mul_f32 v[8:9], v[8:9], v[8:9]
	v_pk_mul_f32 v[10:11], v[4:5], v[4:5]
	v_pk_mul_f32 v[14:15], v[6:7], v[6:7]
	v_cvt_pk_bf16_f32 v4, v8, v9
	v_cvt_pk_bf16_f32 v5, v10, v11
	v_cvt_pk_bf16_f32 v6, v12, v13
	v_cvt_pk_bf16_f32 v7, v14, v15
	global_store_dwordx4 v[32:33], v[4:7], off offset:128
	v_max_f32_e32 v0, v0, v0
	v_max_f32_e32 v1, v1, v1
	v_max_f32_e32 v4, v20, v20
	v_max_f32_e32 v5, v21, v21
	v_max_f32_e32 v2, v2, v2
	v_max_f32_e32 v6, v22, v22
	v_max_f32_e32 v3, v3, v3
	v_max_f32_e32 v7, v23, v23
	v_max_f32_e32 v0, 0, v0
	v_max_f32_e32 v4, 0, v4
	v_max_f32_e32 v1, 0, v1
	v_max_f32_e32 v5, 0, v5
	v_max_f32_e32 v2, 0, v2
	v_max_f32_e32 v6, 0, v6
	v_max_f32_e32 v3, 0, v3
	v_max_f32_e32 v7, 0, v7
	v_pk_mul_f32 v[0:1], v[0:1], v[0:1]
	v_pk_mul_f32 v[4:5], v[4:5], v[4:5]
	v_pk_mul_f32 v[2:3], v[2:3], v[2:3]
	v_pk_mul_f32 v[6:7], v[6:7], v[6:7]
	v_cvt_pk_bf16_f32 v0, v0, v1
	v_cvt_pk_bf16_f32 v1, v2, v3
	v_cvt_pk_bf16_f32 v2, v4, v5
	v_cvt_pk_bf16_f32 v3, v6, v7
	global_store_dwordx4 v[32:33], v[0:3], off offset:192
	s_cbranch_scc0 .LBB0_1005

.LBB0_1070:
	s_ashr_i32 s34, s41, 3
	s_add_i32 s34, s43, s34
	s_ashr_i32 s35, s34, 31
	s_lshr_b32 s35, s35, 26
	s_add_i32 s35, s34, s35
	s_ashr_i32 s42, s35, 6
	s_and_b32 s35, s35, 0xffc0
	s_sub_i32 s34, s34, s35
	s_bfe_i32 s35, s34, 0x80000
	s_bfe_u32 s35, s35, 0x3000c
	s_add_i32 s35, s34, s35
	s_bfe_i32 s41, s35, 0x80000
	s_and_b32 s35, s35, 0xf8
	s_sub_i32 s34, s34, s35
	s_lshl_b32 s42, s42, 3
	s_sext_i32_i8 s34, s34
	s_add_i32 s34, s42, s34
	s_ashr_i32 s35, s34, 31
	s_lshr_b32 s35, s35, 26
	s_add_i32 s35, s34, s35
	s_sext_i32_i16 s41, s41
	s_ashr_i32 s42, s35, 6
	s_andn2_b32 s35, s35, 63
	s_ashr_i32 s41, s41, 3
	s_mulk_i32 s42, 0x42
	s_sub_i32 s34, s34, s35
	s_add_i32 s42, s34, s42
	s_mul_i32 s34, s41, 0x82000
	s_add_i32 s42, s42, 2
	s_ashr_i32 s35, s34, 31
	v_readfirstlane_b32 s43, v94
	v_mad_i64_i32 v[0:1], s[44:45], s42, v93, v[64:65]
	s_lshl_b64 s[34:35], s[34:35], 1
	s_mov_b32 m0, s43
	v_readfirstlane_b32 s43, v95
	v_lshl_add_u64 v[2:3], v[66:67], 0, s[34:35]
	s_waitcnt vmcnt(63) expcnt(7) lgkmcnt(15)
	s_barrier
	global_load_lds_dwordx4 v[0:1], off
	s_mov_b32 m0, s43
	v_readfirstlane_b32 s43, v96
	global_load_lds_dwordx4 v[2:3], off
	v_lshl_add_u64 v[4:5], v[0:1], 0, s[8:9]
	s_mov_b32 m0, s43
	v_readfirstlane_b32 s43, v97
	global_load_lds_dwordx4 v[4:5], off
	v_lshl_add_u64 v[4:5], v[2:3], 0, s[8:9]
	s_mov_b32 m0, s43
	v_readfirstlane_b32 s43, v98
	global_load_lds_dwordx4 v[4:5], off
	v_lshl_add_u64 v[4:5], v[0:1], 0, s[10:11]
	s_mov_b32 m0, s43
	v_readfirstlane_b32 s43, v99
	global_load_lds_dwordx4 v[4:5], off
	v_lshl_add_u64 v[4:5], v[2:3], 0, s[10:11]
	s_mov_b32 m0, s43
	v_readfirstlane_b32 s43, v100
	global_load_lds_dwordx4 v[4:5], off
	v_lshl_add_u64 v[0:1], v[0:1], 0, s[12:13]
	s_mov_b32 m0, s43
	v_readfirstlane_b32 s43, v101
	global_load_lds_dwordx4 v[0:1], off
	v_lshl_add_u64 v[0:1], v[2:3], 0, s[12:13]
	s_mov_b32 m0, s43
	v_mov_b32_e32 v36, 0
	global_load_lds_dwordx4 v[0:1], off
	v_mad_i64_i32 v[72:73], s[44:45], s42, v93, v[68:69]
	v_lshl_add_u64 v[74:75], v[70:71], 0, s[34:35]
	s_mov_b64 s[34:35], 0
	s_mov_b32 s43, 0
	v_mov_b32_e32 v37, v36
	v_mov_b32_e32 v38, v36
	v_mov_b32_e32 v39, v36
	v_mov_b32_e32 v0, v36
	v_mov_b32_e32 v1, v36
	v_mov_b32_e32 v2, v36
	v_mov_b32_e32 v3, v36
	v_mov_b32_e32 v4, v36
	v_mov_b32_e32 v5, v36
	v_mov_b32_e32 v6, v36
	v_mov_b32_e32 v7, v36
	v_mov_b32_e32 v8, v36
	v_mov_b32_e32 v9, v36
	v_mov_b32_e32 v10, v36
	v_mov_b32_e32 v11, v36
	v_mov_b32_e32 v12, v36
	v_mov_b32_e32 v13, v36
	v_mov_b32_e32 v14, v36
	v_mov_b32_e32 v15, v36
	v_mov_b32_e32 v16, v36
	v_mov_b32_e32 v17, v36
	v_mov_b32_e32 v18, v36
	v_mov_b32_e32 v19, v36
	v_mov_b32_e32 v20, v36
	v_mov_b32_e32 v21, v36
	v_mov_b32_e32 v22, v36
	v_mov_b32_e32 v23, v36
	v_mov_b32_e32 v24, v36
	v_mov_b32_e32 v25, v36
	v_mov_b32_e32 v26, v36
	v_mov_b32_e32 v27, v36
	v_mov_b32_e32 v28, v36
	v_mov_b32_e32 v29, v36
	v_mov_b32_e32 v30, v36
	v_mov_b32_e32 v31, v36
	v_mov_b32_e32 v32, v36
	v_mov_b32_e32 v33, v36
	v_mov_b32_e32 v34, v36
	v_mov_b32_e32 v35, v36
	v_mov_b32_e32 v40, v36
	v_mov_b32_e32 v41, v36
	v_mov_b32_e32 v42, v36
	v_mov_b32_e32 v43, v36
	v_mov_b32_e32 v44, v36
	v_mov_b32_e32 v45, v36
	v_mov_b32_e32 v46, v36
	v_mov_b32_e32 v47, v36
	v_mov_b32_e32 v48, v36
	v_mov_b32_e32 v49, v36
	v_mov_b32_e32 v50, v36
	v_mov_b32_e32 v51, v36
	v_mov_b32_e32 v52, v36
	v_mov_b32_e32 v53, v36
	v_mov_b32_e32 v54, v36
	v_mov_b32_e32 v55, v36
	v_mov_b32_e32 v56, v36
	v_mov_b32_e32 v57, v36
	v_mov_b32_e32 v58, v36
	v_mov_b32_e32 v59, v36
	v_mov_b32_e32 v60, v36
	v_mov_b32_e32 v61, v36
	v_mov_b32_e32 v62, v36
	v_mov_b32_e32 v63, v36
	v_readfirstlane_b32 s96, v72
	v_readfirstlane_b32 s97, v73
	v_readfirstlane_b32 s88, v74
	v_readfirstlane_b32 s89, v75
	v_readfirstlane_b32 s87, v88
	s_nop 1
	v_subrev_u32_e32 v244, s96, v72
	v_subrev_u32_e32 v245, s88, v74
	v_add_u32_e32 v246, 0x41000, v244
	v_add_u32_e32 v247, 0x41000, v245
	v_add_u32_e32 v248, 0x82000, v244
	v_add_u32_e32 v249, 0x82000, v245
	v_add_u32_e32 v250, 0xc3000, v244
	v_add_u32_e32 v251, 0xc3000, v245
	s_add_u32 s96, s96, 0x4510080
	s_addc_u32 s97, s97, 0
	s_add_u32 s88, s88, 0x1910080
	s_addc_u32 s89, s89, 0
	v_add_u32_e32 v169, v84, v89
	v_add_u32_e32 v210, v89, v90
	v_add_u32_e32 v211, v84, v91
	v_add_u32_e32 v212, v90, v91
.LBB0_1071:
	s_add_i32 s45, s43, 0x8000
	s_and_b32 s44, s45, 0x8000
	s_add_i32 s44, s44, 0
	s_add_u32 s86, s44, s87
	s_mov_b32 m0, s86
	s_waitcnt vmcnt(0) lgkmcnt(0)
	s_barrier
	global_load_lds_dwordx4 v244, s[96:97]
	s_add_u32 m0, s86, 0x4000
	s_nop 0
	global_load_lds_dwordx4 v245, s[88:89]
	s_add_u32 m0, s86, 0x1000
	s_nop 0
	global_load_lds_dwordx4 v246, s[96:97]
	s_add_u32 m0, s86, 0x5000
	s_nop 0
	global_load_lds_dwordx4 v247, s[88:89]
	s_add_u32 m0, s86, 0x2000
	s_nop 0
	global_load_lds_dwordx4 v248, s[96:97]
	s_add_u32 m0, s86, 0x6000
	s_nop 0
	global_load_lds_dwordx4 v249, s[88:89]
	s_add_u32 m0, s86, 0x3000
	s_nop 0
	global_load_lds_dwordx4 v250, s[96:97]
	s_add_u32 m0, s86, 0x7000
	s_nop 0
	global_load_lds_dwordx4 v251, s[88:89]
	s_add_u32 s96, s96, 0x80
	s_addc_u32 s97, s97, 0
	s_add_u32 s88, s88, 0x80
	s_addc_u32 s89, s89, 0
	s_and_b32 s43, s43, 0x8000
	s_add_i32 s43, s43, 0
	ds_read_b128 v[106:109], v210
	ds_read_b128 v[76:79], v169 offset:16384
	ds_read_b128 v[102:105], v169 offset:18432
	ds_read_b128 v[110:113], v210 offset:2048
	ds_read_b128 v[114:117], v169 offset:20480
	ds_read_b128 v[118:121], v169 offset:22528
	ds_read_b128 v[122:125], v169 offset:24576
	ds_read_b128 v[126:129], v169 offset:26624
	ds_read_b128 v[130:133], v169 offset:28672
	ds_read_b128 v[134:137], v169 offset:30720
	ds_read_b128 v[178:181], v212
	ds_read_b128 v[170:173], v211 offset:16384
	ds_read_b128 v[174:177], v211 offset:18432
	ds_read_b128 v[182:185], v212 offset:2048
	ds_read_b128 v[186:189], v211 offset:20480
	ds_read_b128 v[190:193], v211 offset:22528
	ds_read_b128 v[194:197], v211 offset:24576
	ds_read_b128 v[198:201], v211 offset:26624
	ds_read_b128 v[202:205], v211 offset:28672
	ds_read_b128 v[206:209], v211 offset:30720
	s_add_u32 s34, s34, 0x80
	s_addc_u32 s35, s35, 0
	s_cmpk_eq_i32 s34, 0x1f80
	s_mov_b32 s43, s45
	s_waitcnt lgkmcnt(15)
	v_mfma_f32_16x16x32_bf16 v[60:63], v[76:79], v[106:109], v[60:63]
	v_mfma_f32_16x16x32_bf16 v[56:59], v[102:105], v[106:109], v[56:59]
	v_mfma_f32_16x16x32_bf16 v[24:27], v[76:79], v[110:113], v[24:27]
	v_mfma_f32_16x16x32_bf16 v[20:23], v[102:105], v[110:113], v[20:23]
	v_mfma_f32_16x16x32_bf16 v[52:55], v[114:117], v[106:109], v[52:55]
	v_mfma_f32_16x16x32_bf16 v[16:19], v[114:117], v[110:113], v[16:19]
	s_waitcnt lgkmcnt(14)
	v_mfma_f32_16x16x32_bf16 v[48:51], v[118:121], v[106:109], v[48:51]
	v_mfma_f32_16x16x32_bf16 v[12:15], v[118:121], v[110:113], v[12:15]
	s_waitcnt lgkmcnt(13)
	v_mfma_f32_16x16x32_bf16 v[44:47], v[122:125], v[106:109], v[44:47]
	v_mfma_f32_16x16x32_bf16 v[8:11], v[122:125], v[110:113], v[8:11]
	s_waitcnt lgkmcnt(12)
	v_mfma_f32_16x16x32_bf16 v[40:43], v[126:129], v[106:109], v[40:43]
	v_mfma_f32_16x16x32_bf16 v[4:7], v[126:129], v[110:113], v[4:7]
	s_waitcnt lgkmcnt(11)
	v_mfma_f32_16x16x32_bf16 v[32:35], v[130:133], v[106:109], v[32:35]
	v_mfma_f32_16x16x32_bf16 v[0:3], v[130:133], v[110:113], v[0:3]
	s_waitcnt lgkmcnt(10)
	v_mfma_f32_16x16x32_bf16 v[28:31], v[134:137], v[106:109], v[28:31]
	v_mfma_f32_16x16x32_bf16 v[36:39], v[134:137], v[110:113], v[36:39]
	s_waitcnt lgkmcnt(8)
	v_mfma_f32_16x16x32_bf16 v[60:63], v[170:173], v[178:181], v[60:63]
	s_waitcnt lgkmcnt(7)
	v_mfma_f32_16x16x32_bf16 v[56:59], v[174:177], v[178:181], v[56:59]
	s_waitcnt lgkmcnt(6)
	v_mfma_f32_16x16x32_bf16 v[24:27], v[170:173], v[182:185], v[24:27]
	v_mfma_f32_16x16x32_bf16 v[20:23], v[174:177], v[182:185], v[20:23]
	s_waitcnt lgkmcnt(5)
	v_mfma_f32_16x16x32_bf16 v[52:55], v[186:189], v[178:181], v[52:55]
	v_mfma_f32_16x16x32_bf16 v[16:19], v[186:189], v[182:185], v[16:19]
	s_waitcnt lgkmcnt(4)
	v_mfma_f32_16x16x32_bf16 v[48:51], v[190:193], v[178:181], v[48:51]
	v_mfma_f32_16x16x32_bf16 v[12:15], v[190:193], v[182:185], v[12:15]
	s_waitcnt lgkmcnt(3)
	v_mfma_f32_16x16x32_bf16 v[44:47], v[194:197], v[178:181], v[44:47]
	v_mfma_f32_16x16x32_bf16 v[8:11], v[194:197], v[182:185], v[8:11]
	s_waitcnt lgkmcnt(2)
	v_mfma_f32_16x16x32_bf16 v[40:43], v[198:201], v[178:181], v[40:43]
	v_mfma_f32_16x16x32_bf16 v[4:7], v[198:201], v[182:185], v[4:7]
	s_waitcnt lgkmcnt(1)
	v_mfma_f32_16x16x32_bf16 v[32:35], v[202:205], v[178:181], v[32:35]
	v_mfma_f32_16x16x32_bf16 v[0:3], v[202:205], v[182:185], v[0:3]
	s_waitcnt lgkmcnt(0)
	v_mfma_f32_16x16x32_bf16 v[28:31], v[206:209], v[178:181], v[28:31]
	v_mfma_f32_16x16x32_bf16 v[36:39], v[206:209], v[182:185], v[36:39]
	s_cbranch_scc1 .Lu2x_1071
	s_add_i32 s45, s43, 0x8000
	s_and_b32 s44, s45, 0x8000
	s_add_i32 s44, s44, 0
	s_add_u32 s86, s44, s87
	s_mov_b32 m0, s86
	s_waitcnt vmcnt(0) lgkmcnt(0)
	s_barrier
	global_load_lds_dwordx4 v244, s[96:97]
	s_add_u32 m0, s86, 0x4000
	s_nop 0
	global_load_lds_dwordx4 v245, s[88:89]
	s_add_u32 m0, s86, 0x1000
	s_nop 0
	global_load_lds_dwordx4 v246, s[96:97]
	s_add_u32 m0, s86, 0x5000
	s_nop 0
	global_load_lds_dwordx4 v247, s[88:89]
	s_add_u32 m0, s86, 0x2000
	s_nop 0
	global_load_lds_dwordx4 v248, s[96:97]
	s_add_u32 m0, s86, 0x6000
	s_nop 0
	global_load_lds_dwordx4 v249, s[88:89]
	s_add_u32 m0, s86, 0x3000
	s_nop 0
	global_load_lds_dwordx4 v250, s[96:97]
	s_add_u32 m0, s86, 0x7000
	s_nop 0
	global_load_lds_dwordx4 v251, s[88:89]
	s_add_u32 s96, s96, 0x80
	s_addc_u32 s97, s97, 0
	s_add_u32 s88, s88, 0x80
	s_addc_u32 s89, s89, 0
	s_and_b32 s43, s43, 0x8000
	s_add_i32 s43, s43, 0
	ds_read_b128 v[106:109], v210 offset:32768
	ds_read_b128 v[76:79], v169 offset:49152
	ds_read_b128 v[102:105], v169 offset:51200
	ds_read_b128 v[110:113], v210 offset:34816
	ds_read_b128 v[114:117], v169 offset:53248
	ds_read_b128 v[118:121], v169 offset:55296
	ds_read_b128 v[122:125], v169 offset:57344
	ds_read_b128 v[126:129], v169 offset:59392
	ds_read_b128 v[130:133], v169 offset:61440
	ds_read_b128 v[134:137], v169 offset:63488
	ds_read_b128 v[178:181], v212 offset:32768
	ds_read_b128 v[170:173], v211 offset:49152
	ds_read_b128 v[174:177], v211 offset:51200
	ds_read_b128 v[182:185], v212 offset:34816
	ds_read_b128 v[186:189], v211 offset:53248
	ds_read_b128 v[190:193], v211 offset:55296
	ds_read_b128 v[194:197], v211 offset:57344
	ds_read_b128 v[198:201], v211 offset:59392
	ds_read_b128 v[202:205], v211 offset:61440
	ds_read_b128 v[206:209], v211 offset:63488
	s_add_u32 s34, s34, 0x80
	s_addc_u32 s35, s35, 0
	s_cmpk_eq_i32 s34, 0x1f80
	s_mov_b32 s43, s45
	s_waitcnt lgkmcnt(15)
	v_mfma_f32_16x16x32_bf16 v[60:63], v[76:79], v[106:109], v[60:63]
	v_mfma_f32_16x16x32_bf16 v[56:59], v[102:105], v[106:109], v[56:59]
	v_mfma_f32_16x16x32_bf16 v[24:27], v[76:79], v[110:113], v[24:27]
	v_mfma_f32_16x16x32_bf16 v[20:23], v[102:105], v[110:113], v[20:23]
	v_mfma_f32_16x16x32_bf16 v[52:55], v[114:117], v[106:109], v[52:55]
	v_mfma_f32_16x16x32_bf16 v[16:19], v[114:117], v[110:113], v[16:19]
	s_waitcnt lgkmcnt(14)
	v_mfma_f32_16x16x32_bf16 v[48:51], v[118:121], v[106:109], v[48:51]
	v_mfma_f32_16x16x32_bf16 v[12:15], v[118:121], v[110:113], v[12:15]
	s_waitcnt lgkmcnt(13)
	v_mfma_f32_16x16x32_bf16 v[44:47], v[122:125], v[106:109], v[44:47]
	v_mfma_f32_16x16x32_bf16 v[8:11], v[122:125], v[110:113], v[8:11]
	s_waitcnt lgkmcnt(12)
	v_mfma_f32_16x16x32_bf16 v[40:43], v[126:129], v[106:109], v[40:43]
	v_mfma_f32_16x16x32_bf16 v[4:7], v[126:129], v[110:113], v[4:7]
	s_waitcnt lgkmcnt(11)
	v_mfma_f32_16x16x32_bf16 v[32:35], v[130:133], v[106:109], v[32:35]
	v_mfma_f32_16x16x32_bf16 v[0:3], v[130:133], v[110:113], v[0:3]
	s_waitcnt lgkmcnt(10)
	v_mfma_f32_16x16x32_bf16 v[28:31], v[134:137], v[106:109], v[28:31]
	v_mfma_f32_16x16x32_bf16 v[36:39], v[134:137], v[110:113], v[36:39]
	s_waitcnt lgkmcnt(8)
	v_mfma_f32_16x16x32_bf16 v[60:63], v[170:173], v[178:181], v[60:63]
	s_waitcnt lgkmcnt(7)
	v_mfma_f32_16x16x32_bf16 v[56:59], v[174:177], v[178:181], v[56:59]
	s_waitcnt lgkmcnt(6)
	v_mfma_f32_16x16x32_bf16 v[24:27], v[170:173], v[182:185], v[24:27]
	v_mfma_f32_16x16x32_bf16 v[20:23], v[174:177], v[182:185], v[20:23]
	s_waitcnt lgkmcnt(5)
	v_mfma_f32_16x16x32_bf16 v[52:55], v[186:189], v[178:181], v[52:55]
	v_mfma_f32_16x16x32_bf16 v[16:19], v[186:189], v[182:185], v[16:19]
	s_waitcnt lgkmcnt(4)
	v_mfma_f32_16x16x32_bf16 v[48:51], v[190:193], v[178:181], v[48:51]
	v_mfma_f32_16x16x32_bf16 v[12:15], v[190:193], v[182:185], v[12:15]
	s_waitcnt lgkmcnt(3)
	v_mfma_f32_16x16x32_bf16 v[44:47], v[194:197], v[178:181], v[44:47]
	v_mfma_f32_16x16x32_bf16 v[8:11], v[194:197], v[182:185], v[8:11]
	s_waitcnt lgkmcnt(2)
	v_mfma_f32_16x16x32_bf16 v[40:43], v[198:201], v[178:181], v[40:43]
	v_mfma_f32_16x16x32_bf16 v[4:7], v[198:201], v[182:185], v[4:7]
	s_waitcnt lgkmcnt(1)
	v_mfma_f32_16x16x32_bf16 v[32:35], v[202:205], v[178:181], v[32:35]
	v_mfma_f32_16x16x32_bf16 v[0:3], v[202:205], v[182:185], v[0:3]
	s_waitcnt lgkmcnt(0)
	v_mfma_f32_16x16x32_bf16 v[28:31], v[206:209], v[178:181], v[28:31]
	v_mfma_f32_16x16x32_bf16 v[36:39], v[206:209], v[182:185], v[36:39]
	s_cbranch_scc0 .LBB0_1071
.Lu2x_1071:
	v_add_u32_e32 v80, s44, v84
	v_add_u32_e32 v81, v80, v89
	v_add3_u32 v106, s44, v89, v90
	s_waitcnt vmcnt(0)
	s_barrier
	ds_read_b128 v[72:75], v81 offset:16384
	ds_read_b128 v[76:79], v81 offset:18432
	ds_read_b128 v[102:105], v106
	ds_read_b128 v[106:109], v106 offset:2048
	ds_read_b128 v[110:113], v81 offset:20480
	ds_read_b128 v[114:117], v81 offset:22528
	ds_read_b128 v[118:121], v81 offset:24576
	ds_read_b128 v[122:125], v81 offset:26624
	ds_read_b128 v[126:129], v81 offset:28672
	ds_read_b128 v[130:133], v81 offset:30720
	v_add_u32_e32 v80, v80, v91
	s_waitcnt lgkmcnt(7)
	v_mfma_f32_16x16x32_bf16 v[60:63], v[72:75], v[102:105], v[60:63]
	s_lshl_b32 s42, s42, 7
	v_mfma_f32_16x16x32_bf16 v[56:59], v[76:79], v[102:105], v[56:59]
	s_waitcnt lgkmcnt(4)
	v_mfma_f32_16x16x32_bf16 v[48:51], v[114:117], v[102:105], v[48:51]
	s_waitcnt lgkmcnt(3)
	v_mfma_f32_16x16x32_bf16 v[44:47], v[118:121], v[102:105], v[44:47]
	s_waitcnt lgkmcnt(2)
	v_mfma_f32_16x16x32_bf16 v[40:43], v[122:125], v[102:105], v[40:43]
	s_waitcnt lgkmcnt(1)
	v_mfma_f32_16x16x32_bf16 v[32:35], v[126:129], v[102:105], v[32:35]
	s_waitcnt lgkmcnt(0)
	v_mfma_f32_16x16x32_bf16 v[28:31], v[130:133], v[102:105], v[28:31]
	v_mfma_f32_16x16x32_bf16 v[24:27], v[72:75], v[106:109], v[24:27]
	ds_read_b128 v[72:75], v80 offset:16384
	v_mfma_f32_16x16x32_bf16 v[52:55], v[110:113], v[102:105], v[52:55]
	v_mfma_f32_16x16x32_bf16 v[20:23], v[76:79], v[106:109], v[20:23]
	v_mfma_f32_16x16x32_bf16 v[16:19], v[110:113], v[106:109], v[16:19]
	v_mfma_f32_16x16x32_bf16 v[12:15], v[114:117], v[106:109], v[12:15]
	v_mfma_f32_16x16x32_bf16 v[8:11], v[118:121], v[106:109], v[8:11]
	v_mfma_f32_16x16x32_bf16 v[4:7], v[122:125], v[106:109], v[4:7]
	v_mfma_f32_16x16x32_bf16 v[0:3], v[126:129], v[106:109], v[0:3]
	v_mfma_f32_16x16x32_bf16 v[102:105], v[130:133], v[106:109], v[36:39]
	s_nop 2
	v_add3_u32 v36, s44, v91, v90
	ds_read_b128 v[76:79], v80 offset:18432
	ds_read_b128 v[106:109], v36
	ds_read_b128 v[110:113], v36 offset:2048
	ds_read_b128 v[130:133], v80 offset:28672
	ds_read_b128 v[134:137], v80 offset:30720
	ds_read_b128 v[114:117], v80 offset:20480
	ds_read_b128 v[118:121], v80 offset:22528
	ds_read_b128 v[122:125], v80 offset:24576
	ds_read_b128 v[126:129], v80 offset:26624
	s_waitcnt lgkmcnt(7)
	v_mfma_f32_16x16x32_bf16 v[60:63], v[72:75], v[106:109], v[60:63]
	s_waitcnt lgkmcnt(5)
	v_mfma_f32_16x16x32_bf16 v[36:39], v[130:133], v[106:109], v[32:35]
	s_waitcnt lgkmcnt(4)
	v_mfma_f32_16x16x32_bf16 v[32:35], v[134:137], v[106:109], v[28:31]
	v_mfma_f32_16x16x32_bf16 v[28:31], v[72:75], v[110:113], v[24:27]
	v_add_u32_e32 v72, s42, v85
	v_mul_hi_i32 v73, v72, s36
	v_mfma_f32_16x16x32_bf16 v[24:27], v[76:79], v[110:113], v[20:23]
	s_waitcnt lgkmcnt(3)
	v_mfma_f32_16x16x32_bf16 v[20:23], v[114:117], v[110:113], v[16:19]
	s_waitcnt lgkmcnt(2)
	v_mfma_f32_16x16x32_bf16 v[16:19], v[118:121], v[110:113], v[12:15]
	s_waitcnt lgkmcnt(1)
	v_mfma_f32_16x16x32_bf16 v[12:15], v[122:125], v[110:113], v[8:11]
	s_waitcnt lgkmcnt(0)
	v_mfma_f32_16x16x32_bf16 v[8:11], v[126:129], v[110:113], v[4:7]
	s_nop 2
	v_lshrrev_b32_e32 v4, 31, v73
	v_ashrrev_i32_e32 v5, 11, v73
	v_mfma_f32_16x16x32_bf16 v[56:59], v[76:79], v[106:109], v[56:59]
	v_add_u32_e32 v73, v5, v4
	v_mad_i32_i24 v78, v73, s37, v72
	v_lshlrev_b32_e32 v75, 13, v73
	v_mfma_f32_16x16x32_bf16 v[52:55], v[114:117], v[106:109], v[52:55]
	v_cmp_lt_i32_e32 vcc, s38, v78
	v_add3_u32 v74, v75, v78, s39
	v_mfma_f32_16x16x32_bf16 v[48:51], v[118:121], v[106:109], v[48:51]
	v_mfma_f32_16x16x32_bf16 v[44:47], v[122:125], v[106:109], v[44:47]
	v_mfma_f32_16x16x32_bf16 v[40:43], v[126:129], v[106:109], v[40:43]
	v_mfma_f32_16x16x32_bf16 v[4:7], v[130:133], v[110:113], v[0:3]
	v_mfma_f32_16x16x32_bf16 v[0:3], v[134:137], v[110:113], v[102:105]
	s_and_saveexec_b64 s[34:35], vcc
	s_xor_b64 s[34:35], exec, s[34:35]
	v_add3_u32 v72, v75, v78, s39
	s_or_saveexec_b64 s[34:35], s[34:35]
	v_mov_b64_e32 v[76:77], s[92:93]
	v_lshl_add_u32 v75, v73, 8, v78
	s_xor_b64 exec, exec, s[34:35]
	v_lshl_add_u32 v72, v73, 8, v78
	v_mov_b64_e32 v[76:77], s[6:7]
	s_or_b64 exec, exec, s[34:35]
	s_and_saveexec_b64 s[34:35], vcc
	s_xor_b64 s[34:35], exec, s[34:35]
	s_cbranch_execz .LBB0_1078
	v_mul_hi_i32_i24_e32 v79, 0x6000, v73
	v_mul_i32_i24_e32 v78, 0x6000, v73
	s_or_saveexec_b64 s[34:35], s[34:35]
	v_mov_b64_e32 v[80:81], s[92:93]
	s_xor_b64 exec, exec, s[34:35]
	s_cbranch_execnz .LBB0_1079
	s_branch .LBB0_1080

.LBB0_1216:
	s_ashr_i32 s0, s52, 31
	s_lshr_b32 s0, s0, 29
	s_add_i32 s0, s52, s0
	s_ashr_i32 s1, s0, 3
	s_and_b32 s0, s0, -8
	s_sub_i32 s0, s52, s0
	s_cmp_lt_i32 s0, 0
	s_cselect_b32 s2, s47, 0x16b
	s_mul_i32 s0, s2, s0
	s_add_i32 s3, s0, s1
	s_mul_hi_i32 s0, s3, 0x2e8ba2e9
	s_lshr_b32 s1, s0, 31
	s_ashr_i32 s0, s0, 5
	s_add_i32 s0, s0, s1
	s_lshl_b32 s41, s0, 3
	s_mul_i32 s40, s0, 0xb0
	s_sub_i32 s0, 0x84, s41
	s_min_u32 s42, s0, 8
	s_sub_i32 s2, s3, s40
	v_cvt_f32_ubyte0_e32 v1, s42
	v_cvt_f32_i32_e32 v0, s2
	v_rcp_iflag_f32_e32 v2, v1
	s_ashr_i32 s0, s2, 30
	s_or_b32 s38, s0, 1
	s_waitcnt vmcnt(63) expcnt(7) lgkmcnt(15)
	v_mul_f32_e32 v2, v0, v2
	v_trunc_f32_e32 v2, v2
	v_fma_f32 v0, -v2, v1, v0
	v_cvt_i32_f32_e32 v2, v2
	v_cmp_ge_f32_e64 s[0:1], |v0|, v1
	s_and_b64 s[0:1], s[0:1], exec
	s_cselect_b32 s0, s38, 0
	v_readfirstlane_b32 s38, v2
	s_add_i32 s38, s38, s0
	s_mul_i32 s42, s38, s42
	s_sub_i32 s0, s2, s42
	s_sext_i32_i16 s0, s0
	s_sext_i32_i16 s39, s38
	s_add_i32 s2, s41, s0
	v_mad_i64_i32 v[0:1], s[0:1], s2, v93, v[66:67]
	v_mad_i64_i32 v[2:3], s[0:1], s39, v93, v[68:69]
	v_readfirstlane_b32 s0, v94
	s_mov_b32 m0, s0
	v_readfirstlane_b32 s0, v95
	s_barrier
	global_load_lds_dwordx4 v[0:1], off
	s_mov_b32 m0, s0
	v_readfirstlane_b32 s0, v96
	global_load_lds_dwordx4 v[2:3], off
	v_lshl_add_u64 v[4:5], v[0:1], 0, s[12:13]
	s_mov_b32 m0, s0
	v_readfirstlane_b32 s0, v97
	global_load_lds_dwordx4 v[4:5], off
	v_lshl_add_u64 v[4:5], v[2:3], 0, s[12:13]
	s_mov_b32 m0, s0
	v_readfirstlane_b32 s0, v98
	global_load_lds_dwordx4 v[4:5], off
	v_lshl_add_u64 v[4:5], v[0:1], 0, s[14:15]
	s_mov_b32 m0, s0
	v_readfirstlane_b32 s0, v99
	global_load_lds_dwordx4 v[4:5], off
	v_lshl_add_u64 v[4:5], v[2:3], 0, s[14:15]
	s_mov_b32 m0, s0
	v_readfirstlane_b32 s0, v100
	global_load_lds_dwordx4 v[4:5], off
	v_lshl_add_u64 v[0:1], v[0:1], 0, s[16:17]
	s_mov_b32 m0, s0
	v_readfirstlane_b32 s0, v101
	global_load_lds_dwordx4 v[0:1], off
	v_lshl_add_u64 v[0:1], v[2:3], 0, s[16:17]
	s_mov_b32 m0, s0
	s_sub_i32 s0, s3, s42
	global_load_lds_dwordx4 v[0:1], off
	s_sub_i32 s0, s0, s40
	s_sext_i32_i16 s0, s0
	s_add_i32 s41, s41, s0
	v_mad_i64_i32 v[82:83], s[0:1], s41, v93, v[78:79]
	v_mad_i64_i32 v[84:85], s[0:1], s39, v93, v[80:81]
	s_mov_b64 s[0:1], 0
	s_mov_b32 s3, 0
	v_mov_b32_e32 v40, 0
	v_mov_b32_e32 v41, v65
	v_mov_b32_e32 v42, v65
	v_mov_b32_e32 v43, v65
	v_mov_b32_e32 v0, 0
	v_mov_b32_e32 v1, v65
	v_mov_b32_e32 v2, v65
	v_mov_b32_e32 v3, v65
	v_mov_b32_e32 v4, 0
	v_mov_b32_e32 v5, v65
	v_mov_b32_e32 v6, v65
	v_mov_b32_e32 v7, v65
	v_mov_b32_e32 v8, 0
	v_mov_b32_e32 v9, v65
	v_mov_b32_e32 v10, v65
	v_mov_b32_e32 v11, v65
	v_mov_b32_e32 v12, 0
	v_mov_b32_e32 v13, v65
	v_mov_b32_e32 v14, v65
	v_mov_b32_e32 v15, v65
	v_mov_b32_e32 v16, 0
	v_mov_b32_e32 v17, v65
	v_mov_b32_e32 v18, v65
	v_mov_b32_e32 v19, v65
	v_mov_b32_e32 v20, 0
	v_mov_b32_e32 v21, v65
	v_mov_b32_e32 v22, v65
	v_mov_b32_e32 v23, v65
	v_mov_b32_e32 v24, 0
	v_mov_b32_e32 v25, v65
	v_mov_b32_e32 v26, v65
	v_mov_b32_e32 v27, v65
	v_mov_b32_e32 v28, 0
	v_mov_b32_e32 v29, v65
	v_mov_b32_e32 v30, v65
	v_mov_b32_e32 v31, v65
	v_mov_b32_e32 v32, 0
	v_mov_b32_e32 v33, v65
	v_mov_b32_e32 v34, v65
	v_mov_b32_e32 v35, v65
	v_mov_b32_e32 v36, 0
	v_mov_b32_e32 v37, v65
	v_mov_b32_e32 v38, v65
	v_mov_b32_e32 v39, v65
	v_mov_b32_e32 v44, 0
	v_mov_b32_e32 v45, v65
	v_mov_b32_e32 v46, v65
	v_mov_b32_e32 v47, v65
	v_mov_b32_e32 v48, 0
	v_mov_b32_e32 v49, v65
	v_mov_b32_e32 v50, v65
	v_mov_b32_e32 v51, v65
	v_mov_b32_e32 v52, 0
	v_mov_b32_e32 v53, v65
	v_mov_b32_e32 v54, v65
	v_mov_b32_e32 v55, v65
	v_mov_b32_e32 v56, 0
	v_mov_b32_e32 v57, v65
	v_mov_b32_e32 v58, v65
	v_mov_b32_e32 v59, v65
	v_mov_b32_e32 v60, 0
	v_mov_b32_e32 v61, v65
	v_mov_b32_e32 v62, v65
	v_mov_b32_e32 v63, v65
	v_readfirstlane_b32 s96, v82
	v_readfirstlane_b32 s97, v83
	v_readfirstlane_b32 s88, v84
	v_readfirstlane_b32 s89, v85
	v_readfirstlane_b32 s87, v86
	s_nop 1
	v_subrev_u32_e32 v244, s96, v82
	v_subrev_u32_e32 v245, s88, v84
	v_add_u32_e32 v246, 0x11000, v244
	v_add_u32_e32 v247, 0x11000, v245
	v_add_u32_e32 v248, 0x22000, v244
	v_add_u32_e32 v249, 0x22000, v245
	v_add_u32_e32 v250, 0x33000, v244
	v_add_u32_e32 v251, 0x33000, v245
	s_add_u32 s96, s96, 0x2200080
	s_addc_u32 s97, s97, 0
	s_add_u32 s88, s88, 0xd990080
	s_addc_u32 s89, s89, 0
	v_add_u32_e32 v145, v87, v88
	v_add_u32_e32 v186, v88, v89
	v_add_u32_e32 v187, v87, v90
	v_add_u32_e32 v188, v89, v90
.LBB0_1217:
	s_add_i32 s41, s3, 0x8000
	s_and_b32 s40, s41, 0x8000
	s_add_i32 s40, s40, 0
	s_add_u32 s86, s40, s87
	s_mov_b32 m0, s86
	s_waitcnt vmcnt(0) lgkmcnt(0)
	s_barrier
	global_load_lds_dwordx4 v244, s[96:97]
	s_add_u32 m0, s86, 0x4000
	s_nop 0
	global_load_lds_dwordx4 v245, s[88:89]
	s_add_u32 m0, s86, 0x1000
	s_nop 0
	global_load_lds_dwordx4 v246, s[96:97]
	s_add_u32 m0, s86, 0x5000
	s_nop 0
	global_load_lds_dwordx4 v247, s[88:89]
	s_add_u32 m0, s86, 0x2000
	s_nop 0
	global_load_lds_dwordx4 v248, s[96:97]
	s_add_u32 m0, s86, 0x6000
	s_nop 0
	global_load_lds_dwordx4 v249, s[88:89]
	s_add_u32 m0, s86, 0x3000
	s_nop 0
	global_load_lds_dwordx4 v250, s[96:97]
	s_add_u32 m0, s86, 0x7000
	s_nop 0
	global_load_lds_dwordx4 v251, s[88:89]
	s_add_u32 s96, s96, 0x80
	s_addc_u32 s97, s97, 0
	s_add_u32 s88, s88, 0x80
	s_addc_u32 s89, s89, 0
	s_and_b32 s3, s3, 0x8000
	s_add_i32 s3, s3, 0
	ds_read_b128 v[112:115], v186
	ds_read_b128 v[104:107], v145 offset:16384
	ds_read_b128 v[108:111], v145 offset:18432
	ds_read_b128 v[116:119], v186 offset:2048
	ds_read_b128 v[120:123], v145 offset:20480
	ds_read_b128 v[124:127], v145 offset:22528
	ds_read_b128 v[128:131], v145 offset:24576
	ds_read_b128 v[132:135], v145 offset:26624
	ds_read_b128 v[136:139], v145 offset:28672
	ds_read_b128 v[140:143], v145 offset:30720
	ds_read_b128 v[154:157], v188
	ds_read_b128 v[146:149], v187 offset:16384
	ds_read_b128 v[150:153], v187 offset:18432
	ds_read_b128 v[158:161], v188 offset:2048
	ds_read_b128 v[162:165], v187 offset:20480
	ds_read_b128 v[166:169], v187 offset:22528
	ds_read_b128 v[170:173], v187 offset:24576
	ds_read_b128 v[174:177], v187 offset:26624
	ds_read_b128 v[178:181], v187 offset:28672
	ds_read_b128 v[182:185], v187 offset:30720
	s_add_u32 s0, s0, 0x80
	s_addc_u32 s1, s1, 0
	s_cmpk_eq_i32 s0, 0x780
	s_mov_b32 s3, s41
	s_waitcnt lgkmcnt(15)
	v_mfma_f32_16x16x32_bf16 v[60:63], v[104:107], v[112:115], v[60:63]
	v_mfma_f32_16x16x32_bf16 v[56:59], v[108:111], v[112:115], v[56:59]
	v_mfma_f32_16x16x32_bf16 v[24:27], v[104:107], v[116:119], v[24:27]
	v_mfma_f32_16x16x32_bf16 v[20:23], v[108:111], v[116:119], v[20:23]
	v_mfma_f32_16x16x32_bf16 v[52:55], v[120:123], v[112:115], v[52:55]
	v_mfma_f32_16x16x32_bf16 v[16:19], v[120:123], v[116:119], v[16:19]
	s_waitcnt lgkmcnt(14)
	v_mfma_f32_16x16x32_bf16 v[48:51], v[124:127], v[112:115], v[48:51]
	v_mfma_f32_16x16x32_bf16 v[12:15], v[124:127], v[116:119], v[12:15]
	s_waitcnt lgkmcnt(13)
	v_mfma_f32_16x16x32_bf16 v[44:47], v[128:131], v[112:115], v[44:47]
	v_mfma_f32_16x16x32_bf16 v[8:11], v[128:131], v[116:119], v[8:11]
	s_waitcnt lgkmcnt(12)
	v_mfma_f32_16x16x32_bf16 v[36:39], v[132:135], v[112:115], v[36:39]
	v_mfma_f32_16x16x32_bf16 v[4:7], v[132:135], v[116:119], v[4:7]
	s_waitcnt lgkmcnt(11)
	v_mfma_f32_16x16x32_bf16 v[32:35], v[136:139], v[112:115], v[32:35]
	v_mfma_f32_16x16x32_bf16 v[0:3], v[136:139], v[116:119], v[0:3]
	s_waitcnt lgkmcnt(10)
	v_mfma_f32_16x16x32_bf16 v[28:31], v[140:143], v[112:115], v[28:31]
	v_mfma_f32_16x16x32_bf16 v[40:43], v[140:143], v[116:119], v[40:43]
	s_waitcnt lgkmcnt(8)
	v_mfma_f32_16x16x32_bf16 v[60:63], v[146:149], v[154:157], v[60:63]
	s_waitcnt lgkmcnt(7)
	v_mfma_f32_16x16x32_bf16 v[56:59], v[150:153], v[154:157], v[56:59]
	s_waitcnt lgkmcnt(6)
	v_mfma_f32_16x16x32_bf16 v[24:27], v[146:149], v[158:161], v[24:27]
	v_mfma_f32_16x16x32_bf16 v[20:23], v[150:153], v[158:161], v[20:23]
	s_waitcnt lgkmcnt(5)
	v_mfma_f32_16x16x32_bf16 v[52:55], v[162:165], v[154:157], v[52:55]
	v_mfma_f32_16x16x32_bf16 v[16:19], v[162:165], v[158:161], v[16:19]
	s_waitcnt lgkmcnt(4)
	v_mfma_f32_16x16x32_bf16 v[48:51], v[166:169], v[154:157], v[48:51]
	v_mfma_f32_16x16x32_bf16 v[12:15], v[166:169], v[158:161], v[12:15]
	s_waitcnt lgkmcnt(3)
	v_mfma_f32_16x16x32_bf16 v[44:47], v[170:173], v[154:157], v[44:47]
	v_mfma_f32_16x16x32_bf16 v[8:11], v[170:173], v[158:161], v[8:11]
	s_waitcnt lgkmcnt(2)
	v_mfma_f32_16x16x32_bf16 v[36:39], v[174:177], v[154:157], v[36:39]
	v_mfma_f32_16x16x32_bf16 v[4:7], v[174:177], v[158:161], v[4:7]
	s_waitcnt lgkmcnt(1)
	v_mfma_f32_16x16x32_bf16 v[32:35], v[178:181], v[154:157], v[32:35]
	v_mfma_f32_16x16x32_bf16 v[0:3], v[178:181], v[158:161], v[0:3]
	s_waitcnt lgkmcnt(0)
	v_mfma_f32_16x16x32_bf16 v[28:31], v[182:185], v[154:157], v[28:31]
	v_mfma_f32_16x16x32_bf16 v[40:43], v[182:185], v[158:161], v[40:43]
	s_cbranch_scc1 .Lu2x_1217
	s_add_i32 s41, s3, 0x8000
	s_and_b32 s40, s41, 0x8000
	s_add_i32 s40, s40, 0
	s_add_u32 s86, s40, s87
	s_mov_b32 m0, s86
	s_waitcnt vmcnt(0) lgkmcnt(0)
	s_barrier
	global_load_lds_dwordx4 v244, s[96:97]
	s_add_u32 m0, s86, 0x4000
	s_nop 0
	global_load_lds_dwordx4 v245, s[88:89]
	s_add_u32 m0, s86, 0x1000
	s_nop 0
	global_load_lds_dwordx4 v246, s[96:97]
	s_add_u32 m0, s86, 0x5000
	s_nop 0
	global_load_lds_dwordx4 v247, s[88:89]
	s_add_u32 m0, s86, 0x2000
	s_nop 0
	global_load_lds_dwordx4 v248, s[96:97]
	s_add_u32 m0, s86, 0x6000
	s_nop 0
	global_load_lds_dwordx4 v249, s[88:89]
	s_add_u32 m0, s86, 0x3000
	s_nop 0
	global_load_lds_dwordx4 v250, s[96:97]
	s_add_u32 m0, s86, 0x7000
	s_nop 0
	global_load_lds_dwordx4 v251, s[88:89]
	s_add_u32 s96, s96, 0x80
	s_addc_u32 s97, s97, 0
	s_add_u32 s88, s88, 0x80
	s_addc_u32 s89, s89, 0
	s_and_b32 s3, s3, 0x8000
	s_add_i32 s3, s3, 0
	ds_read_b128 v[112:115], v186 offset:32768
	ds_read_b128 v[104:107], v145 offset:49152
	ds_read_b128 v[108:111], v145 offset:51200
	ds_read_b128 v[116:119], v186 offset:34816
	ds_read_b128 v[120:123], v145 offset:53248
	ds_read_b128 v[124:127], v145 offset:55296
	ds_read_b128 v[128:131], v145 offset:57344
	ds_read_b128 v[132:135], v145 offset:59392
	ds_read_b128 v[136:139], v145 offset:61440
	ds_read_b128 v[140:143], v145 offset:63488
	ds_read_b128 v[154:157], v188 offset:32768
	ds_read_b128 v[146:149], v187 offset:49152
	ds_read_b128 v[150:153], v187 offset:51200
	ds_read_b128 v[158:161], v188 offset:34816
	ds_read_b128 v[162:165], v187 offset:53248
	ds_read_b128 v[166:169], v187 offset:55296
	ds_read_b128 v[170:173], v187 offset:57344
	ds_read_b128 v[174:177], v187 offset:59392
	ds_read_b128 v[178:181], v187 offset:61440
	ds_read_b128 v[182:185], v187 offset:63488
	s_add_u32 s0, s0, 0x80
	s_addc_u32 s1, s1, 0
	s_cmpk_eq_i32 s0, 0x780
	s_mov_b32 s3, s41
	s_waitcnt lgkmcnt(15)
	v_mfma_f32_16x16x32_bf16 v[60:63], v[104:107], v[112:115], v[60:63]
	v_mfma_f32_16x16x32_bf16 v[56:59], v[108:111], v[112:115], v[56:59]
	v_mfma_f32_16x16x32_bf16 v[24:27], v[104:107], v[116:119], v[24:27]
	v_mfma_f32_16x16x32_bf16 v[20:23], v[108:111], v[116:119], v[20:23]
	v_mfma_f32_16x16x32_bf16 v[52:55], v[120:123], v[112:115], v[52:55]
	v_mfma_f32_16x16x32_bf16 v[16:19], v[120:123], v[116:119], v[16:19]
	s_waitcnt lgkmcnt(14)
	v_mfma_f32_16x16x32_bf16 v[48:51], v[124:127], v[112:115], v[48:51]
	v_mfma_f32_16x16x32_bf16 v[12:15], v[124:127], v[116:119], v[12:15]
	s_waitcnt lgkmcnt(13)
	v_mfma_f32_16x16x32_bf16 v[44:47], v[128:131], v[112:115], v[44:47]
	v_mfma_f32_16x16x32_bf16 v[8:11], v[128:131], v[116:119], v[8:11]
	s_waitcnt lgkmcnt(12)
	v_mfma_f32_16x16x32_bf16 v[36:39], v[132:135], v[112:115], v[36:39]
	v_mfma_f32_16x16x32_bf16 v[4:7], v[132:135], v[116:119], v[4:7]
	s_waitcnt lgkmcnt(11)
	v_mfma_f32_16x16x32_bf16 v[32:35], v[136:139], v[112:115], v[32:35]
	v_mfma_f32_16x16x32_bf16 v[0:3], v[136:139], v[116:119], v[0:3]
	s_waitcnt lgkmcnt(10)
	v_mfma_f32_16x16x32_bf16 v[28:31], v[140:143], v[112:115], v[28:31]
	v_mfma_f32_16x16x32_bf16 v[40:43], v[140:143], v[116:119], v[40:43]
	s_waitcnt lgkmcnt(8)
	v_mfma_f32_16x16x32_bf16 v[60:63], v[146:149], v[154:157], v[60:63]
	s_waitcnt lgkmcnt(7)
	v_mfma_f32_16x16x32_bf16 v[56:59], v[150:153], v[154:157], v[56:59]
	s_waitcnt lgkmcnt(6)
	v_mfma_f32_16x16x32_bf16 v[24:27], v[146:149], v[158:161], v[24:27]
	v_mfma_f32_16x16x32_bf16 v[20:23], v[150:153], v[158:161], v[20:23]
	s_waitcnt lgkmcnt(5)
	v_mfma_f32_16x16x32_bf16 v[52:55], v[162:165], v[154:157], v[52:55]
	v_mfma_f32_16x16x32_bf16 v[16:19], v[162:165], v[158:161], v[16:19]
	s_waitcnt lgkmcnt(4)
	v_mfma_f32_16x16x32_bf16 v[48:51], v[166:169], v[154:157], v[48:51]
	v_mfma_f32_16x16x32_bf16 v[12:15], v[166:169], v[158:161], v[12:15]
	s_waitcnt lgkmcnt(3)
	v_mfma_f32_16x16x32_bf16 v[44:47], v[170:173], v[154:157], v[44:47]
	v_mfma_f32_16x16x32_bf16 v[8:11], v[170:173], v[158:161], v[8:11]
	s_waitcnt lgkmcnt(2)
	v_mfma_f32_16x16x32_bf16 v[36:39], v[174:177], v[154:157], v[36:39]
	v_mfma_f32_16x16x32_bf16 v[4:7], v[174:177], v[158:161], v[4:7]
	s_waitcnt lgkmcnt(1)
	v_mfma_f32_16x16x32_bf16 v[32:35], v[178:181], v[154:157], v[32:35]
	v_mfma_f32_16x16x32_bf16 v[0:3], v[178:181], v[158:161], v[0:3]
	s_waitcnt lgkmcnt(0)
	v_mfma_f32_16x16x32_bf16 v[28:31], v[182:185], v[154:157], v[28:31]
	v_mfma_f32_16x16x32_bf16 v[40:43], v[182:185], v[158:161], v[40:43]
	s_cbranch_scc0 .LBB0_1217
.Lu2x_1217:
	v_add_u32_e32 v64, s40, v87
	v_add_u32_e32 v103, v64, v88
	v_add3_u32 v112, s40, v88, v89
	s_waitcnt vmcnt(0)
	s_barrier
	ds_read_b128 v[82:85], v103 offset:16384
	ds_read_b128 v[104:107], v103 offset:18432
	ds_read_b128 v[108:111], v112
	ds_read_b128 v[112:115], v112 offset:2048
	ds_read_b128 v[116:119], v103 offset:20480
	ds_read_b128 v[120:123], v103 offset:22528
	ds_read_b128 v[124:127], v103 offset:24576
	ds_read_b128 v[128:131], v103 offset:26624
	ds_read_b128 v[132:135], v103 offset:28672
	ds_read_b128 v[136:139], v103 offset:30720
	v_add_u32_e32 v64, v64, v90
	s_waitcnt lgkmcnt(7)
	v_mfma_f32_16x16x32_bf16 v[60:63], v[82:85], v[108:111], v[60:63]
	s_mul_hi_i32 s0, s2, 0x3e0f83e1
	s_lshr_b32 s1, s0, 31
	s_ashr_i32 s56, s0, 4
	v_mfma_f32_16x16x32_bf16 v[56:59], v[104:107], v[108:111], v[56:59]
	s_add_i32 s56, s56, s1
	s_cmp_gt_i32 s39, 11
	s_cselect_b64 s[0:1], -1, 0
	s_waitcnt lgkmcnt(4)
	v_mfma_f32_16x16x32_bf16 v[48:51], v[120:123], v[108:111], v[48:51]
	s_lshl_b32 s53, s2, 7
	s_cmp_lt_i32 s39, 12
	s_mul_i32 s54, s56, 0xffffdf00
	s_waitcnt lgkmcnt(3)
	v_mfma_f32_16x16x32_bf16 v[44:47], v[124:127], v[108:111], v[44:47]
	s_waitcnt lgkmcnt(2)
	v_mfma_f32_16x16x32_bf16 v[36:39], v[128:131], v[108:111], v[36:39]
	s_waitcnt lgkmcnt(1)
	v_mfma_f32_16x16x32_bf16 v[32:35], v[132:135], v[108:111], v[32:35]
	s_waitcnt lgkmcnt(0)
	v_mfma_f32_16x16x32_bf16 v[28:31], v[136:139], v[108:111], v[28:31]
	v_mfma_f32_16x16x32_bf16 v[24:27], v[82:85], v[112:115], v[24:27]
	ds_read_b128 v[82:85], v64 offset:16384
	v_mfma_f32_16x16x32_bf16 v[52:55], v[116:119], v[108:111], v[52:55]
	v_mfma_f32_16x16x32_bf16 v[20:23], v[104:107], v[112:115], v[20:23]
	v_mfma_f32_16x16x32_bf16 v[16:19], v[116:119], v[112:115], v[16:19]
	v_mfma_f32_16x16x32_bf16 v[12:15], v[120:123], v[112:115], v[12:15]
	v_mfma_f32_16x16x32_bf16 v[8:11], v[124:127], v[112:115], v[8:11]
	v_mfma_f32_16x16x32_bf16 v[4:7], v[128:131], v[112:115], v[4:7]
	v_mfma_f32_16x16x32_bf16 v[0:3], v[132:135], v[112:115], v[0:3]
	v_mfma_f32_16x16x32_bf16 v[104:107], v[136:139], v[112:115], v[40:43]
	s_nop 2
	v_add3_u32 v40, s40, v90, v89
	ds_read_b128 v[108:111], v64 offset:18432
	ds_read_b128 v[112:115], v40
	ds_read_b128 v[116:119], v40 offset:2048
	ds_read_b128 v[120:123], v64 offset:20480
	ds_read_b128 v[124:127], v64 offset:22528
	ds_read_b128 v[128:131], v64 offset:24576
	ds_read_b128 v[132:135], v64 offset:26624
	ds_read_b128 v[136:139], v64 offset:28672
	ds_read_b128 v[140:143], v64 offset:30720
	s_waitcnt lgkmcnt(7)
	v_mfma_f32_16x16x32_bf16 v[60:63], v[82:85], v[112:115], v[60:63]
	v_mfma_f32_16x16x32_bf16 v[56:59], v[108:111], v[112:115], v[56:59]
	s_waitcnt lgkmcnt(5)
	v_mfma_f32_16x16x32_bf16 v[52:55], v[120:123], v[112:115], v[52:55]
	s_waitcnt lgkmcnt(4)
	v_mfma_f32_16x16x32_bf16 v[48:51], v[124:127], v[112:115], v[48:51]
	s_waitcnt lgkmcnt(3)
	v_mfma_f32_16x16x32_bf16 v[44:47], v[128:131], v[112:115], v[44:47]
	s_waitcnt lgkmcnt(2)
	v_mfma_f32_16x16x32_bf16 v[40:43], v[132:135], v[112:115], v[36:39]
	s_waitcnt lgkmcnt(1)
	v_mfma_f32_16x16x32_bf16 v[36:39], v[136:139], v[112:115], v[32:35]
	s_waitcnt lgkmcnt(0)
	v_mfma_f32_16x16x32_bf16 v[32:35], v[140:143], v[112:115], v[28:31]
	v_mfma_f32_16x16x32_bf16 v[28:31], v[82:85], v[116:119], v[24:27]
	v_mfma_f32_16x16x32_bf16 v[24:27], v[108:111], v[116:119], v[20:23]
	v_mfma_f32_16x16x32_bf16 v[20:23], v[120:123], v[116:119], v[16:19]
	v_mfma_f32_16x16x32_bf16 v[16:19], v[124:127], v[116:119], v[12:15]
	v_mfma_f32_16x16x32_bf16 v[12:15], v[128:131], v[116:119], v[8:11]
	v_mfma_f32_16x16x32_bf16 v[8:11], v[132:135], v[116:119], v[4:7]
	v_mfma_f32_16x16x32_bf16 v[4:7], v[136:139], v[116:119], v[0:3]
	v_mfma_f32_16x16x32_bf16 v[0:3], v[140:143], v[116:119], v[104:107]
	s_cbranch_scc0 .LBB0_1224
	s_add_i32 s40, s54, s53
	v_add_u32_e32 v64, s40, v70
	v_cmp_lt_i32_e32 vcc, s48, v64
	s_and_saveexec_b64 s[2:3], vcc
	s_cbranch_execz .LBB0_1221
	v_lshl_add_u32 v64, v64, 5, v102
	v_lshlrev_b64 v[108:109], 2, v[64:65]
	v_lshl_add_u64 v[104:105], v[76:77], 0, v[108:109]
	global_load_dwordx4 v[82:85], v[104:105], off
	s_nop 0
	global_load_dwordx4 v[104:107], v[104:105], off offset:16
	v_lshl_add_u64 v[112:113], v[74:75], 0, v[108:109]
	global_load_dwordx4 v[108:111], v[112:113], off
	s_nop 0
	global_load_dwordx4 v[112:115], v[112:113], off offset:16
	s_waitcnt vmcnt(3)
	v_pk_mul_f32 v[116:117], v[54:55], v[84:85]
	v_pk_mul_f32 v[118:119], v[52:53], v[82:83]
	v_pk_mul_f32 v[120:121], v[62:63], v[84:85]
	v_pk_mul_f32 v[122:123], v[60:61], v[82:83]
	s_waitcnt vmcnt(2)
	v_pk_mul_f32 v[124:125], v[50:51], v[106:107]
	v_pk_mul_f32 v[126:127], v[48:49], v[104:105]
	v_pk_mul_f32 v[128:129], v[58:59], v[106:107]
	v_pk_mul_f32 v[130:131], v[56:57], v[104:105]
	v_pk_mul_f32 v[132:133], v[38:39], v[84:85]
	v_pk_mul_f32 v[134:135], v[36:37], v[82:83]
	v_pk_mul_f32 v[84:85], v[46:47], v[84:85]
	v_pk_mul_f32 v[82:83], v[44:45], v[82:83]
	v_pk_mul_f32 v[136:137], v[34:35], v[106:107]
	v_pk_mul_f32 v[138:139], v[32:33], v[104:105]
	v_pk_mul_f32 v[106:107], v[42:43], v[106:107]
	v_pk_mul_f32 v[104:105], v[40:41], v[104:105]
	s_waitcnt vmcnt(1)
	v_pk_fma_f32 v[62:63], v[62:63], v[110:111], v[116:117] neg_lo:[0,0,1] neg_hi:[0,0,1]
	v_pk_fma_f32 v[60:61], v[60:61], v[108:109], v[118:119] neg_lo:[0,0,1] neg_hi:[0,0,1]
	v_pk_fma_f32 v[54:55], v[54:55], v[110:111], v[120:121]
	v_pk_fma_f32 v[52:53], v[52:53], v[108:109], v[122:123]
	s_waitcnt vmcnt(0)
	v_pk_fma_f32 v[58:59], v[58:59], v[114:115], v[124:125] neg_lo:[0,0,1] neg_hi:[0,0,1]
	v_pk_fma_f32 v[56:57], v[56:57], v[112:113], v[126:127] neg_lo:[0,0,1] neg_hi:[0,0,1]
	v_pk_fma_f32 v[50:51], v[50:51], v[114:115], v[128:129]
	v_pk_fma_f32 v[48:49], v[48:49], v[112:113], v[130:131]
	v_pk_fma_f32 v[46:47], v[46:47], v[110:111], v[132:133] neg_lo:[0,0,1] neg_hi:[0,0,1]
	v_pk_fma_f32 v[44:45], v[44:45], v[108:109], v[134:135] neg_lo:[0,0,1] neg_hi:[0,0,1]
	v_pk_fma_f32 v[38:39], v[38:39], v[110:111], v[84:85]
	v_pk_fma_f32 v[36:37], v[36:37], v[108:109], v[82:83]
	v_pk_fma_f32 v[42:43], v[42:43], v[114:115], v[136:137] neg_lo:[0,0,1] neg_hi:[0,0,1]
	v_pk_fma_f32 v[40:41], v[40:41], v[112:113], v[138:139] neg_lo:[0,0,1] neg_hi:[0,0,1]
	v_pk_fma_f32 v[34:35], v[34:35], v[114:115], v[106:107]
	v_pk_fma_f32 v[32:33], v[32:33], v[112:113], v[104:105]

.LBB0_1614:
	s_ashr_i32 s28, s37, 3
	s_add_i32 s28, s39, s28
	s_ashr_i32 s29, s28, 31
	s_lshr_b32 s29, s29, 26
	s_add_i32 s29, s28, s29
	s_ashr_i32 s38, s29, 6
	s_and_b32 s29, s29, 0xffc0
	s_sub_i32 s28, s28, s29
	s_bfe_i32 s29, s28, 0x80000
	s_bfe_u32 s29, s29, 0x3000c
	s_add_i32 s29, s28, s29
	s_bfe_i32 s37, s29, 0x80000
	s_and_b32 s29, s29, 0xf8
	s_sub_i32 s28, s28, s29
	s_lshl_b32 s38, s38, 3
	s_sext_i32_i8 s28, s28
	s_add_i32 s28, s38, s28
	s_ashr_i32 s29, s28, 31
	s_lshr_b32 s29, s29, 26
	s_add_i32 s29, s28, s29
	s_sext_i32_i16 s37, s37
	s_ashr_i32 s38, s29, 6
	s_andn2_b32 s29, s29, 63
	s_ashr_i32 s37, s37, 3
	s_mulk_i32 s38, 0x42
	s_sub_i32 s28, s28, s29
	s_add_i32 s38, s28, s38
	s_mul_i32 s28, s37, 0x22000
	s_add_i32 s38, s38, 2
	s_ashr_i32 s29, s28, 31
	v_readfirstlane_b32 s39, v91
	v_mad_i64_i32 v[0:1], s[40:41], s38, v90, v[64:65]
	s_lshl_b64 s[28:29], s[28:29], 1
	s_mov_b32 m0, s39
	v_readfirstlane_b32 s39, v92
	v_lshl_add_u64 v[2:3], v[66:67], 0, s[28:29]
	s_waitcnt lgkmcnt(0)
	s_barrier
	global_load_lds_dwordx4 v[0:1], off
	s_mov_b32 m0, s39
	v_readfirstlane_b32 s39, v93
	global_load_lds_dwordx4 v[2:3], off
	v_lshl_add_u64 v[4:5], v[0:1], 0, s[4:5]
	s_mov_b32 m0, s39
	v_readfirstlane_b32 s39, v94
	global_load_lds_dwordx4 v[4:5], off
	v_lshl_add_u64 v[4:5], v[2:3], 0, s[4:5]
	s_mov_b32 m0, s39
	v_readfirstlane_b32 s39, v95
	global_load_lds_dwordx4 v[4:5], off
	v_lshl_add_u64 v[4:5], v[0:1], 0, s[6:7]
	s_mov_b32 m0, s39
	v_readfirstlane_b32 s39, v96
	global_load_lds_dwordx4 v[4:5], off
	v_lshl_add_u64 v[4:5], v[2:3], 0, s[6:7]
	s_mov_b32 m0, s39
	v_readfirstlane_b32 s39, v97
	global_load_lds_dwordx4 v[4:5], off
	v_lshl_add_u64 v[0:1], v[0:1], 0, s[8:9]
	s_mov_b32 m0, s39
	v_readfirstlane_b32 s39, v98
	global_load_lds_dwordx4 v[0:1], off
	v_lshl_add_u64 v[0:1], v[2:3], 0, s[8:9]
	s_mov_b32 m0, s39
	v_mov_b32_e32 v36, 0
	global_load_lds_dwordx4 v[0:1], off
	v_mad_i64_i32 v[72:73], s[40:41], s38, v90, v[68:69]
	v_lshl_add_u64 v[74:75], v[70:71], 0, s[28:29]
	s_mov_b64 s[28:29], 0
	s_mov_b32 s39, 0
	v_mov_b32_e32 v37, v36
	v_mov_b32_e32 v38, v36
	v_mov_b32_e32 v39, v36
	v_mov_b32_e32 v0, v36
	v_mov_b32_e32 v1, v36
	v_mov_b32_e32 v2, v36
	v_mov_b32_e32 v3, v36
	v_mov_b32_e32 v4, v36
	v_mov_b32_e32 v5, v36
	v_mov_b32_e32 v6, v36
	v_mov_b32_e32 v7, v36
	v_mov_b32_e32 v8, v36
	v_mov_b32_e32 v9, v36
	v_mov_b32_e32 v10, v36
	v_mov_b32_e32 v11, v36
	v_mov_b32_e32 v12, v36
	v_mov_b32_e32 v13, v36
	v_mov_b32_e32 v14, v36
	v_mov_b32_e32 v15, v36
	v_mov_b32_e32 v16, v36
	v_mov_b32_e32 v17, v36
	v_mov_b32_e32 v18, v36
	v_mov_b32_e32 v19, v36
	v_mov_b32_e32 v20, v36
	v_mov_b32_e32 v21, v36
	v_mov_b32_e32 v22, v36
	v_mov_b32_e32 v23, v36
	v_mov_b32_e32 v24, v36
	v_mov_b32_e32 v25, v36
	v_mov_b32_e32 v26, v36
	v_mov_b32_e32 v27, v36
	v_mov_b32_e32 v28, v36
	v_mov_b32_e32 v29, v36
	v_mov_b32_e32 v30, v36
	v_mov_b32_e32 v31, v36
	v_mov_b32_e32 v32, v36
	v_mov_b32_e32 v33, v36
	v_mov_b32_e32 v34, v36
	v_mov_b32_e32 v35, v36
	v_mov_b32_e32 v40, v36
	v_mov_b32_e32 v41, v36
	v_mov_b32_e32 v42, v36
	v_mov_b32_e32 v43, v36
	v_mov_b32_e32 v44, v36
	v_mov_b32_e32 v45, v36
	v_mov_b32_e32 v46, v36
	v_mov_b32_e32 v47, v36
	v_mov_b32_e32 v48, v36
	v_mov_b32_e32 v49, v36
	v_mov_b32_e32 v50, v36
	v_mov_b32_e32 v51, v36
	v_mov_b32_e32 v52, v36
	v_mov_b32_e32 v53, v36
	v_mov_b32_e32 v54, v36
	v_mov_b32_e32 v55, v36
	v_mov_b32_e32 v56, v36
	v_mov_b32_e32 v57, v36
	v_mov_b32_e32 v58, v36
	v_mov_b32_e32 v59, v36
	v_mov_b32_e32 v60, v36
	v_mov_b32_e32 v61, v36
	v_mov_b32_e32 v62, v36
	v_mov_b32_e32 v63, v36
	v_readfirstlane_b32 s96, v72
	v_readfirstlane_b32 s97, v73
	v_readfirstlane_b32 s88, v74
	v_readfirstlane_b32 s89, v75
	v_readfirstlane_b32 s87, v82
	s_nop 1
	v_subrev_u32_e32 v244, s96, v72
	v_subrev_u32_e32 v245, s88, v74
	v_add_u32_e32 v246, 0x11000, v244
	v_add_u32_e32 v247, 0x11000, v245
	v_add_u32_e32 v248, 0x22000, v244
	v_add_u32_e32 v249, 0x22000, v245
	v_add_u32_e32 v250, 0x33000, v244
	v_add_u32_e32 v251, 0x33000, v245
	s_add_u32 s96, s96, 0x2200080
	s_addc_u32 s97, s97, 0
	s_add_u32 s88, s88, 0xe100080
	s_addc_u32 s89, s89, 0
	v_add_u32_e32 v145, v84, v85
	v_add_u32_e32 v178, v85, v86
	v_add_u32_e32 v179, v84, v87
	v_add_u32_e32 v180, v86, v87
.LBB0_1615:
	s_add_i32 s41, s39, 0x8000
	s_and_b32 s40, s41, 0x8000
	s_add_i32 s40, s40, 0
	s_add_u32 s86, s40, s87
	s_mov_b32 m0, s86
	s_waitcnt vmcnt(0) lgkmcnt(0)
	s_barrier
	global_load_lds_dwordx4 v244, s[96:97]
	s_add_u32 m0, s86, 0x4000
	s_nop 0
	global_load_lds_dwordx4 v245, s[88:89]
	s_add_u32 m0, s86, 0x1000
	s_nop 0
	global_load_lds_dwordx4 v246, s[96:97]
	s_add_u32 m0, s86, 0x5000
	s_nop 0
	global_load_lds_dwordx4 v247, s[88:89]
	s_add_u32 m0, s86, 0x2000
	s_nop 0
	global_load_lds_dwordx4 v248, s[96:97]
	s_add_u32 m0, s86, 0x6000
	s_nop 0
	global_load_lds_dwordx4 v249, s[88:89]
	s_add_u32 m0, s86, 0x3000
	s_nop 0
	global_load_lds_dwordx4 v250, s[96:97]
	s_add_u32 m0, s86, 0x7000
	s_nop 0
	global_load_lds_dwordx4 v251, s[88:89]
	s_add_u32 s96, s96, 0x80
	s_addc_u32 s97, s97, 0
	s_add_u32 s88, s88, 0x80
	s_addc_u32 s89, s89, 0
	s_and_b32 s39, s39, 0x8000
	s_add_i32 s39, s39, 0
	ds_read_b128 v[104:107], v178
	ds_read_b128 v[76:79], v145 offset:16384
	ds_read_b128 v[100:103], v145 offset:18432
	ds_read_b128 v[108:111], v178 offset:2048
	ds_read_b128 v[112:115], v145 offset:20480
	ds_read_b128 v[116:119], v145 offset:22528
	ds_read_b128 v[120:123], v145 offset:24576
	ds_read_b128 v[124:127], v145 offset:26624
	ds_read_b128 v[128:131], v145 offset:28672
	ds_read_b128 v[132:135], v145 offset:30720
	ds_read_b128 v[146:149], v180
	ds_read_b128 v[136:139], v179 offset:16384
	ds_read_b128 v[140:143], v179 offset:18432
	ds_read_b128 v[150:153], v180 offset:2048
	ds_read_b128 v[154:157], v179 offset:20480
	ds_read_b128 v[158:161], v179 offset:22528
	ds_read_b128 v[162:165], v179 offset:24576
	ds_read_b128 v[166:169], v179 offset:26624
	ds_read_b128 v[170:173], v179 offset:28672
	ds_read_b128 v[174:177], v179 offset:30720
	s_add_u32 s28, s28, 0x80
	s_addc_u32 s29, s29, 0
	s_cmpk_eq_i32 s28, 0x780
	s_mov_b32 s39, s41
	s_waitcnt lgkmcnt(15)
	v_mfma_f32_16x16x32_bf16 v[60:63], v[76:79], v[104:107], v[60:63]
	v_mfma_f32_16x16x32_bf16 v[56:59], v[100:103], v[104:107], v[56:59]
	v_mfma_f32_16x16x32_bf16 v[24:27], v[76:79], v[108:111], v[24:27]
	v_mfma_f32_16x16x32_bf16 v[20:23], v[100:103], v[108:111], v[20:23]
	v_mfma_f32_16x16x32_bf16 v[52:55], v[112:115], v[104:107], v[52:55]
	v_mfma_f32_16x16x32_bf16 v[16:19], v[112:115], v[108:111], v[16:19]
	s_waitcnt lgkmcnt(14)
	v_mfma_f32_16x16x32_bf16 v[48:51], v[116:119], v[104:107], v[48:51]
	v_mfma_f32_16x16x32_bf16 v[12:15], v[116:119], v[108:111], v[12:15]
	s_waitcnt lgkmcnt(13)
	v_mfma_f32_16x16x32_bf16 v[44:47], v[120:123], v[104:107], v[44:47]
	v_mfma_f32_16x16x32_bf16 v[8:11], v[120:123], v[108:111], v[8:11]
	s_waitcnt lgkmcnt(12)
	v_mfma_f32_16x16x32_bf16 v[40:43], v[124:127], v[104:107], v[40:43]
	v_mfma_f32_16x16x32_bf16 v[4:7], v[124:127], v[108:111], v[4:7]
	s_waitcnt lgkmcnt(11)
	v_mfma_f32_16x16x32_bf16 v[32:35], v[128:131], v[104:107], v[32:35]
	v_mfma_f32_16x16x32_bf16 v[0:3], v[128:131], v[108:111], v[0:3]
	s_waitcnt lgkmcnt(10)
	v_mfma_f32_16x16x32_bf16 v[28:31], v[132:135], v[104:107], v[28:31]
	v_mfma_f32_16x16x32_bf16 v[36:39], v[132:135], v[108:111], v[36:39]
	s_waitcnt lgkmcnt(8)
	v_mfma_f32_16x16x32_bf16 v[60:63], v[136:139], v[146:149], v[60:63]
	s_waitcnt lgkmcnt(7)
	v_mfma_f32_16x16x32_bf16 v[56:59], v[140:143], v[146:149], v[56:59]
	s_waitcnt lgkmcnt(6)
	v_mfma_f32_16x16x32_bf16 v[24:27], v[136:139], v[150:153], v[24:27]
	v_mfma_f32_16x16x32_bf16 v[20:23], v[140:143], v[150:153], v[20:23]
	s_waitcnt lgkmcnt(5)
	v_mfma_f32_16x16x32_bf16 v[52:55], v[154:157], v[146:149], v[52:55]
	v_mfma_f32_16x16x32_bf16 v[16:19], v[154:157], v[150:153], v[16:19]
	s_waitcnt lgkmcnt(4)
	v_mfma_f32_16x16x32_bf16 v[48:51], v[158:161], v[146:149], v[48:51]
	v_mfma_f32_16x16x32_bf16 v[12:15], v[158:161], v[150:153], v[12:15]
	s_waitcnt lgkmcnt(3)
	v_mfma_f32_16x16x32_bf16 v[44:47], v[162:165], v[146:149], v[44:47]
	v_mfma_f32_16x16x32_bf16 v[8:11], v[162:165], v[150:153], v[8:11]
	s_waitcnt lgkmcnt(2)
	v_mfma_f32_16x16x32_bf16 v[40:43], v[166:169], v[146:149], v[40:43]
	v_mfma_f32_16x16x32_bf16 v[4:7], v[166:169], v[150:153], v[4:7]
	s_waitcnt lgkmcnt(1)
	v_mfma_f32_16x16x32_bf16 v[32:35], v[170:173], v[146:149], v[32:35]
	v_mfma_f32_16x16x32_bf16 v[0:3], v[170:173], v[150:153], v[0:3]
	s_waitcnt lgkmcnt(0)
	v_mfma_f32_16x16x32_bf16 v[28:31], v[174:177], v[146:149], v[28:31]
	v_mfma_f32_16x16x32_bf16 v[36:39], v[174:177], v[150:153], v[36:39]
	s_cbranch_scc1 .Lu2x_1615
	s_add_i32 s41, s39, 0x8000
	s_and_b32 s40, s41, 0x8000
	s_add_i32 s40, s40, 0
	s_add_u32 s86, s40, s87
	s_mov_b32 m0, s86
	s_waitcnt vmcnt(0) lgkmcnt(0)
	s_barrier
	global_load_lds_dwordx4 v244, s[96:97]
	s_add_u32 m0, s86, 0x4000
	s_nop 0
	global_load_lds_dwordx4 v245, s[88:89]
	s_add_u32 m0, s86, 0x1000
	s_nop 0
	global_load_lds_dwordx4 v246, s[96:97]
	s_add_u32 m0, s86, 0x5000
	s_nop 0
	global_load_lds_dwordx4 v247, s[88:89]
	s_add_u32 m0, s86, 0x2000
	s_nop 0
	global_load_lds_dwordx4 v248, s[96:97]
	s_add_u32 m0, s86, 0x6000
	s_nop 0
	global_load_lds_dwordx4 v249, s[88:89]
	s_add_u32 m0, s86, 0x3000
	s_nop 0
	global_load_lds_dwordx4 v250, s[96:97]
	s_add_u32 m0, s86, 0x7000
	s_nop 0
	global_load_lds_dwordx4 v251, s[88:89]
	s_add_u32 s96, s96, 0x80
	s_addc_u32 s97, s97, 0
	s_add_u32 s88, s88, 0x80
	s_addc_u32 s89, s89, 0
	s_and_b32 s39, s39, 0x8000
	s_add_i32 s39, s39, 0
	ds_read_b128 v[104:107], v178 offset:32768
	ds_read_b128 v[76:79], v145 offset:49152
	ds_read_b128 v[100:103], v145 offset:51200
	ds_read_b128 v[108:111], v178 offset:34816
	ds_read_b128 v[112:115], v145 offset:53248
	ds_read_b128 v[116:119], v145 offset:55296
	ds_read_b128 v[120:123], v145 offset:57344
	ds_read_b128 v[124:127], v145 offset:59392
	ds_read_b128 v[128:131], v145 offset:61440
	ds_read_b128 v[132:135], v145 offset:63488
	ds_read_b128 v[146:149], v180 offset:32768
	ds_read_b128 v[136:139], v179 offset:49152
	ds_read_b128 v[140:143], v179 offset:51200
	ds_read_b128 v[150:153], v180 offset:34816
	ds_read_b128 v[154:157], v179 offset:53248
	ds_read_b128 v[158:161], v179 offset:55296
	ds_read_b128 v[162:165], v179 offset:57344
	ds_read_b128 v[166:169], v179 offset:59392
	ds_read_b128 v[170:173], v179 offset:61440
	ds_read_b128 v[174:177], v179 offset:63488
	s_add_u32 s28, s28, 0x80
	s_addc_u32 s29, s29, 0
	s_cmpk_eq_i32 s28, 0x780
	s_mov_b32 s39, s41
	s_waitcnt lgkmcnt(15)
	v_mfma_f32_16x16x32_bf16 v[60:63], v[76:79], v[104:107], v[60:63]
	v_mfma_f32_16x16x32_bf16 v[56:59], v[100:103], v[104:107], v[56:59]
	v_mfma_f32_16x16x32_bf16 v[24:27], v[76:79], v[108:111], v[24:27]
	v_mfma_f32_16x16x32_bf16 v[20:23], v[100:103], v[108:111], v[20:23]
	v_mfma_f32_16x16x32_bf16 v[52:55], v[112:115], v[104:107], v[52:55]
	v_mfma_f32_16x16x32_bf16 v[16:19], v[112:115], v[108:111], v[16:19]
	s_waitcnt lgkmcnt(14)
	v_mfma_f32_16x16x32_bf16 v[48:51], v[116:119], v[104:107], v[48:51]
	v_mfma_f32_16x16x32_bf16 v[12:15], v[116:119], v[108:111], v[12:15]
	s_waitcnt lgkmcnt(13)
	v_mfma_f32_16x16x32_bf16 v[44:47], v[120:123], v[104:107], v[44:47]
	v_mfma_f32_16x16x32_bf16 v[8:11], v[120:123], v[108:111], v[8:11]
	s_waitcnt lgkmcnt(12)
	v_mfma_f32_16x16x32_bf16 v[40:43], v[124:127], v[104:107], v[40:43]
	v_mfma_f32_16x16x32_bf16 v[4:7], v[124:127], v[108:111], v[4:7]
	s_waitcnt lgkmcnt(11)
	v_mfma_f32_16x16x32_bf16 v[32:35], v[128:131], v[104:107], v[32:35]
	v_mfma_f32_16x16x32_bf16 v[0:3], v[128:131], v[108:111], v[0:3]
	s_waitcnt lgkmcnt(10)
	v_mfma_f32_16x16x32_bf16 v[28:31], v[132:135], v[104:107], v[28:31]
	v_mfma_f32_16x16x32_bf16 v[36:39], v[132:135], v[108:111], v[36:39]
	s_waitcnt lgkmcnt(8)
	v_mfma_f32_16x16x32_bf16 v[60:63], v[136:139], v[146:149], v[60:63]
	s_waitcnt lgkmcnt(7)
	v_mfma_f32_16x16x32_bf16 v[56:59], v[140:143], v[146:149], v[56:59]
	s_waitcnt lgkmcnt(6)
	v_mfma_f32_16x16x32_bf16 v[24:27], v[136:139], v[150:153], v[24:27]
	v_mfma_f32_16x16x32_bf16 v[20:23], v[140:143], v[150:153], v[20:23]
	s_waitcnt lgkmcnt(5)
	v_mfma_f32_16x16x32_bf16 v[52:55], v[154:157], v[146:149], v[52:55]
	v_mfma_f32_16x16x32_bf16 v[16:19], v[154:157], v[150:153], v[16:19]
	s_waitcnt lgkmcnt(4)
	v_mfma_f32_16x16x32_bf16 v[48:51], v[158:161], v[146:149], v[48:51]
	v_mfma_f32_16x16x32_bf16 v[12:15], v[158:161], v[150:153], v[12:15]
	s_waitcnt lgkmcnt(3)
	v_mfma_f32_16x16x32_bf16 v[44:47], v[162:165], v[146:149], v[44:47]
	v_mfma_f32_16x16x32_bf16 v[8:11], v[162:165], v[150:153], v[8:11]
	s_waitcnt lgkmcnt(2)
	v_mfma_f32_16x16x32_bf16 v[40:43], v[166:169], v[146:149], v[40:43]
	v_mfma_f32_16x16x32_bf16 v[4:7], v[166:169], v[150:153], v[4:7]
	s_waitcnt lgkmcnt(1)
	v_mfma_f32_16x16x32_bf16 v[32:35], v[170:173], v[146:149], v[32:35]
	v_mfma_f32_16x16x32_bf16 v[0:3], v[170:173], v[150:153], v[0:3]
	s_waitcnt lgkmcnt(0)
	v_mfma_f32_16x16x32_bf16 v[28:31], v[174:177], v[146:149], v[28:31]
	v_mfma_f32_16x16x32_bf16 v[36:39], v[174:177], v[150:153], v[36:39]
	s_cbranch_scc0 .LBB0_1615
.Lu2x_1615:
	v_add_u32_e32 v80, s40, v84
	v_add_u32_e32 v81, v80, v85
	s_waitcnt vmcnt(0)
	s_barrier
	ds_read_b128 v[72:75], v81 offset:16384
	v_add3_u32 v99, s40, v85, v86
	ds_read_b128 v[76:79], v81 offset:18432
	ds_read_b128 v[100:103], v99
	ds_read_b128 v[104:107], v99 offset:2048
	ds_read_b128 v[108:111], v81 offset:20480
	ds_read_b128 v[112:115], v81 offset:22528
	ds_read_b128 v[116:119], v81 offset:24576
	ds_read_b128 v[120:123], v81 offset:26624
	ds_read_b128 v[124:127], v81 offset:28672
	ds_read_b128 v[128:131], v81 offset:30720
	v_add_u32_e32 v80, v80, v87
	s_waitcnt lgkmcnt(7)
	v_mfma_f32_16x16x32_bf16 v[60:63], v[72:75], v[100:103], v[60:63]
	s_lshl_b32 s38, s38, 7
	v_mfma_f32_16x16x32_bf16 v[56:59], v[76:79], v[100:103], v[56:59]
	s_waitcnt lgkmcnt(4)
	v_mfma_f32_16x16x32_bf16 v[48:51], v[112:115], v[100:103], v[48:51]
	s_waitcnt lgkmcnt(3)
	v_mfma_f32_16x16x32_bf16 v[44:47], v[116:119], v[100:103], v[44:47]
	s_waitcnt lgkmcnt(2)
	v_mfma_f32_16x16x32_bf16 v[40:43], v[120:123], v[100:103], v[40:43]
	s_waitcnt lgkmcnt(1)
	v_mfma_f32_16x16x32_bf16 v[32:35], v[124:127], v[100:103], v[32:35]
	s_waitcnt lgkmcnt(0)
	v_mfma_f32_16x16x32_bf16 v[28:31], v[128:131], v[100:103], v[28:31]
	v_mfma_f32_16x16x32_bf16 v[24:27], v[72:75], v[104:107], v[24:27]
	ds_read_b128 v[72:75], v80 offset:16384
	v_mfma_f32_16x16x32_bf16 v[52:55], v[108:111], v[100:103], v[52:55]
	v_mfma_f32_16x16x32_bf16 v[20:23], v[76:79], v[104:107], v[20:23]
	v_mfma_f32_16x16x32_bf16 v[16:19], v[108:111], v[104:107], v[16:19]
	v_mfma_f32_16x16x32_bf16 v[12:15], v[112:115], v[104:107], v[12:15]
	v_mfma_f32_16x16x32_bf16 v[8:11], v[116:119], v[104:107], v[8:11]
	v_mfma_f32_16x16x32_bf16 v[4:7], v[120:123], v[104:107], v[4:7]
	v_mfma_f32_16x16x32_bf16 v[0:3], v[124:127], v[104:107], v[0:3]
	v_mfma_f32_16x16x32_bf16 v[100:103], v[128:131], v[104:107], v[36:39]
	s_nop 2
	v_add3_u32 v36, s40, v87, v86
	ds_read_b128 v[76:79], v80 offset:18432
	ds_read_b128 v[104:107], v36
	ds_read_b128 v[108:111], v36 offset:2048
	ds_read_b128 v[128:131], v80 offset:28672
	ds_read_b128 v[132:135], v80 offset:30720
	ds_read_b128 v[112:115], v80 offset:20480
	ds_read_b128 v[116:119], v80 offset:22528
	ds_read_b128 v[120:123], v80 offset:24576
	ds_read_b128 v[124:127], v80 offset:26624
	s_waitcnt lgkmcnt(7)
	v_mfma_f32_16x16x32_bf16 v[60:63], v[72:75], v[104:107], v[60:63]
	s_waitcnt lgkmcnt(5)
	v_mfma_f32_16x16x32_bf16 v[36:39], v[128:131], v[104:107], v[32:35]
	s_waitcnt lgkmcnt(4)
	v_mfma_f32_16x16x32_bf16 v[32:35], v[132:135], v[104:107], v[28:31]
	v_mfma_f32_16x16x32_bf16 v[28:31], v[72:75], v[108:111], v[24:27]
	v_add_u32_e32 v72, s38, v83
	v_mul_hi_i32 v73, v72, s31
	v_mfma_f32_16x16x32_bf16 v[24:27], v[76:79], v[108:111], v[20:23]
	s_waitcnt lgkmcnt(3)
	v_mfma_f32_16x16x32_bf16 v[20:23], v[112:115], v[108:111], v[16:19]
	s_waitcnt lgkmcnt(2)
	v_mfma_f32_16x16x32_bf16 v[16:19], v[116:119], v[108:111], v[12:15]
	s_waitcnt lgkmcnt(1)
	v_mfma_f32_16x16x32_bf16 v[12:15], v[120:123], v[108:111], v[8:11]
	s_waitcnt lgkmcnt(0)
	v_mfma_f32_16x16x32_bf16 v[8:11], v[124:127], v[108:111], v[4:7]
	s_nop 2
	v_lshrrev_b32_e32 v4, 31, v73
	v_ashrrev_i32_e32 v5, 11, v73
	v_mfma_f32_16x16x32_bf16 v[56:59], v[76:79], v[104:107], v[56:59]
	v_add_u32_e32 v73, v5, v4
	v_mad_i32_i24 v78, v73, s33, v72
	v_lshlrev_b32_e32 v75, 13, v73
	v_mfma_f32_16x16x32_bf16 v[52:55], v[112:115], v[104:107], v[52:55]
	v_cmp_lt_i32_e32 vcc, s34, v78
	v_add3_u32 v74, v75, v78, s35
	v_mfma_f32_16x16x32_bf16 v[48:51], v[116:119], v[104:107], v[48:51]
	v_mfma_f32_16x16x32_bf16 v[44:47], v[120:123], v[104:107], v[44:47]
	v_mfma_f32_16x16x32_bf16 v[40:43], v[124:127], v[104:107], v[40:43]
	v_mfma_f32_16x16x32_bf16 v[4:7], v[128:131], v[108:111], v[0:3]
	v_mfma_f32_16x16x32_bf16 v[0:3], v[132:135], v[108:111], v[100:103]
	s_and_saveexec_b64 s[28:29], vcc
	s_xor_b64 s[28:29], exec, s[28:29]
	v_add3_u32 v72, v75, v78, s35
	s_or_saveexec_b64 s[28:29], s[28:29]
	v_mov_b64_e32 v[76:77], s[92:93]
	v_lshl_add_u32 v75, v73, 8, v78
	s_xor_b64 exec, exec, s[28:29]
	v_lshl_add_u32 v72, v73, 8, v78
	v_mov_b64_e32 v[76:77], s[2:3]
	s_or_b64 exec, exec, s[28:29]
	s_and_saveexec_b64 s[28:29], vcc
	s_xor_b64 s[28:29], exec, s[28:29]
	s_cbranch_execz .LBB0_1622
	v_add_u32_e32 v73, 3, v73
	v_mul_hi_i32_i24_e32 v79, 0x6000, v73
	v_mul_i32_i24_e32 v78, 0x6000, v73
	s_or_saveexec_b64 s[28:29], s[28:29]
	v_mov_b64_e32 v[80:81], s[92:93]
	s_xor_b64 exec, exec, s[28:29]
	s_cbranch_execnz .LBB0_1623
	s_branch .LBB0_1624

.LBB0_1758:
	s_ashr_i32 s26, s31, 3
	s_add_i32 s26, s34, s26
	s_ashr_i32 s27, s26, 31
	s_lshr_b32 s27, s27, 24
	s_add_i32 s27, s26, s27
	s_ashr_i32 s33, s27, 8
	s_and_b32 s27, s27, 0xff00
	s_sub_i32 s26, s26, s27
	s_sext_i32_i16 s27, s26
	s_bfe_u32 s27, s27, 0x3001c
	s_add_i32 s27, s26, s27
	s_sext_i32_i16 s31, s27
	s_and_b32 s27, s27, 0xfff8
	s_sub_i32 s26, s26, s27
	s_lshl_b32 s33, s33, 3
	s_sext_i32_i16 s26, s26
	s_add_i32 s26, s33, s26
	s_ashr_i32 s27, s26, 31
	s_lshr_b32 s27, s27, 26
	s_add_i32 s27, s26, s27
	s_ashr_i32 s33, s27, 6
	s_andn2_b32 s27, s27, 63
	s_mulk_i32 s33, 0x42
	s_sub_i32 s26, s26, s27
	s_add_i32 s33, s26, s33
	s_ashr_i32 s31, s31, 3
	s_add_i32 s33, s33, 2
	s_mul_i32 s26, s31, 0x22000
	v_mad_i64_i32 v[0:1], s[34:35], s33, v85, v[66:67]
	s_ashr_i32 s27, s26, 31
	v_readfirstlane_b32 s34, v86
	s_lshl_b64 s[26:27], s[26:27], 1
	s_mov_b32 m0, s34
	v_readfirstlane_b32 s34, v87
	v_lshl_add_u64 v[2:3], v[68:69], 0, s[26:27]
	s_waitcnt lgkmcnt(0)
	s_barrier
	global_load_lds_dwordx4 v[0:1], off
	s_mov_b32 m0, s34
	v_readfirstlane_b32 s34, v88
	global_load_lds_dwordx4 v[2:3], off
	v_lshl_add_u64 v[4:5], v[0:1], 0, s[4:5]
	s_mov_b32 m0, s34
	v_readfirstlane_b32 s34, v89
	global_load_lds_dwordx4 v[4:5], off
	v_lshl_add_u64 v[4:5], v[2:3], 0, s[4:5]
	s_mov_b32 m0, s34
	v_readfirstlane_b32 s34, v90
	global_load_lds_dwordx4 v[4:5], off
	v_lshl_add_u64 v[4:5], v[0:1], 0, s[6:7]
	s_mov_b32 m0, s34
	v_readfirstlane_b32 s34, v91
	global_load_lds_dwordx4 v[4:5], off
	v_lshl_add_u64 v[4:5], v[2:3], 0, s[6:7]
	s_mov_b32 m0, s34
	v_readfirstlane_b32 s34, v92
	global_load_lds_dwordx4 v[4:5], off
	v_lshl_add_u64 v[0:1], v[0:1], 0, s[8:9]
	s_mov_b32 m0, s34
	v_readfirstlane_b32 s34, v93
	global_load_lds_dwordx4 v[0:1], off
	v_lshl_add_u64 v[0:1], v[2:3], 0, s[8:9]
	s_mov_b32 m0, s34
	v_mad_i64_i32 v[74:75], s[34:35], s33, v85, v[70:71]
	global_load_lds_dwordx4 v[0:1], off
	v_mov_b32_e32 v16, 0
	v_lshl_add_u64 v[76:77], v[72:73], 0, s[26:27]
	s_mov_b64 s[26:27], 0
	s_mov_b32 s34, 0
	v_mov_b32_e32 v17, v16
	v_mov_b32_e32 v18, v16
	v_mov_b32_e32 v19, v16
	v_mov_b32_e32 v0, v16
	v_mov_b32_e32 v1, v16
	v_mov_b32_e32 v2, v16
	v_mov_b32_e32 v3, v16
	v_mov_b32_e32 v4, v16
	v_mov_b32_e32 v5, v16
	v_mov_b32_e32 v6, v16
	v_mov_b32_e32 v7, v16
	v_mov_b32_e32 v8, v16
	v_mov_b32_e32 v9, v16
	v_mov_b32_e32 v10, v16
	v_mov_b32_e32 v11, v16
	v_mov_b32_e32 v12, v16
	v_mov_b32_e32 v13, v16
	v_mov_b32_e32 v14, v16
	v_mov_b32_e32 v15, v16
	v_mov_b32_e32 v20, v16
	v_mov_b32_e32 v21, v16
	v_mov_b32_e32 v22, v16
	v_mov_b32_e32 v23, v16
	v_mov_b32_e32 v24, v16
	v_mov_b32_e32 v25, v16
	v_mov_b32_e32 v26, v16
	v_mov_b32_e32 v27, v16
	v_mov_b32_e32 v28, v16
	v_mov_b32_e32 v29, v16
	v_mov_b32_e32 v30, v16
	v_mov_b32_e32 v31, v16
	v_mov_b32_e32 v32, v16
	v_mov_b32_e32 v33, v16
	v_mov_b32_e32 v34, v16
	v_mov_b32_e32 v35, v16
	v_mov_b32_e32 v36, v16
	v_mov_b32_e32 v37, v16
	v_mov_b32_e32 v38, v16
	v_mov_b32_e32 v39, v16
	v_mov_b32_e32 v40, v16
	v_mov_b32_e32 v41, v16
	v_mov_b32_e32 v42, v16
	v_mov_b32_e32 v43, v16
	v_mov_b32_e32 v44, v16
	v_mov_b32_e32 v45, v16
	v_mov_b32_e32 v46, v16
	v_mov_b32_e32 v47, v16
	v_mov_b32_e32 v48, v16
	v_mov_b32_e32 v49, v16
	v_mov_b32_e32 v50, v16
	v_mov_b32_e32 v51, v16
	v_mov_b32_e32 v52, v16
	v_mov_b32_e32 v53, v16
	v_mov_b32_e32 v54, v16
	v_mov_b32_e32 v55, v16
	v_mov_b32_e32 v56, v16
	v_mov_b32_e32 v57, v16
	v_mov_b32_e32 v58, v16
	v_mov_b32_e32 v59, v16
	v_mov_b32_e32 v60, v16
	v_mov_b32_e32 v61, v16
	v_mov_b32_e32 v62, v16
	v_mov_b32_e32 v63, v16
	v_readfirstlane_b32 s96, v74
	v_readfirstlane_b32 s97, v75
	v_readfirstlane_b32 s88, v76
	v_readfirstlane_b32 s89, v77
	v_readfirstlane_b32 s87, v78
	s_nop 1
	v_subrev_u32_e32 v244, s96, v74
	v_subrev_u32_e32 v245, s88, v76
	v_add_u32_e32 v246, 0x11000, v244
	v_add_u32_e32 v247, 0x11000, v245
	v_add_u32_e32 v248, 0x22000, v244
	v_add_u32_e32 v249, 0x22000, v245
	v_add_u32_e32 v250, 0x33000, v244
	v_add_u32_e32 v251, 0x33000, v245
	s_add_u32 s96, s96, 0x2200080
	s_addc_u32 s97, s97, 0
	s_add_u32 s88, s88, 0xe320080
	s_addc_u32 s89, s89, 0
	v_add_u32_e32 v143, v80, v81
	v_add_u32_e32 v145, v81, v82
	v_add_u32_e32 v206, v80, v83
	v_add_u32_e32 v207, v82, v83
.LBB0_1759:
	s_add_i32 s36, s34, 0x8000
	s_and_b32 s35, s36, 0x8000
	s_add_i32 s35, s35, 0
	s_add_u32 s86, s35, s87
	s_mov_b32 m0, s86
	s_waitcnt vmcnt(0) lgkmcnt(0)
	s_barrier
	global_load_lds_dwordx4 v244, s[96:97]
	s_add_u32 m0, s86, 0x4000
	s_nop 0
	global_load_lds_dwordx4 v245, s[88:89]
	s_add_u32 m0, s86, 0x1000
	s_nop 0
	global_load_lds_dwordx4 v246, s[96:97]
	s_add_u32 m0, s86, 0x5000
	s_nop 0
	global_load_lds_dwordx4 v247, s[88:89]
	s_add_u32 m0, s86, 0x2000
	s_nop 0
	global_load_lds_dwordx4 v248, s[96:97]
	s_add_u32 m0, s86, 0x6000
	s_nop 0
	global_load_lds_dwordx4 v249, s[88:89]
	s_add_u32 m0, s86, 0x3000
	s_nop 0
	global_load_lds_dwordx4 v250, s[96:97]
	s_add_u32 m0, s86, 0x7000
	s_nop 0
	global_load_lds_dwordx4 v251, s[88:89]
	s_add_u32 s96, s96, 0x80
	s_addc_u32 s97, s97, 0
	s_add_u32 s88, s88, 0x80
	s_addc_u32 s89, s89, 0
	s_and_b32 s34, s34, 0x8000
	s_add_i32 s34, s34, 0
	ds_read_b128 v[102:105], v145
	ds_read_b128 v[94:97], v143 offset:16384
	ds_read_b128 v[98:101], v143 offset:18432
	ds_read_b128 v[106:109], v145 offset:2048
	ds_read_b128 v[110:113], v143 offset:20480
	ds_read_b128 v[114:117], v143 offset:22528
	ds_read_b128 v[118:121], v143 offset:24576
	ds_read_b128 v[122:125], v143 offset:26624
	ds_read_b128 v[126:129], v143 offset:28672
	ds_read_b128 v[130:133], v143 offset:30720
	ds_read_b128 v[174:177], v207
	ds_read_b128 v[166:169], v206 offset:16384
	ds_read_b128 v[170:173], v206 offset:18432
	ds_read_b128 v[178:181], v207 offset:2048
	ds_read_b128 v[182:185], v206 offset:20480
	ds_read_b128 v[186:189], v206 offset:22528
	ds_read_b128 v[190:193], v206 offset:24576
	ds_read_b128 v[194:197], v206 offset:26624
	ds_read_b128 v[198:201], v206 offset:28672
	ds_read_b128 v[202:205], v206 offset:30720
	s_add_u32 s26, s26, 0x80
	s_addc_u32 s27, s27, 0
	s_cmpk_eq_i32 s26, 0x780
	s_mov_b32 s34, s36
	s_waitcnt lgkmcnt(15)
	v_mfma_f32_16x16x32_bf16 v[60:63], v[94:97], v[102:105], v[60:63]
	v_mfma_f32_16x16x32_bf16 v[56:59], v[98:101], v[102:105], v[56:59]
	v_mfma_f32_16x16x32_bf16 v[28:31], v[94:97], v[106:109], v[28:31]
	v_mfma_f32_16x16x32_bf16 v[24:27], v[98:101], v[106:109], v[24:27]
	v_mfma_f32_16x16x32_bf16 v[52:55], v[110:113], v[102:105], v[52:55]
	v_mfma_f32_16x16x32_bf16 v[20:23], v[110:113], v[106:109], v[20:23]
	s_waitcnt lgkmcnt(14)
	v_mfma_f32_16x16x32_bf16 v[48:51], v[114:117], v[102:105], v[48:51]
	v_mfma_f32_16x16x32_bf16 v[12:15], v[114:117], v[106:109], v[12:15]
	s_waitcnt lgkmcnt(13)
	v_mfma_f32_16x16x32_bf16 v[44:47], v[118:121], v[102:105], v[44:47]
	v_mfma_f32_16x16x32_bf16 v[8:11], v[118:121], v[106:109], v[8:11]
	s_waitcnt lgkmcnt(12)
	v_mfma_f32_16x16x32_bf16 v[40:43], v[122:125], v[102:105], v[40:43]
	v_mfma_f32_16x16x32_bf16 v[4:7], v[122:125], v[106:109], v[4:7]
	s_waitcnt lgkmcnt(11)
	v_mfma_f32_16x16x32_bf16 v[36:39], v[126:129], v[102:105], v[36:39]
	v_mfma_f32_16x16x32_bf16 v[0:3], v[126:129], v[106:109], v[0:3]
	s_waitcnt lgkmcnt(10)
	v_mfma_f32_16x16x32_bf16 v[32:35], v[130:133], v[102:105], v[32:35]
	v_mfma_f32_16x16x32_bf16 v[16:19], v[130:133], v[106:109], v[16:19]
	s_waitcnt lgkmcnt(8)
	v_mfma_f32_16x16x32_bf16 v[60:63], v[166:169], v[174:177], v[60:63]
	s_waitcnt lgkmcnt(7)
	v_mfma_f32_16x16x32_bf16 v[56:59], v[170:173], v[174:177], v[56:59]
	s_waitcnt lgkmcnt(6)
	v_mfma_f32_16x16x32_bf16 v[28:31], v[166:169], v[178:181], v[28:31]
	v_mfma_f32_16x16x32_bf16 v[24:27], v[170:173], v[178:181], v[24:27]
	s_waitcnt lgkmcnt(5)
	v_mfma_f32_16x16x32_bf16 v[52:55], v[182:185], v[174:177], v[52:55]
	v_mfma_f32_16x16x32_bf16 v[20:23], v[182:185], v[178:181], v[20:23]
	s_waitcnt lgkmcnt(4)
	v_mfma_f32_16x16x32_bf16 v[48:51], v[186:189], v[174:177], v[48:51]
	v_mfma_f32_16x16x32_bf16 v[12:15], v[186:189], v[178:181], v[12:15]
	s_waitcnt lgkmcnt(3)
	v_mfma_f32_16x16x32_bf16 v[44:47], v[190:193], v[174:177], v[44:47]
	v_mfma_f32_16x16x32_bf16 v[8:11], v[190:193], v[178:181], v[8:11]
	s_waitcnt lgkmcnt(2)
	v_mfma_f32_16x16x32_bf16 v[40:43], v[194:197], v[174:177], v[40:43]
	v_mfma_f32_16x16x32_bf16 v[4:7], v[194:197], v[178:181], v[4:7]
	s_waitcnt lgkmcnt(1)
	v_mfma_f32_16x16x32_bf16 v[36:39], v[198:201], v[174:177], v[36:39]
	v_mfma_f32_16x16x32_bf16 v[0:3], v[198:201], v[178:181], v[0:3]
	s_waitcnt lgkmcnt(0)
	v_mfma_f32_16x16x32_bf16 v[32:35], v[202:205], v[174:177], v[32:35]
	v_mfma_f32_16x16x32_bf16 v[16:19], v[202:205], v[178:181], v[16:19]
	s_cbranch_scc1 .Lu2x_1759
	s_add_i32 s36, s34, 0x8000
	s_and_b32 s35, s36, 0x8000
	s_add_i32 s35, s35, 0
	s_add_u32 s86, s35, s87
	s_mov_b32 m0, s86
	s_waitcnt vmcnt(0) lgkmcnt(0)
	s_barrier
	global_load_lds_dwordx4 v244, s[96:97]
	s_add_u32 m0, s86, 0x4000
	s_nop 0
	global_load_lds_dwordx4 v245, s[88:89]
	s_add_u32 m0, s86, 0x1000
	s_nop 0
	global_load_lds_dwordx4 v246, s[96:97]
	s_add_u32 m0, s86, 0x5000
	s_nop 0
	global_load_lds_dwordx4 v247, s[88:89]
	s_add_u32 m0, s86, 0x2000
	s_nop 0
	global_load_lds_dwordx4 v248, s[96:97]
	s_add_u32 m0, s86, 0x6000
	s_nop 0
	global_load_lds_dwordx4 v249, s[88:89]
	s_add_u32 m0, s86, 0x3000
	s_nop 0
	global_load_lds_dwordx4 v250, s[96:97]
	s_add_u32 m0, s86, 0x7000
	s_nop 0
	global_load_lds_dwordx4 v251, s[88:89]
	s_add_u32 s96, s96, 0x80
	s_addc_u32 s97, s97, 0
	s_add_u32 s88, s88, 0x80
	s_addc_u32 s89, s89, 0
	s_and_b32 s34, s34, 0x8000
	s_add_i32 s34, s34, 0
	ds_read_b128 v[102:105], v145 offset:32768
	ds_read_b128 v[94:97], v143 offset:49152
	ds_read_b128 v[98:101], v143 offset:51200
	ds_read_b128 v[106:109], v145 offset:34816
	ds_read_b128 v[110:113], v143 offset:53248
	ds_read_b128 v[114:117], v143 offset:55296
	ds_read_b128 v[118:121], v143 offset:57344
	ds_read_b128 v[122:125], v143 offset:59392
	ds_read_b128 v[126:129], v143 offset:61440
	ds_read_b128 v[130:133], v143 offset:63488
	ds_read_b128 v[174:177], v207 offset:32768
	ds_read_b128 v[166:169], v206 offset:49152
	ds_read_b128 v[170:173], v206 offset:51200
	ds_read_b128 v[178:181], v207 offset:34816
	ds_read_b128 v[182:185], v206 offset:53248
	ds_read_b128 v[186:189], v206 offset:55296
	ds_read_b128 v[190:193], v206 offset:57344
	ds_read_b128 v[194:197], v206 offset:59392
	ds_read_b128 v[198:201], v206 offset:61440
	ds_read_b128 v[202:205], v206 offset:63488
	s_add_u32 s26, s26, 0x80
	s_addc_u32 s27, s27, 0
	s_cmpk_eq_i32 s26, 0x780
	s_mov_b32 s34, s36
	s_waitcnt lgkmcnt(15)
	v_mfma_f32_16x16x32_bf16 v[60:63], v[94:97], v[102:105], v[60:63]
	v_mfma_f32_16x16x32_bf16 v[56:59], v[98:101], v[102:105], v[56:59]
	v_mfma_f32_16x16x32_bf16 v[28:31], v[94:97], v[106:109], v[28:31]
	v_mfma_f32_16x16x32_bf16 v[24:27], v[98:101], v[106:109], v[24:27]
	v_mfma_f32_16x16x32_bf16 v[52:55], v[110:113], v[102:105], v[52:55]
	v_mfma_f32_16x16x32_bf16 v[20:23], v[110:113], v[106:109], v[20:23]
	s_waitcnt lgkmcnt(14)
	v_mfma_f32_16x16x32_bf16 v[48:51], v[114:117], v[102:105], v[48:51]
	v_mfma_f32_16x16x32_bf16 v[12:15], v[114:117], v[106:109], v[12:15]
	s_waitcnt lgkmcnt(13)
	v_mfma_f32_16x16x32_bf16 v[44:47], v[118:121], v[102:105], v[44:47]
	v_mfma_f32_16x16x32_bf16 v[8:11], v[118:121], v[106:109], v[8:11]
	s_waitcnt lgkmcnt(12)
	v_mfma_f32_16x16x32_bf16 v[40:43], v[122:125], v[102:105], v[40:43]
	v_mfma_f32_16x16x32_bf16 v[4:7], v[122:125], v[106:109], v[4:7]
	s_waitcnt lgkmcnt(11)
	v_mfma_f32_16x16x32_bf16 v[36:39], v[126:129], v[102:105], v[36:39]
	v_mfma_f32_16x16x32_bf16 v[0:3], v[126:129], v[106:109], v[0:3]
	s_waitcnt lgkmcnt(10)
	v_mfma_f32_16x16x32_bf16 v[32:35], v[130:133], v[102:105], v[32:35]
	v_mfma_f32_16x16x32_bf16 v[16:19], v[130:133], v[106:109], v[16:19]
	s_waitcnt lgkmcnt(8)
	v_mfma_f32_16x16x32_bf16 v[60:63], v[166:169], v[174:177], v[60:63]
	s_waitcnt lgkmcnt(7)
	v_mfma_f32_16x16x32_bf16 v[56:59], v[170:173], v[174:177], v[56:59]
	s_waitcnt lgkmcnt(6)
	v_mfma_f32_16x16x32_bf16 v[28:31], v[166:169], v[178:181], v[28:31]
	v_mfma_f32_16x16x32_bf16 v[24:27], v[170:173], v[178:181], v[24:27]
	s_waitcnt lgkmcnt(5)
	v_mfma_f32_16x16x32_bf16 v[52:55], v[182:185], v[174:177], v[52:55]
	v_mfma_f32_16x16x32_bf16 v[20:23], v[182:185], v[178:181], v[20:23]
	s_waitcnt lgkmcnt(4)
	v_mfma_f32_16x16x32_bf16 v[48:51], v[186:189], v[174:177], v[48:51]
	v_mfma_f32_16x16x32_bf16 v[12:15], v[186:189], v[178:181], v[12:15]
	s_waitcnt lgkmcnt(3)
	v_mfma_f32_16x16x32_bf16 v[44:47], v[190:193], v[174:177], v[44:47]
	v_mfma_f32_16x16x32_bf16 v[8:11], v[190:193], v[178:181], v[8:11]
	s_waitcnt lgkmcnt(2)
	v_mfma_f32_16x16x32_bf16 v[40:43], v[194:197], v[174:177], v[40:43]
	v_mfma_f32_16x16x32_bf16 v[4:7], v[194:197], v[178:181], v[4:7]
	s_waitcnt lgkmcnt(1)
	v_mfma_f32_16x16x32_bf16 v[36:39], v[198:201], v[174:177], v[36:39]
	v_mfma_f32_16x16x32_bf16 v[0:3], v[198:201], v[178:181], v[0:3]
	s_waitcnt lgkmcnt(0)
	v_mfma_f32_16x16x32_bf16 v[32:35], v[202:205], v[174:177], v[32:35]
	v_mfma_f32_16x16x32_bf16 v[16:19], v[202:205], v[178:181], v[16:19]
	s_cbranch_scc0 .LBB0_1759
.Lu2x_1759:
	v_add_u32_e32 v138, s35, v80
	v_add_u32_e32 v126, v138, v81
	s_waitcnt vmcnt(0)
	s_barrier
	ds_read_b128 v[74:77], v126 offset:16384
	v_add3_u32 v102, s35, v81, v82
	ds_read_b128 v[94:97], v102
	ds_read_b128 v[98:101], v126 offset:18432
	ds_read_b128 v[102:105], v102 offset:2048
	ds_read_b128 v[106:109], v126 offset:20480
	ds_read_b128 v[110:113], v126 offset:22528
	ds_read_b128 v[114:117], v126 offset:24576
	ds_read_b128 v[118:121], v126 offset:26624
	v_add3_u32 v134, s35, v83, v82
	v_add_u32_e32 v142, v138, v83
	ds_read_b128 v[122:125], v126 offset:28672
	ds_read_b128 v[126:129], v126 offset:30720
	ds_read_b128 v[130:133], v134
	ds_read_b128 v[134:137], v134 offset:2048
	ds_read_b128 v[138:141], v142 offset:16384
	ds_read_b128 v[146:149], v142 offset:18432
	s_waitcnt lgkmcnt(11)
	v_mfma_f32_16x16x32_bf16 v[56:59], v[98:101], v[94:97], v[56:59]
	s_lshl_b32 s33, s33, 7
	s_lshl_b32 s26, s31, 7
	s_ashr_i32 s27, s26, 31
	v_mfma_f32_16x16x32_bf16 v[60:63], v[74:77], v[94:97], v[60:63]
	s_lshl_b64 s[26:27], s[26:27], 1
	s_add_i32 s30, s30, s28
	s_cmpk_gt_i32 s30, 0xfff
	s_waitcnt lgkmcnt(0)
	v_mfma_f32_16x16x32_bf16 v[56:59], v[146:149], v[130:133], v[56:59]
	v_mfma_f32_16x16x32_bf16 v[48:51], v[110:113], v[94:97], v[48:51]
	v_mfma_f32_16x16x32_bf16 v[52:55], v[106:109], v[94:97], v[52:55]
	s_nop 5
	v_max_f32_e32 v56, v56, v56
	v_max_f32_e32 v57, v57, v57
	v_max_f32_e32 v56, 0, v56
	v_mfma_f32_16x16x32_bf16 v[44:47], v[114:117], v[94:97], v[44:47]
	v_max_f32_e32 v57, 0, v57
	v_max_f32_e32 v59, v59, v59
	v_max_f32_e32 v59, 0, v59
	v_mfma_f32_16x16x32_bf16 v[40:43], v[118:121], v[94:97], v[40:43]
	v_mfma_f32_16x16x32_bf16 v[36:39], v[122:125], v[94:97], v[36:39]
	v_mfma_f32_16x16x32_bf16 v[32:35], v[126:129], v[94:97], v[32:35]
	ds_read_b128 v[94:97], v142 offset:20480
	ds_read_b128 v[150:153], v142 offset:22528
	ds_read_b128 v[154:157], v142 offset:24576
	ds_read_b128 v[158:161], v142 offset:26624
	v_mfma_f32_16x16x32_bf16 v[60:63], v[138:141], v[130:133], v[60:63]
	s_waitcnt lgkmcnt(2)
	v_mfma_f32_16x16x32_bf16 v[48:51], v[150:153], v[130:133], v[48:51]
	v_mfma_f32_16x16x32_bf16 v[20:23], v[106:109], v[102:105], v[20:23]
	v_mul_f32_e64 v106, v56, v56
	v_mul_f32_e64 v107, v57, v57
	v_max_f32_e32 v57, v58, v58
	s_nop 1
	v_max_f32_e32 v60, v60, v60
	v_mfma_f32_16x16x32_bf16 v[24:27], v[98:101], v[102:105], v[24:27]
	v_add_u32_e32 v100, s33, v79
	v_mov_b64_e32 v[98:99], s[0:1]
	v_max_f32_e32 v61, v61, v61
	v_max_f32_e32 v56, v62, v62
	v_max_f32_e32 v58, 0, v57
	v_max_f32_e32 v57, v63, v63
	v_mad_i64_i32 v[100:101], s[34:35], v100, s29, v[98:99]
	v_max_f32_e32 v60, 0, v60
	v_max_f32_e32 v61, 0, v61
	v_max_f32_e32 v56, 0, v56
	v_max_f32_e32 v57, 0, v57
	v_mfma_f32_16x16x32_bf16 v[52:55], v[94:97], v[130:133], v[52:55]
	v_lshl_add_u64 v[100:101], v[100:101], 0, s[26:27]
	v_pk_mul_f32 v[60:61], v[60:61], v[60:61]
	v_pk_mul_f32 v[62:63], v[56:57], v[56:57]
	v_mfma_f32_16x16x32_bf16 v[28:31], v[74:77], v[102:105], v[28:31]
	v_max_f32_e32 v48, v48, v48
	v_max_f32_e32 v49, v49, v49
	ds_read_b128 v[74:77], v142 offset:28672
	ds_read_b128 v[162:165], v142 offset:30720
	v_mfma_f32_16x16x32_bf16 v[12:15], v[110:113], v[102:105], v[12:15]
	v_lshl_add_u64 v[100:101], v[100:101], 0, v[64:65]
	v_cvt_pk_bf16_f32 v56, v60, v61
	v_cvt_pk_bf16_f32 v57, v62, v63
	v_mfma_f32_16x16x32_bf16 v[8:11], v[114:117], v[102:105], v[8:11]
	v_max_f32_e32 v48, 0, v48
	v_max_f32_e32 v49, 0, v49
	v_max_f32_e32 v52, v52, v52
	v_mfma_f32_16x16x32_bf16 v[4:7], v[118:121], v[102:105], v[4:7]
	v_max_f32_e32 v53, v53, v53
	v_max_f32_e32 v51, v51, v51
	v_max_f32_e32 v52, 0, v52
	v_mfma_f32_16x16x32_bf16 v[0:3], v[122:125], v[102:105], v[0:3]
	v_max_f32_e32 v53, 0, v53
	v_max_f32_e32 v51, 0, v51
	v_pk_mul_f32 v[52:53], v[52:53], v[52:53]
	v_mfma_f32_16x16x32_bf16 v[16:19], v[126:129], v[102:105], v[16:19]
	v_mul_f32_e64 v102, v58, v58
	v_mul_f32_e64 v103, v59, v59
	v_cvt_pk_bf16_f32 v58, v106, v107
	v_cvt_pk_bf16_f32 v59, v102, v103
	s_waitcnt lgkmcnt(2)
	v_mfma_f32_16x16x32_bf16 v[40:43], v[158:161], v[130:133], v[40:43]
	global_store_dwordx4 v[100:101], v[56:59], off
	s_nop 1
	v_pk_mul_f32 v[56:57], v[48:49], v[48:49]
	v_max_f32_e32 v49, v50, v50
	v_max_f32_e32 v48, v54, v54
	v_max_f32_e32 v50, 0, v49
	v_max_f32_e32 v49, v55, v55
	v_mfma_f32_16x16x32_bf16 v[44:47], v[154:157], v[130:133], v[44:47]
	v_max_f32_e32 v48, 0, v48
	v_max_f32_e32 v49, 0, v49
	v_pk_mul_f32 v[54:55], v[48:49], v[48:49]
	v_pk_mul_f32 v[58:59], v[50:51], v[50:51]
	v_max_f32_e32 v40, v40, v40
	v_max_f32_e32 v41, v41, v41
	s_waitcnt lgkmcnt(0)
	v_mfma_f32_16x16x32_bf16 v[32:35], v[162:165], v[130:133], v[32:35]
	v_cvt_pk_bf16_f32 v48, v52, v53
	v_cvt_pk_bf16_f32 v49, v54, v55
	v_cvt_pk_bf16_f32 v50, v56, v57
	v_cvt_pk_bf16_f32 v51, v58, v59
	v_max_f32_e32 v40, 0, v40
	v_max_f32_e32 v41, 0, v41
	global_store_dwordx4 v[100:101], v[48:51], off offset:64
	v_max_f32_e32 v44, v44, v44
	v_max_f32_e32 v45, v45, v45
	v_pk_mul_f32 v[48:49], v[40:41], v[40:41]
	v_max_f32_e32 v41, v42, v42
	v_max_f32_e32 v40, v46, v46
	v_max_f32_e32 v42, 0, v41
	v_max_f32_e32 v41, v47, v47
	v_max_f32_e32 v43, v43, v43
	v_mfma_f32_16x16x32_bf16 v[36:39], v[74:77], v[130:133], v[36:39]
	v_max_f32_e32 v44, 0, v44
	v_max_f32_e32 v45, 0, v45
	v_max_f32_e32 v40, 0, v40
	v_max_f32_e32 v41, 0, v41
	v_max_f32_e32 v43, 0, v43
	v_pk_mul_f32 v[44:45], v[44:45], v[44:45]
	v_pk_mul_f32 v[46:47], v[40:41], v[40:41]
	v_pk_mul_f32 v[50:51], v[42:43], v[42:43]
	v_max_f32_e32 v32, v32, v32
	v_max_f32_e32 v33, v33, v33
	v_mfma_f32_16x16x32_bf16 v[24:27], v[146:149], v[134:137], v[24:27]
	v_cvt_pk_bf16_f32 v40, v44, v45
	v_cvt_pk_bf16_f32 v41, v46, v47
	v_cvt_pk_bf16_f32 v42, v48, v49
	v_cvt_pk_bf16_f32 v43, v50, v51
	v_max_f32_e32 v32, 0, v32
	v_max_f32_e32 v33, 0, v33
	global_store_dwordx4 v[100:101], v[40:43], off offset:128
	v_max_f32_e32 v36, v36, v36
	v_max_f32_e32 v37, v37, v37
	v_pk_mul_f32 v[40:41], v[32:33], v[32:33]
	v_max_f32_e32 v33, v34, v34
	v_max_f32_e32 v32, v38, v38
	v_max_f32_e32 v34, 0, v33
	v_max_f32_e32 v33, v39, v39
	v_max_f32_e32 v35, v35, v35
	v_mfma_f32_16x16x32_bf16 v[28:31], v[138:141], v[134:137], v[28:31]
	v_max_f32_e32 v36, 0, v36
	v_max_f32_e32 v37, 0, v37
	v_max_f32_e32 v32, 0, v32
	v_max_f32_e32 v33, 0, v33
	v_max_f32_e32 v35, 0, v35
	v_pk_mul_f32 v[36:37], v[36:37], v[36:37]
	v_pk_mul_f32 v[38:39], v[32:33], v[32:33]
	v_pk_mul_f32 v[42:43], v[34:35], v[34:35]
	v_max_f32_e32 v24, v24, v24
	v_max_f32_e32 v25, v25, v25
	v_mfma_f32_16x16x32_bf16 v[12:15], v[150:153], v[134:137], v[12:15]
	v_cvt_pk_bf16_f32 v32, v36, v37
	v_cvt_pk_bf16_f32 v33, v38, v39
	v_cvt_pk_bf16_f32 v34, v40, v41
	v_cvt_pk_bf16_f32 v35, v42, v43
	v_max_f32_e32 v24, 0, v24
	v_max_f32_e32 v25, 0, v25
	global_store_dwordx4 v[100:101], v[32:35], off offset:192
	v_max_f32_e32 v28, v28, v28
	v_max_f32_e32 v29, v29, v29
	v_pk_mul_f32 v[34:35], v[24:25], v[24:25]
	v_max_f32_e32 v25, v26, v26
	v_add_u32_e32 v32, s33, v84
	v_max_f32_e32 v24, v30, v30
	v_max_f32_e32 v26, 0, v25
	v_max_f32_e32 v25, v31, v31
	v_max_f32_e32 v27, v27, v27
	v_mfma_f32_16x16x32_bf16 v[20:23], v[94:97], v[134:137], v[20:23]
	v_mad_i64_i32 v[32:33], s[34:35], v32, s29, v[98:99]
	v_max_f32_e32 v28, 0, v28
	v_max_f32_e32 v29, 0, v29
	v_max_f32_e32 v24, 0, v24
	v_max_f32_e32 v25, 0, v25
	v_max_f32_e32 v27, 0, v27
	v_lshl_add_u64 v[32:33], v[32:33], 0, s[26:27]
	v_pk_mul_f32 v[28:29], v[28:29], v[28:29]
	v_pk_mul_f32 v[30:31], v[24:25], v[24:25]
	v_pk_mul_f32 v[36:37], v[26:27], v[26:27]
	v_max_f32_e32 v12, v12, v12
	v_max_f32_e32 v13, v13, v13
	v_mfma_f32_16x16x32_bf16 v[4:7], v[158:161], v[134:137], v[4:7]
	v_lshl_add_u64 v[32:33], v[32:33], 0, v[64:65]
	v_cvt_pk_bf16_f32 v24, v28, v29
	v_cvt_pk_bf16_f32 v25, v30, v31
	v_cvt_pk_bf16_f32 v26, v34, v35
	v_cvt_pk_bf16_f32 v27, v36, v37
	v_max_f32_e32 v12, 0, v12
	v_max_f32_e32 v13, 0, v13
	global_store_dwordx4 v[32:33], v[24:27], off
	v_max_f32_e32 v20, v20, v20
	v_max_f32_e32 v21, v21, v21
	v_pk_mul_f32 v[24:25], v[12:13], v[12:13]
	v_max_f32_e32 v13, v14, v14
	v_max_f32_e32 v12, v22, v22
	v_max_f32_e32 v14, 0, v13
	v_max_f32_e32 v13, v23, v23
	v_max_f32_e32 v15, v15, v15
	v_mfma_f32_16x16x32_bf16 v[8:11], v[154:157], v[134:137], v[8:11]
	v_max_f32_e32 v20, 0, v20
	v_max_f32_e32 v21, 0, v21
	v_max_f32_e32 v12, 0, v12
	v_max_f32_e32 v13, 0, v13
	v_max_f32_e32 v15, 0, v15
	v_pk_mul_f32 v[20:21], v[20:21], v[20:21]
	v_pk_mul_f32 v[22:23], v[12:13], v[12:13]
	v_pk_mul_f32 v[26:27], v[14:15], v[14:15]
	v_max_f32_e32 v4, v4, v4
	v_max_f32_e32 v5, v5, v5
	v_cvt_pk_bf16_f32 v12, v20, v21
	v_cvt_pk_bf16_f32 v13, v22, v23
	v_cvt_pk_bf16_f32 v14, v24, v25
	v_cvt_pk_bf16_f32 v15, v26, v27
	v_max_f32_e32 v4, 0, v4
	v_max_f32_e32 v5, 0, v5
	global_store_dwordx4 v[32:33], v[12:15], off offset:64
	v_mfma_f32_16x16x32_bf16 v[0:3], v[74:77], v[134:137], v[0:3]
	v_max_f32_e32 v8, v8, v8
	v_pk_mul_f32 v[12:13], v[4:5], v[4:5]
	v_max_f32_e32 v5, v6, v6
	v_mfma_f32_16x16x32_bf16 v[16:19], v[162:165], v[134:137], v[16:19]
	v_max_f32_e32 v9, v9, v9
	v_max_f32_e32 v4, v10, v10
	v_max_f32_e32 v6, 0, v5
	v_max_f32_e32 v5, v11, v11
	v_max_f32_e32 v7, v7, v7
	v_max_f32_e32 v8, 0, v8
	v_max_f32_e32 v9, 0, v9
	v_max_f32_e32 v4, 0, v4
	v_max_f32_e32 v5, 0, v5
	v_max_f32_e32 v7, 0, v7
	v_pk_mul_f32 v[8:9], v[8:9], v[8:9]
	v_pk_mul_f32 v[10:11], v[4:5], v[4:5]
	v_pk_mul_f32 v[14:15], v[6:7], v[6:7]
	v_cvt_pk_bf16_f32 v4, v8, v9
	v_cvt_pk_bf16_f32 v5, v10, v11
	v_cvt_pk_bf16_f32 v6, v12, v13
	v_cvt_pk_bf16_f32 v7, v14, v15
	global_store_dwordx4 v[32:33], v[4:7], off offset:128
	v_max_f32_e32 v0, v0, v0
	v_max_f32_e32 v1, v1, v1
	v_max_f32_e32 v4, v16, v16
	v_max_f32_e32 v5, v17, v17
	v_max_f32_e32 v2, v2, v2
	v_max_f32_e32 v6, v18, v18
	v_max_f32_e32 v3, v3, v3
	v_max_f32_e32 v7, v19, v19
	v_max_f32_e32 v0, 0, v0
	v_max_f32_e32 v4, 0, v4
	v_max_f32_e32 v1, 0, v1
	v_max_f32_e32 v5, 0, v5
	v_max_f32_e32 v2, 0, v2
	v_max_f32_e32 v6, 0, v6
	v_max_f32_e32 v3, 0, v3
	v_max_f32_e32 v7, 0, v7
	v_pk_mul_f32 v[0:1], v[0:1], v[0:1]
	v_pk_mul_f32 v[4:5], v[4:5], v[4:5]
	v_pk_mul_f32 v[2:3], v[2:3], v[2:3]
	v_pk_mul_f32 v[6:7], v[6:7], v[6:7]
	v_cvt_pk_bf16_f32 v0, v0, v1
	v_cvt_pk_bf16_f32 v1, v2, v3
	v_cvt_pk_bf16_f32 v2, v4, v5
	v_cvt_pk_bf16_f32 v3, v6, v7
	global_store_dwordx4 v[32:33], v[0:3], off offset:192
	s_cbranch_scc0 .LBB0_1754

.LBB0_1823:
	s_ashr_i32 s28, s37, 3
	s_add_i32 s28, s39, s28
	s_ashr_i32 s29, s28, 31
	s_lshr_b32 s29, s29, 26
	s_add_i32 s29, s28, s29
	s_ashr_i32 s38, s29, 6
	s_and_b32 s29, s29, 0xffc0
	s_sub_i32 s28, s28, s29
	s_bfe_i32 s29, s28, 0x80000
	s_bfe_u32 s29, s29, 0x3000c
	s_add_i32 s29, s28, s29
	s_bfe_i32 s37, s29, 0x80000
	s_and_b32 s29, s29, 0xf8
	s_sub_i32 s28, s28, s29
	s_lshl_b32 s38, s38, 3
	s_sext_i32_i8 s28, s28
	s_add_i32 s28, s38, s28
	s_ashr_i32 s29, s28, 31
	s_lshr_b32 s29, s29, 26
	s_add_i32 s29, s28, s29
	s_sext_i32_i16 s37, s37
	s_ashr_i32 s38, s29, 6
	s_andn2_b32 s29, s29, 63
	s_ashr_i32 s37, s37, 3
	s_mulk_i32 s38, 0x42
	s_sub_i32 s28, s28, s29
	s_add_i32 s38, s28, s38
	s_mul_i32 s28, s37, 0x82000
	s_add_i32 s38, s38, 2
	s_ashr_i32 s29, s28, 31
	v_readfirstlane_b32 s39, v91
	v_mad_i64_i32 v[0:1], s[40:41], s38, v90, v[64:65]
	s_lshl_b64 s[28:29], s[28:29], 1
	s_mov_b32 m0, s39
	v_readfirstlane_b32 s39, v92
	v_lshl_add_u64 v[2:3], v[66:67], 0, s[28:29]
	s_waitcnt lgkmcnt(0)
	s_barrier
	global_load_lds_dwordx4 v[0:1], off
	s_mov_b32 m0, s39
	v_readfirstlane_b32 s39, v93
	global_load_lds_dwordx4 v[2:3], off
	v_lshl_add_u64 v[4:5], v[0:1], 0, s[4:5]
	s_mov_b32 m0, s39
	v_readfirstlane_b32 s39, v94
	global_load_lds_dwordx4 v[4:5], off
	v_lshl_add_u64 v[4:5], v[2:3], 0, s[4:5]
	s_mov_b32 m0, s39
	v_readfirstlane_b32 s39, v95
	global_load_lds_dwordx4 v[4:5], off
	v_lshl_add_u64 v[4:5], v[0:1], 0, s[6:7]
	s_mov_b32 m0, s39
	v_readfirstlane_b32 s39, v96
	global_load_lds_dwordx4 v[4:5], off
	v_lshl_add_u64 v[4:5], v[2:3], 0, s[6:7]
	s_mov_b32 m0, s39
	v_readfirstlane_b32 s39, v97
	global_load_lds_dwordx4 v[4:5], off
	v_lshl_add_u64 v[0:1], v[0:1], 0, s[8:9]
	s_mov_b32 m0, s39
	v_readfirstlane_b32 s39, v98
	global_load_lds_dwordx4 v[0:1], off
	v_lshl_add_u64 v[0:1], v[2:3], 0, s[8:9]
	s_mov_b32 m0, s39
	v_mov_b32_e32 v36, 0
	global_load_lds_dwordx4 v[0:1], off
	v_mad_i64_i32 v[72:73], s[40:41], s38, v90, v[68:69]
	v_lshl_add_u64 v[74:75], v[70:71], 0, s[28:29]
	s_mov_b64 s[28:29], 0
	s_mov_b32 s39, 0
	v_mov_b32_e32 v37, v36
	v_mov_b32_e32 v38, v36
	v_mov_b32_e32 v39, v36
	v_mov_b32_e32 v0, v36
	v_mov_b32_e32 v1, v36
	v_mov_b32_e32 v2, v36
	v_mov_b32_e32 v3, v36
	v_mov_b32_e32 v4, v36
	v_mov_b32_e32 v5, v36
	v_mov_b32_e32 v6, v36
	v_mov_b32_e32 v7, v36
	v_mov_b32_e32 v8, v36
	v_mov_b32_e32 v9, v36
	v_mov_b32_e32 v10, v36
	v_mov_b32_e32 v11, v36
	v_mov_b32_e32 v12, v36
	v_mov_b32_e32 v13, v36
	v_mov_b32_e32 v14, v36
	v_mov_b32_e32 v15, v36
	v_mov_b32_e32 v16, v36
	v_mov_b32_e32 v17, v36
	v_mov_b32_e32 v18, v36
	v_mov_b32_e32 v19, v36
	v_mov_b32_e32 v20, v36
	v_mov_b32_e32 v21, v36
	v_mov_b32_e32 v22, v36
	v_mov_b32_e32 v23, v36
	v_mov_b32_e32 v24, v36
	v_mov_b32_e32 v25, v36
	v_mov_b32_e32 v26, v36
	v_mov_b32_e32 v27, v36
	v_mov_b32_e32 v28, v36
	v_mov_b32_e32 v29, v36
	v_mov_b32_e32 v30, v36
	v_mov_b32_e32 v31, v36
	v_mov_b32_e32 v32, v36
	v_mov_b32_e32 v33, v36
	v_mov_b32_e32 v34, v36
	v_mov_b32_e32 v35, v36
	v_mov_b32_e32 v40, v36
	v_mov_b32_e32 v41, v36
	v_mov_b32_e32 v42, v36
	v_mov_b32_e32 v43, v36
	v_mov_b32_e32 v44, v36
	v_mov_b32_e32 v45, v36
	v_mov_b32_e32 v46, v36
	v_mov_b32_e32 v47, v36
	v_mov_b32_e32 v48, v36
	v_mov_b32_e32 v49, v36
	v_mov_b32_e32 v50, v36
	v_mov_b32_e32 v51, v36
	v_mov_b32_e32 v52, v36
	v_mov_b32_e32 v53, v36
	v_mov_b32_e32 v54, v36
	v_mov_b32_e32 v55, v36
	v_mov_b32_e32 v56, v36
	v_mov_b32_e32 v57, v36
	v_mov_b32_e32 v58, v36
	v_mov_b32_e32 v59, v36
	v_mov_b32_e32 v60, v36
	v_mov_b32_e32 v61, v36
	v_mov_b32_e32 v62, v36
	v_mov_b32_e32 v63, v36
	v_readfirstlane_b32 s96, v72
	v_readfirstlane_b32 s97, v73
	v_readfirstlane_b32 s88, v74
	v_readfirstlane_b32 s89, v75
	v_readfirstlane_b32 s87, v82
	s_nop 1
	v_subrev_u32_e32 v244, s96, v72
	v_subrev_u32_e32 v245, s88, v74
	v_add_u32_e32 v246, 0x41000, v244
	v_add_u32_e32 v247, 0x41000, v245
	v_add_u32_e32 v248, 0x82000, v244
	v_add_u32_e32 v249, 0x82000, v245
	v_add_u32_e32 v250, 0xc3000, v244
	v_add_u32_e32 v251, 0xc3000, v245
	s_add_u32 s96, s96, 0x4510080
	s_addc_u32 s97, s97, 0
	s_add_u32 s88, s88, 0xeba0080
	s_addc_u32 s89, s89, 0
	v_add_u32_e32 v145, v84, v85
	v_add_u32_e32 v178, v85, v86
	v_add_u32_e32 v179, v84, v87
	v_add_u32_e32 v180, v86, v87
.LBB0_1824:
	s_add_i32 s41, s39, 0x8000
	s_and_b32 s40, s41, 0x8000
	s_add_i32 s40, s40, 0
	s_add_u32 s86, s40, s87
	s_mov_b32 m0, s86
	s_waitcnt vmcnt(0) lgkmcnt(0)
	s_barrier
	global_load_lds_dwordx4 v244, s[96:97]
	s_add_u32 m0, s86, 0x4000
	s_nop 0
	global_load_lds_dwordx4 v245, s[88:89]
	s_add_u32 m0, s86, 0x1000
	s_nop 0
	global_load_lds_dwordx4 v246, s[96:97]
	s_add_u32 m0, s86, 0x5000
	s_nop 0
	global_load_lds_dwordx4 v247, s[88:89]
	s_add_u32 m0, s86, 0x2000
	s_nop 0
	global_load_lds_dwordx4 v248, s[96:97]
	s_add_u32 m0, s86, 0x6000
	s_nop 0
	global_load_lds_dwordx4 v249, s[88:89]
	s_add_u32 m0, s86, 0x3000
	s_nop 0
	global_load_lds_dwordx4 v250, s[96:97]
	s_add_u32 m0, s86, 0x7000
	s_nop 0
	global_load_lds_dwordx4 v251, s[88:89]
	s_add_u32 s96, s96, 0x80
	s_addc_u32 s97, s97, 0
	s_add_u32 s88, s88, 0x80
	s_addc_u32 s89, s89, 0
	s_and_b32 s39, s39, 0x8000
	s_add_i32 s39, s39, 0
	ds_read_b128 v[104:107], v178
	ds_read_b128 v[76:79], v145 offset:16384
	ds_read_b128 v[100:103], v145 offset:18432
	ds_read_b128 v[108:111], v178 offset:2048
	ds_read_b128 v[112:115], v145 offset:20480
	ds_read_b128 v[116:119], v145 offset:22528
	ds_read_b128 v[120:123], v145 offset:24576
	ds_read_b128 v[124:127], v145 offset:26624
	ds_read_b128 v[128:131], v145 offset:28672
	ds_read_b128 v[132:135], v145 offset:30720
	ds_read_b128 v[146:149], v180
	ds_read_b128 v[136:139], v179 offset:16384
	ds_read_b128 v[140:143], v179 offset:18432
	ds_read_b128 v[150:153], v180 offset:2048
	ds_read_b128 v[154:157], v179 offset:20480
	ds_read_b128 v[158:161], v179 offset:22528
	ds_read_b128 v[162:165], v179 offset:24576
	ds_read_b128 v[166:169], v179 offset:26624
	ds_read_b128 v[170:173], v179 offset:28672
	ds_read_b128 v[174:177], v179 offset:30720
	s_add_u32 s28, s28, 0x80
	s_addc_u32 s29, s29, 0
	s_cmpk_eq_i32 s28, 0x1f80
	s_mov_b32 s39, s41
	s_waitcnt lgkmcnt(15)
	v_mfma_f32_16x16x32_bf16 v[60:63], v[76:79], v[104:107], v[60:63]
	v_mfma_f32_16x16x32_bf16 v[56:59], v[100:103], v[104:107], v[56:59]
	v_mfma_f32_16x16x32_bf16 v[24:27], v[76:79], v[108:111], v[24:27]
	v_mfma_f32_16x16x32_bf16 v[20:23], v[100:103], v[108:111], v[20:23]
	v_mfma_f32_16x16x32_bf16 v[52:55], v[112:115], v[104:107], v[52:55]
	v_mfma_f32_16x16x32_bf16 v[16:19], v[112:115], v[108:111], v[16:19]
	s_waitcnt lgkmcnt(14)
	v_mfma_f32_16x16x32_bf16 v[48:51], v[116:119], v[104:107], v[48:51]
	v_mfma_f32_16x16x32_bf16 v[12:15], v[116:119], v[108:111], v[12:15]
	s_waitcnt lgkmcnt(13)
	v_mfma_f32_16x16x32_bf16 v[44:47], v[120:123], v[104:107], v[44:47]
	v_mfma_f32_16x16x32_bf16 v[8:11], v[120:123], v[108:111], v[8:11]
	s_waitcnt lgkmcnt(12)
	v_mfma_f32_16x16x32_bf16 v[40:43], v[124:127], v[104:107], v[40:43]
	v_mfma_f32_16x16x32_bf16 v[4:7], v[124:127], v[108:111], v[4:7]
	s_waitcnt lgkmcnt(11)
	v_mfma_f32_16x16x32_bf16 v[32:35], v[128:131], v[104:107], v[32:35]
	v_mfma_f32_16x16x32_bf16 v[0:3], v[128:131], v[108:111], v[0:3]
	s_waitcnt lgkmcnt(10)
	v_mfma_f32_16x16x32_bf16 v[28:31], v[132:135], v[104:107], v[28:31]
	v_mfma_f32_16x16x32_bf16 v[36:39], v[132:135], v[108:111], v[36:39]
	s_waitcnt lgkmcnt(8)
	v_mfma_f32_16x16x32_bf16 v[60:63], v[136:139], v[146:149], v[60:63]
	s_waitcnt lgkmcnt(7)
	v_mfma_f32_16x16x32_bf16 v[56:59], v[140:143], v[146:149], v[56:59]
	s_waitcnt lgkmcnt(6)
	v_mfma_f32_16x16x32_bf16 v[24:27], v[136:139], v[150:153], v[24:27]
	v_mfma_f32_16x16x32_bf16 v[20:23], v[140:143], v[150:153], v[20:23]
	s_waitcnt lgkmcnt(5)
	v_mfma_f32_16x16x32_bf16 v[52:55], v[154:157], v[146:149], v[52:55]
	v_mfma_f32_16x16x32_bf16 v[16:19], v[154:157], v[150:153], v[16:19]
	s_waitcnt lgkmcnt(4)
	v_mfma_f32_16x16x32_bf16 v[48:51], v[158:161], v[146:149], v[48:51]
	v_mfma_f32_16x16x32_bf16 v[12:15], v[158:161], v[150:153], v[12:15]
	s_waitcnt lgkmcnt(3)
	v_mfma_f32_16x16x32_bf16 v[44:47], v[162:165], v[146:149], v[44:47]
	v_mfma_f32_16x16x32_bf16 v[8:11], v[162:165], v[150:153], v[8:11]
	s_waitcnt lgkmcnt(2)
	v_mfma_f32_16x16x32_bf16 v[40:43], v[166:169], v[146:149], v[40:43]
	v_mfma_f32_16x16x32_bf16 v[4:7], v[166:169], v[150:153], v[4:7]
	s_waitcnt lgkmcnt(1)
	v_mfma_f32_16x16x32_bf16 v[32:35], v[170:173], v[146:149], v[32:35]
	v_mfma_f32_16x16x32_bf16 v[0:3], v[170:173], v[150:153], v[0:3]
	s_waitcnt lgkmcnt(0)
	v_mfma_f32_16x16x32_bf16 v[28:31], v[174:177], v[146:149], v[28:31]
	v_mfma_f32_16x16x32_bf16 v[36:39], v[174:177], v[150:153], v[36:39]
	s_cbranch_scc1 .Lu2x_1824
	s_add_i32 s41, s39, 0x8000
	s_and_b32 s40, s41, 0x8000
	s_add_i32 s40, s40, 0
	s_add_u32 s86, s40, s87
	s_mov_b32 m0, s86
	s_waitcnt vmcnt(0) lgkmcnt(0)
	s_barrier
	global_load_lds_dwordx4 v244, s[96:97]
	s_add_u32 m0, s86, 0x4000
	s_nop 0
	global_load_lds_dwordx4 v245, s[88:89]
	s_add_u32 m0, s86, 0x1000
	s_nop 0
	global_load_lds_dwordx4 v246, s[96:97]
	s_add_u32 m0, s86, 0x5000
	s_nop 0
	global_load_lds_dwordx4 v247, s[88:89]
	s_add_u32 m0, s86, 0x2000
	s_nop 0
	global_load_lds_dwordx4 v248, s[96:97]
	s_add_u32 m0, s86, 0x6000
	s_nop 0
	global_load_lds_dwordx4 v249, s[88:89]
	s_add_u32 m0, s86, 0x3000
	s_nop 0
	global_load_lds_dwordx4 v250, s[96:97]
	s_add_u32 m0, s86, 0x7000
	s_nop 0
	global_load_lds_dwordx4 v251, s[88:89]
	s_add_u32 s96, s96, 0x80
	s_addc_u32 s97, s97, 0
	s_add_u32 s88, s88, 0x80
	s_addc_u32 s89, s89, 0
	s_and_b32 s39, s39, 0x8000
	s_add_i32 s39, s39, 0
	ds_read_b128 v[104:107], v178 offset:32768
	ds_read_b128 v[76:79], v145 offset:49152
	ds_read_b128 v[100:103], v145 offset:51200
	ds_read_b128 v[108:111], v178 offset:34816
	ds_read_b128 v[112:115], v145 offset:53248
	ds_read_b128 v[116:119], v145 offset:55296
	ds_read_b128 v[120:123], v145 offset:57344
	ds_read_b128 v[124:127], v145 offset:59392
	ds_read_b128 v[128:131], v145 offset:61440
	ds_read_b128 v[132:135], v145 offset:63488
	ds_read_b128 v[146:149], v180 offset:32768
	ds_read_b128 v[136:139], v179 offset:49152
	ds_read_b128 v[140:143], v179 offset:51200
	ds_read_b128 v[150:153], v180 offset:34816
	ds_read_b128 v[154:157], v179 offset:53248
	ds_read_b128 v[158:161], v179 offset:55296
	ds_read_b128 v[162:165], v179 offset:57344
	ds_read_b128 v[166:169], v179 offset:59392
	ds_read_b128 v[170:173], v179 offset:61440
	ds_read_b128 v[174:177], v179 offset:63488
	s_add_u32 s28, s28, 0x80
	s_addc_u32 s29, s29, 0
	s_cmpk_eq_i32 s28, 0x1f80
	s_mov_b32 s39, s41
	s_waitcnt lgkmcnt(15)
	v_mfma_f32_16x16x32_bf16 v[60:63], v[76:79], v[104:107], v[60:63]
	v_mfma_f32_16x16x32_bf16 v[56:59], v[100:103], v[104:107], v[56:59]
	v_mfma_f32_16x16x32_bf16 v[24:27], v[76:79], v[108:111], v[24:27]
	v_mfma_f32_16x16x32_bf16 v[20:23], v[100:103], v[108:111], v[20:23]
	v_mfma_f32_16x16x32_bf16 v[52:55], v[112:115], v[104:107], v[52:55]
	v_mfma_f32_16x16x32_bf16 v[16:19], v[112:115], v[108:111], v[16:19]
	s_waitcnt lgkmcnt(14)
	v_mfma_f32_16x16x32_bf16 v[48:51], v[116:119], v[104:107], v[48:51]
	v_mfma_f32_16x16x32_bf16 v[12:15], v[116:119], v[108:111], v[12:15]
	s_waitcnt lgkmcnt(13)
	v_mfma_f32_16x16x32_bf16 v[44:47], v[120:123], v[104:107], v[44:47]
	v_mfma_f32_16x16x32_bf16 v[8:11], v[120:123], v[108:111], v[8:11]
	s_waitcnt lgkmcnt(12)
	v_mfma_f32_16x16x32_bf16 v[40:43], v[124:127], v[104:107], v[40:43]
	v_mfma_f32_16x16x32_bf16 v[4:7], v[124:127], v[108:111], v[4:7]
	s_waitcnt lgkmcnt(11)
	v_mfma_f32_16x16x32_bf16 v[32:35], v[128:131], v[104:107], v[32:35]
	v_mfma_f32_16x16x32_bf16 v[0:3], v[128:131], v[108:111], v[0:3]
	s_waitcnt lgkmcnt(10)
	v_mfma_f32_16x16x32_bf16 v[28:31], v[132:135], v[104:107], v[28:31]
	v_mfma_f32_16x16x32_bf16 v[36:39], v[132:135], v[108:111], v[36:39]
	s_waitcnt lgkmcnt(8)
	v_mfma_f32_16x16x32_bf16 v[60:63], v[136:139], v[146:149], v[60:63]
	s_waitcnt lgkmcnt(7)
	v_mfma_f32_16x16x32_bf16 v[56:59], v[140:143], v[146:149], v[56:59]
	s_waitcnt lgkmcnt(6)
	v_mfma_f32_16x16x32_bf16 v[24:27], v[136:139], v[150:153], v[24:27]
	v_mfma_f32_16x16x32_bf16 v[20:23], v[140:143], v[150:153], v[20:23]
	s_waitcnt lgkmcnt(5)
	v_mfma_f32_16x16x32_bf16 v[52:55], v[154:157], v[146:149], v[52:55]
	v_mfma_f32_16x16x32_bf16 v[16:19], v[154:157], v[150:153], v[16:19]
	s_waitcnt lgkmcnt(4)
	v_mfma_f32_16x16x32_bf16 v[48:51], v[158:161], v[146:149], v[48:51]
	v_mfma_f32_16x16x32_bf16 v[12:15], v[158:161], v[150:153], v[12:15]
	s_waitcnt lgkmcnt(3)
	v_mfma_f32_16x16x32_bf16 v[44:47], v[162:165], v[146:149], v[44:47]
	v_mfma_f32_16x16x32_bf16 v[8:11], v[162:165], v[150:153], v[8:11]
	s_waitcnt lgkmcnt(2)
	v_mfma_f32_16x16x32_bf16 v[40:43], v[166:169], v[146:149], v[40:43]
	v_mfma_f32_16x16x32_bf16 v[4:7], v[166:169], v[150:153], v[4:7]
	s_waitcnt lgkmcnt(1)
	v_mfma_f32_16x16x32_bf16 v[32:35], v[170:173], v[146:149], v[32:35]
	v_mfma_f32_16x16x32_bf16 v[0:3], v[170:173], v[150:153], v[0:3]
	s_waitcnt lgkmcnt(0)
	v_mfma_f32_16x16x32_bf16 v[28:31], v[174:177], v[146:149], v[28:31]
	v_mfma_f32_16x16x32_bf16 v[36:39], v[174:177], v[150:153], v[36:39]
	s_cbranch_scc0 .LBB0_1824
